# PEER gather: ring slot refilled at the end of its step (after the up-projection FMAs) instead of after the dot reduction
# speedup vs baseline: 1.1338x; 1.0035x over previous
; DEV void peer_gather_token(const Params& p, int tok) {
;     ...
;     for (int s = 0; s < 4; ++s) {
;       const int k = k4 + s;
;       if (k + 3 < 128) issue(k + 3, (s + 3) & 3);
;       const v6u dq = v6u{dn[s][0][0], dn[s][0][1], dn[s][1][0], dn[s][1][1], dn[s][2][0], dn[s][2][1]};
;       const v32f dv = __builtin_amdgcn_cvt_scalef32_pk32_f32_fp6(dq, 1.0f);
;       float d0 = 0.f, d1 = 0.f, d2 = 0.f, d3 = 0.f;
; #pragma unroll
;       for (int i = 0; i < 8; ++i) { d0 += dv[4 * i] * hx[4 * i]; d1 += dv[4 * i + 1] * hx[4 * i + 1]; d2 += dv[4 * i + 2] * hx[4 * i + 2]; d3 += dv[4 * i + 3] * hx[4 * i + 3]; }
;       const float d = wave_sum_fast((d0 + d1) + (d2 + d3)) * (1.f / DOWN_SCALE);
;       const float gk = __builtin_bit_cast(float, (k < 64) ? __builtin_amdgcn_readlane(g0, k) : __builtin_amdgcn_readlane(g1, k - 64));
.Lp12_ne8:
	s_waitcnt vmcnt(21)
	v_cvt_scalef32_pk32_f32_fp6 v[2:33], v[98:103], 1.0
	v_mul_f32_e32 v200, v2, v34
	v_mul_f32_e32 v201, v3, v35
	v_mul_f32_e32 v202, v4, v36
	v_mul_f32_e32 v203, v5, v37
	v_fmac_f32_e32 v200, v6, v38
	v_fmac_f32_e32 v201, v7, v39
	v_fmac_f32_e32 v202, v8, v40
	v_fmac_f32_e32 v203, v9, v41
	v_fmac_f32_e32 v200, v10, v42
	v_fmac_f32_e32 v201, v11, v43
	v_fmac_f32_e32 v202, v12, v44
	v_fmac_f32_e32 v203, v13, v45
	v_fmac_f32_e32 v200, v14, v46
	v_fmac_f32_e32 v201, v15, v47
	v_fmac_f32_e32 v202, v16, v48
	v_fmac_f32_e32 v203, v17, v49
	v_fmac_f32_e32 v200, v18, v50
	v_fmac_f32_e32 v201, v19, v51
	v_fmac_f32_e32 v202, v20, v52
	v_fmac_f32_e32 v203, v21, v53
	v_fmac_f32_e32 v200, v22, v54
	v_fmac_f32_e32 v201, v23, v55
	v_fmac_f32_e32 v202, v24, v56
	v_fmac_f32_e32 v203, v25, v57
	v_fmac_f32_e32 v200, v26, v58
	v_fmac_f32_e32 v201, v27, v59
	v_fmac_f32_e32 v202, v28, v60
	v_fmac_f32_e32 v203, v29, v61
	v_fmac_f32_e32 v200, v30, v62
	v_fmac_f32_e32 v201, v31, v63
	v_fmac_f32_e32 v202, v32, v64
	v_fmac_f32_e32 v203, v33, v65
	v_add_f32_e32 v200, v201, v200
	v_add_f32_e32 v202, v203, v202
	v_cvt_scalef32_pk32_f32_fp6 v[2:33], v[104:109], 1.0
	v_add_f32_e32 v200, v202, v200
	s_add_i32 s38, s24, 0
	v_readlane_b32 s26, v199, s38
	s_add_i32 s39, s23, 0
	v_readlane_b32 s25, v198, s39
	v_add_f32_dpp v200, v200, v200 quad_perm:[1,0,3,2] row_mask:0xf bank_mask:0xf bound_ctrl:1
	s_nop 1
	v_add_f32_dpp v200, v200, v200 quad_perm:[2,3,0,1] row_mask:0xf bank_mask:0xf bound_ctrl:1
	s_nop 1
	v_add_f32_dpp v200, v200, v200 row_half_mirror row_mask:0xf bank_mask:0xf bound_ctrl:1
	s_nop 1
	v_add_f32_dpp v200, v200, v200 row_mirror row_mask:0xf bank_mask:0xf bound_ctrl:1
	s_nop 1
	v_add_f32_dpp v200, v200, v200 row_bcast:15 row_mask:0xa bank_mask:0xf
	s_nop 1
	v_add_f32_dpp v200, v200, v200 row_bcast:31 row_mask:0xc bank_mask:0xf
	s_nop 0
	v_readlane_b32 s27, v200, 63
	v_mul_f32_e32 v204, s27, v212
	v_mul_f32_e32 v205, 0x3f3504f3, v204
	v_cmp_lt_f32_e64 s[32:33], |v205|, 1.0
	s_and_b64 vcc, exec, s[32:33]
	s_cbranch_vccnz .Lsm_1
	v_fma_f32 v208, |v205|, s9, v214
	v_fma_f32 v208, |v205|, v208, s10
	v_fma_f32 v208, |v205|, v208, s11
	v_fma_f32 v208, |v205|, v208, s12
	v_fma_f32 v208, |v205|, v208, s13
	v_fma_f32 v208, |v205|, v208, s14
	v_fma_f32 v208, |v205|, v208, |v205|
	v_mul_f32_e32 v209, 0xbfb8aa3b, v208
	v_fma_f32 v210, v208, s15, -v209
	v_rndne_f32_e32 v211, v209
	v_fmac_f32_e32 v210, 0xb2a5705f, v208
	v_sub_f32_e32 v209, v209, v211
	v_add_f32_e32 v209, v209, v210
	v_cvt_i32_f32_e32 v210, v211
	v_exp_f32_e32 v209, v209
	v_cmp_nlt_f32_e32 vcc, s16, v208
	v_ldexp_f32 v209, v209, v210
	s_nop 0
	v_cndmask_b32_e32 v209, 0, v209, vcc
	v_cmp_ngt_f32_e32 vcc, s17, v208
	s_nop 1
	v_cndmask_b32_e32 v208, v215, v209, vcc
	v_sub_f32_e32 v210, 1.0, v208
	s_branch .Ljn_1

; DEV float gelu_exact(float v) { return 0.5f * v * (1.f + erff(v * 0.7071067811865476f)); }
; DEV void peer_gather_token(const Params& p, int tok) {
;     ...
;     for (int s = 0; s < 4; ++s) {
;       const int k = k4 + s;
;       if (k + 3 < 128) issue(k + 3, (s + 3) & 3);
;       const v6u dq = v6u{dn[s][0][0], dn[s][0][1], dn[s][1][0], dn[s][1][1], dn[s][2][0], dn[s][2][1]};
;       const v32f dv = __builtin_amdgcn_cvt_scalef32_pk32_f32_fp6(dq, 1.0f);
;       float d0 = 0.f, d1 = 0.f, d2 = 0.f, d3 = 0.f;
; #pragma unroll
;       for (int i = 0; i < 8; ++i) { d0 += dv[4 * i] * hx[4 * i]; d1 += dv[4 * i + 1] * hx[4 * i + 1]; d2 += dv[4 * i + 2] * hx[4 * i + 2]; d3 += dv[4 * i + 3] * hx[4 * i + 3]; }
;       const float d = wave_sum_fast((d0 + d1) + (d2 + d3)) * (1.f / DOWN_SCALE);
;       const float gk = __builtin_bit_cast(float, (k < 64) ? __builtin_amdgcn_readlane(g0, k) : __builtin_amdgcn_readlane(g1, k - 64));
;       const float act = gelu_exact(d) * gk * (1.f / UP_SCALE);
;       const v6u uq = v6u{up[s][0][0], up[s][0][1], up[s][1][0], up[s][1][1], up[s][2][0], up[s][2][1]};
;       const v32f uv = __builtin_amdgcn_cvt_scalef32_pk32_f32_fp6(uq, 1.0f);
; #pragma unroll
;       for (int i = 0; i < 32; ++i) acc[i] += act * uv[i];
.Ljn_1:
	v_bfi_b32 v209, s18, v210, v205
	v_mul_f32_e32 v208, 0.5, v204
	v_add_f32_e32 v209, 1.0, v209
	v_mul_f32_e32 v208, v208, v209
	v_mul_f32_e32 v208, s26, v208
	v_mul_f32_e32 v206, 0x3e800000, v208
	v_pk_fma_f32 v[66:67], v[2:3], v[206:207], v[66:67] op_sel_hi:[1,0,1]
	v_pk_fma_f32 v[68:69], v[4:5], v[206:207], v[68:69] op_sel_hi:[1,0,1]
	v_pk_fma_f32 v[70:71], v[6:7], v[206:207], v[70:71] op_sel_hi:[1,0,1]
	v_pk_fma_f32 v[72:73], v[8:9], v[206:207], v[72:73] op_sel_hi:[1,0,1]
	v_pk_fma_f32 v[74:75], v[10:11], v[206:207], v[74:75] op_sel_hi:[1,0,1]
	v_pk_fma_f32 v[76:77], v[12:13], v[206:207], v[76:77] op_sel_hi:[1,0,1]
	v_pk_fma_f32 v[78:79], v[14:15], v[206:207], v[78:79] op_sel_hi:[1,0,1]
	v_pk_fma_f32 v[80:81], v[16:17], v[206:207], v[80:81] op_sel_hi:[1,0,1]
	v_pk_fma_f32 v[82:83], v[18:19], v[206:207], v[82:83] op_sel_hi:[1,0,1]
	v_pk_fma_f32 v[84:85], v[20:21], v[206:207], v[84:85] op_sel_hi:[1,0,1]
	v_pk_fma_f32 v[86:87], v[22:23], v[206:207], v[86:87] op_sel_hi:[1,0,1]
	v_pk_fma_f32 v[88:89], v[24:25], v[206:207], v[88:89] op_sel_hi:[1,0,1]
	v_pk_fma_f32 v[90:91], v[26:27], v[206:207], v[90:91] op_sel_hi:[1,0,1]
	v_pk_fma_f32 v[92:93], v[28:29], v[206:207], v[92:93] op_sel_hi:[1,0,1]
	v_pk_fma_f32 v[94:95], v[30:31], v[206:207], v[94:95] op_sel_hi:[1,0,1]
	v_pk_fma_f32 v[96:97], v[32:33], v[206:207], v[96:97] op_sel_hi:[1,0,1]
	s_mul_i32 s40, s25, 0xc00
	s_add_u32 s28, s62, s40
	s_addc_u32 s29, s63, 0
	global_load_dwordx4 v[98:101], v1, s[28:29]
	global_load_dwordx4 v[102:105], v1, s[28:29] offset:2048
	global_load_dwordx4 v[106:109], v1, s[28:29] offset:1024
	s_waitcnt vmcnt(21)
	v_cvt_scalef32_pk32_f32_fp6 v[2:33], v[110:115], 1.0
	v_mul_f32_e32 v200, v2, v34
	v_mul_f32_e32 v201, v3, v35
	v_mul_f32_e32 v202, v4, v36
	v_mul_f32_e32 v203, v5, v37
	v_fmac_f32_e32 v200, v6, v38
	v_fmac_f32_e32 v201, v7, v39
	v_fmac_f32_e32 v202, v8, v40
	v_fmac_f32_e32 v203, v9, v41
	v_fmac_f32_e32 v200, v10, v42
	v_fmac_f32_e32 v201, v11, v43
	v_fmac_f32_e32 v202, v12, v44
	v_fmac_f32_e32 v203, v13, v45
	v_fmac_f32_e32 v200, v14, v46
	v_fmac_f32_e32 v201, v15, v47
	v_fmac_f32_e32 v202, v16, v48
	v_fmac_f32_e32 v203, v17, v49
	v_fmac_f32_e32 v200, v18, v50
	v_fmac_f32_e32 v201, v19, v51
	v_fmac_f32_e32 v202, v20, v52
	v_fmac_f32_e32 v203, v21, v53
	v_fmac_f32_e32 v200, v22, v54
	v_fmac_f32_e32 v201, v23, v55
	v_fmac_f32_e32 v202, v24, v56
	v_fmac_f32_e32 v203, v25, v57
	v_fmac_f32_e32 v200, v26, v58
	v_fmac_f32_e32 v201, v27, v59
	v_fmac_f32_e32 v202, v28, v60
	v_fmac_f32_e32 v203, v29, v61
	v_fmac_f32_e32 v200, v30, v62
	v_fmac_f32_e32 v201, v31, v63
	v_fmac_f32_e32 v202, v32, v64
	v_fmac_f32_e32 v203, v33, v65
	v_add_f32_e32 v200, v201, v200
	v_add_f32_e32 v202, v203, v202
	v_cvt_scalef32_pk32_f32_fp6 v[2:33], v[116:121], 1.0
	v_add_f32_e32 v200, v202, v200
	s_add_i32 s38, s24, 1
	v_readlane_b32 s26, v199, s38
	s_add_i32 s39, s23, 1
	v_readlane_b32 s25, v198, s39
	v_add_f32_dpp v200, v200, v200 quad_perm:[1,0,3,2] row_mask:0xf bank_mask:0xf bound_ctrl:1
	s_nop 1
	v_add_f32_dpp v200, v200, v200 quad_perm:[2,3,0,1] row_mask:0xf bank_mask:0xf bound_ctrl:1
	s_nop 1
	v_add_f32_dpp v200, v200, v200 row_half_mirror row_mask:0xf bank_mask:0xf bound_ctrl:1
	s_nop 1
	v_add_f32_dpp v200, v200, v200 row_mirror row_mask:0xf bank_mask:0xf bound_ctrl:1
	s_nop 1
	v_add_f32_dpp v200, v200, v200 row_bcast:15 row_mask:0xa bank_mask:0xf
	s_nop 1
	v_add_f32_dpp v200, v200, v200 row_bcast:31 row_mask:0xc bank_mask:0xf
	s_nop 0
	v_readlane_b32 s27, v200, 63
	v_mul_f32_e32 v204, s27, v212
	v_mul_f32_e32 v205, 0x3f3504f3, v204
	v_cmp_lt_f32_e64 s[32:33], |v205|, 1.0
	s_and_b64 vcc, exec, s[32:33]
	s_cbranch_vccnz .Lsm_3
	v_fma_f32 v208, |v205|, s9, v214
	v_fma_f32 v208, |v205|, v208, s10
	v_fma_f32 v208, |v205|, v208, s11
	v_fma_f32 v208, |v205|, v208, s12
	v_fma_f32 v208, |v205|, v208, s13
	v_fma_f32 v208, |v205|, v208, s14
	v_fma_f32 v208, |v205|, v208, |v205|
	v_mul_f32_e32 v209, 0xbfb8aa3b, v208
	v_fma_f32 v210, v208, s15, -v209
	v_rndne_f32_e32 v211, v209
	v_fmac_f32_e32 v210, 0xb2a5705f, v208
	v_sub_f32_e32 v209, v209, v211
	v_add_f32_e32 v209, v209, v210
	v_cvt_i32_f32_e32 v210, v211
	v_exp_f32_e32 v209, v209
	v_cmp_nlt_f32_e32 vcc, s16, v208
	v_ldexp_f32 v209, v209, v210
	s_nop 0
	v_cndmask_b32_e32 v209, 0, v209, vcc
	v_cmp_ngt_f32_e32 vcc, s17, v208
	s_nop 1
	v_cndmask_b32_e32 v208, v215, v209, vcc
	v_sub_f32_e32 v210, 1.0, v208
	s_branch .Ljn_3

; DEV float gelu_exact(float v) { return 0.5f * v * (1.f + erff(v * 0.7071067811865476f)); }
; DEV void peer_gather_token(const Params& p, int tok) {
;     ...
;     for (int s = 0; s < 4; ++s) {
;       const int k = k4 + s;
;       if (k + 3 < 128) issue(k + 3, (s + 3) & 3);
;       const v6u dq = v6u{dn[s][0][0], dn[s][0][1], dn[s][1][0], dn[s][1][1], dn[s][2][0], dn[s][2][1]};
;       const v32f dv = __builtin_amdgcn_cvt_scalef32_pk32_f32_fp6(dq, 1.0f);
;       float d0 = 0.f, d1 = 0.f, d2 = 0.f, d3 = 0.f;
; #pragma unroll
;       for (int i = 0; i < 8; ++i) { d0 += dv[4 * i] * hx[4 * i]; d1 += dv[4 * i + 1] * hx[4 * i + 1]; d2 += dv[4 * i + 2] * hx[4 * i + 2]; d3 += dv[4 * i + 3] * hx[4 * i + 3]; }
;       const float d = wave_sum_fast((d0 + d1) + (d2 + d3)) * (1.f / DOWN_SCALE);
;       const float gk = __builtin_bit_cast(float, (k < 64) ? __builtin_amdgcn_readlane(g0, k) : __builtin_amdgcn_readlane(g1, k - 64));
;       const float act = gelu_exact(d) * gk * (1.f / UP_SCALE);
;       const v6u uq = v6u{up[s][0][0], up[s][0][1], up[s][1][0], up[s][1][1], up[s][2][0], up[s][2][1]};
;       const v32f uv = __builtin_amdgcn_cvt_scalef32_pk32_f32_fp6(uq, 1.0f);
; #pragma unroll
;       for (int i = 0; i < 32; ++i) acc[i] += act * uv[i];
.Ljn_3:
	v_bfi_b32 v209, s18, v210, v205
	v_mul_f32_e32 v208, 0.5, v204
	v_add_f32_e32 v209, 1.0, v209
	v_mul_f32_e32 v208, v208, v209
	v_mul_f32_e32 v208, s26, v208
	v_mul_f32_e32 v206, 0x3e800000, v208
	v_pk_fma_f32 v[66:67], v[2:3], v[206:207], v[66:67] op_sel_hi:[1,0,1]
	v_pk_fma_f32 v[68:69], v[4:5], v[206:207], v[68:69] op_sel_hi:[1,0,1]
	v_pk_fma_f32 v[70:71], v[6:7], v[206:207], v[70:71] op_sel_hi:[1,0,1]
	v_pk_fma_f32 v[72:73], v[8:9], v[206:207], v[72:73] op_sel_hi:[1,0,1]
	v_pk_fma_f32 v[74:75], v[10:11], v[206:207], v[74:75] op_sel_hi:[1,0,1]
	v_pk_fma_f32 v[76:77], v[12:13], v[206:207], v[76:77] op_sel_hi:[1,0,1]
	v_pk_fma_f32 v[78:79], v[14:15], v[206:207], v[78:79] op_sel_hi:[1,0,1]
	v_pk_fma_f32 v[80:81], v[16:17], v[206:207], v[80:81] op_sel_hi:[1,0,1]
	v_pk_fma_f32 v[82:83], v[18:19], v[206:207], v[82:83] op_sel_hi:[1,0,1]
	v_pk_fma_f32 v[84:85], v[20:21], v[206:207], v[84:85] op_sel_hi:[1,0,1]
	v_pk_fma_f32 v[86:87], v[22:23], v[206:207], v[86:87] op_sel_hi:[1,0,1]
	v_pk_fma_f32 v[88:89], v[24:25], v[206:207], v[88:89] op_sel_hi:[1,0,1]
	v_pk_fma_f32 v[90:91], v[26:27], v[206:207], v[90:91] op_sel_hi:[1,0,1]
	v_pk_fma_f32 v[92:93], v[28:29], v[206:207], v[92:93] op_sel_hi:[1,0,1]
	v_pk_fma_f32 v[94:95], v[30:31], v[206:207], v[94:95] op_sel_hi:[1,0,1]
	v_pk_fma_f32 v[96:97], v[32:33], v[206:207], v[96:97] op_sel_hi:[1,0,1]
	s_mul_i32 s40, s25, 0xc00
	s_add_u32 s28, s62, s40
	s_addc_u32 s29, s63, 0
	global_load_dwordx4 v[110:113], v1, s[28:29]
	global_load_dwordx4 v[114:117], v1, s[28:29] offset:2048
	global_load_dwordx4 v[118:121], v1, s[28:29] offset:1024
	s_waitcnt vmcnt(21)
	v_cvt_scalef32_pk32_f32_fp6 v[2:33], v[122:127], 1.0
	v_mul_f32_e32 v200, v2, v34
	v_mul_f32_e32 v201, v3, v35
	v_mul_f32_e32 v202, v4, v36
	v_mul_f32_e32 v203, v5, v37
	v_fmac_f32_e32 v200, v6, v38
	v_fmac_f32_e32 v201, v7, v39
	v_fmac_f32_e32 v202, v8, v40
	v_fmac_f32_e32 v203, v9, v41
	v_fmac_f32_e32 v200, v10, v42
	v_fmac_f32_e32 v201, v11, v43
	v_fmac_f32_e32 v202, v12, v44
	v_fmac_f32_e32 v203, v13, v45
	v_fmac_f32_e32 v200, v14, v46
	v_fmac_f32_e32 v201, v15, v47
	v_fmac_f32_e32 v202, v16, v48
	v_fmac_f32_e32 v203, v17, v49
	v_fmac_f32_e32 v200, v18, v50
	v_fmac_f32_e32 v201, v19, v51
	v_fmac_f32_e32 v202, v20, v52
	v_fmac_f32_e32 v203, v21, v53
	v_fmac_f32_e32 v200, v22, v54
	v_fmac_f32_e32 v201, v23, v55
	v_fmac_f32_e32 v202, v24, v56
	v_fmac_f32_e32 v203, v25, v57
	v_fmac_f32_e32 v200, v26, v58
	v_fmac_f32_e32 v201, v27, v59
	v_fmac_f32_e32 v202, v28, v60
	v_fmac_f32_e32 v203, v29, v61
	v_fmac_f32_e32 v200, v30, v62
	v_fmac_f32_e32 v201, v31, v63
	v_fmac_f32_e32 v202, v32, v64
	v_fmac_f32_e32 v203, v33, v65
	v_add_f32_e32 v200, v201, v200
	v_add_f32_e32 v202, v203, v202
	v_cvt_scalef32_pk32_f32_fp6 v[2:33], v[128:133], 1.0
	v_add_f32_e32 v200, v202, v200
	s_add_i32 s38, s24, 2
	v_readlane_b32 s26, v199, s38
	s_add_i32 s39, s23, 2
	v_readlane_b32 s25, v198, s39
	v_add_f32_dpp v200, v200, v200 quad_perm:[1,0,3,2] row_mask:0xf bank_mask:0xf bound_ctrl:1
	s_nop 1
	v_add_f32_dpp v200, v200, v200 quad_perm:[2,3,0,1] row_mask:0xf bank_mask:0xf bound_ctrl:1
	s_nop 1
	v_add_f32_dpp v200, v200, v200 row_half_mirror row_mask:0xf bank_mask:0xf bound_ctrl:1
	s_nop 1
	v_add_f32_dpp v200, v200, v200 row_mirror row_mask:0xf bank_mask:0xf bound_ctrl:1
	s_nop 1
	v_add_f32_dpp v200, v200, v200 row_bcast:15 row_mask:0xa bank_mask:0xf
	s_nop 1
	v_add_f32_dpp v200, v200, v200 row_bcast:31 row_mask:0xc bank_mask:0xf
	s_nop 0
	v_readlane_b32 s27, v200, 63
	v_mul_f32_e32 v204, s27, v212
	v_mul_f32_e32 v205, 0x3f3504f3, v204
	v_cmp_lt_f32_e64 s[32:33], |v205|, 1.0
	s_and_b64 vcc, exec, s[32:33]
	s_cbranch_vccnz .Lsm_5
	v_fma_f32 v208, |v205|, s9, v214
	v_fma_f32 v208, |v205|, v208, s10
	v_fma_f32 v208, |v205|, v208, s11
	v_fma_f32 v208, |v205|, v208, s12
	v_fma_f32 v208, |v205|, v208, s13
	v_fma_f32 v208, |v205|, v208, s14
	v_fma_f32 v208, |v205|, v208, |v205|
	v_mul_f32_e32 v209, 0xbfb8aa3b, v208
	v_fma_f32 v210, v208, s15, -v209
	v_rndne_f32_e32 v211, v209
	v_fmac_f32_e32 v210, 0xb2a5705f, v208
	v_sub_f32_e32 v209, v209, v211
	v_add_f32_e32 v209, v209, v210
	v_cvt_i32_f32_e32 v210, v211
	v_exp_f32_e32 v209, v209
	v_cmp_nlt_f32_e32 vcc, s16, v208
	v_ldexp_f32 v209, v209, v210
	s_nop 0
	v_cndmask_b32_e32 v209, 0, v209, vcc
	v_cmp_ngt_f32_e32 vcc, s17, v208
	s_nop 1
	v_cndmask_b32_e32 v208, v215, v209, vcc
	v_sub_f32_e32 v210, 1.0, v208
	s_branch .Ljn_5

; DEV float gelu_exact(float v) { return 0.5f * v * (1.f + erff(v * 0.7071067811865476f)); }
; DEV void peer_gather_token(const Params& p, int tok) {
;     ...
;     for (int s = 0; s < 4; ++s) {
;       const int k = k4 + s;
;       if (k + 3 < 128) issue(k + 3, (s + 3) & 3);
;       const v6u dq = v6u{dn[s][0][0], dn[s][0][1], dn[s][1][0], dn[s][1][1], dn[s][2][0], dn[s][2][1]};
;       const v32f dv = __builtin_amdgcn_cvt_scalef32_pk32_f32_fp6(dq, 1.0f);
;       float d0 = 0.f, d1 = 0.f, d2 = 0.f, d3 = 0.f;
; #pragma unroll
;       for (int i = 0; i < 8; ++i) { d0 += dv[4 * i] * hx[4 * i]; d1 += dv[4 * i + 1] * hx[4 * i + 1]; d2 += dv[4 * i + 2] * hx[4 * i + 2]; d3 += dv[4 * i + 3] * hx[4 * i + 3]; }
;       const float d = wave_sum_fast((d0 + d1) + (d2 + d3)) * (1.f / DOWN_SCALE);
;       const float gk = __builtin_bit_cast(float, (k < 64) ? __builtin_amdgcn_readlane(g0, k) : __builtin_amdgcn_readlane(g1, k - 64));
;       const float act = gelu_exact(d) * gk * (1.f / UP_SCALE);
;       const v6u uq = v6u{up[s][0][0], up[s][0][1], up[s][1][0], up[s][1][1], up[s][2][0], up[s][2][1]};
;       const v32f uv = __builtin_amdgcn_cvt_scalef32_pk32_f32_fp6(uq, 1.0f);
; #pragma unroll
;       for (int i = 0; i < 32; ++i) acc[i] += act * uv[i];
.Ljn_5:
	v_bfi_b32 v209, s18, v210, v205
	v_mul_f32_e32 v208, 0.5, v204
	v_add_f32_e32 v209, 1.0, v209
	v_mul_f32_e32 v208, v208, v209
	v_mul_f32_e32 v208, s26, v208
	v_mul_f32_e32 v206, 0x3e800000, v208
	v_pk_fma_f32 v[66:67], v[2:3], v[206:207], v[66:67] op_sel_hi:[1,0,1]
	v_pk_fma_f32 v[68:69], v[4:5], v[206:207], v[68:69] op_sel_hi:[1,0,1]
	v_pk_fma_f32 v[70:71], v[6:7], v[206:207], v[70:71] op_sel_hi:[1,0,1]
	v_pk_fma_f32 v[72:73], v[8:9], v[206:207], v[72:73] op_sel_hi:[1,0,1]
	v_pk_fma_f32 v[74:75], v[10:11], v[206:207], v[74:75] op_sel_hi:[1,0,1]
	v_pk_fma_f32 v[76:77], v[12:13], v[206:207], v[76:77] op_sel_hi:[1,0,1]
	v_pk_fma_f32 v[78:79], v[14:15], v[206:207], v[78:79] op_sel_hi:[1,0,1]
	v_pk_fma_f32 v[80:81], v[16:17], v[206:207], v[80:81] op_sel_hi:[1,0,1]
	v_pk_fma_f32 v[82:83], v[18:19], v[206:207], v[82:83] op_sel_hi:[1,0,1]
	v_pk_fma_f32 v[84:85], v[20:21], v[206:207], v[84:85] op_sel_hi:[1,0,1]
	v_pk_fma_f32 v[86:87], v[22:23], v[206:207], v[86:87] op_sel_hi:[1,0,1]
	v_pk_fma_f32 v[88:89], v[24:25], v[206:207], v[88:89] op_sel_hi:[1,0,1]
	v_pk_fma_f32 v[90:91], v[26:27], v[206:207], v[90:91] op_sel_hi:[1,0,1]
	v_pk_fma_f32 v[92:93], v[28:29], v[206:207], v[92:93] op_sel_hi:[1,0,1]
	v_pk_fma_f32 v[94:95], v[30:31], v[206:207], v[94:95] op_sel_hi:[1,0,1]
	v_pk_fma_f32 v[96:97], v[32:33], v[206:207], v[96:97] op_sel_hi:[1,0,1]
	s_mul_i32 s40, s25, 0xc00
	s_add_u32 s28, s62, s40
	s_addc_u32 s29, s63, 0
	global_load_dwordx4 v[122:125], v1, s[28:29]
	global_load_dwordx4 v[126:129], v1, s[28:29] offset:2048
	global_load_dwordx4 v[130:133], v1, s[28:29] offset:1024
	s_waitcnt vmcnt(21)
	v_cvt_scalef32_pk32_f32_fp6 v[2:33], v[134:139], 1.0
	v_mul_f32_e32 v200, v2, v34
	v_mul_f32_e32 v201, v3, v35
	v_mul_f32_e32 v202, v4, v36
	v_mul_f32_e32 v203, v5, v37
	v_fmac_f32_e32 v200, v6, v38
	v_fmac_f32_e32 v201, v7, v39
	v_fmac_f32_e32 v202, v8, v40
	v_fmac_f32_e32 v203, v9, v41
	v_fmac_f32_e32 v200, v10, v42
	v_fmac_f32_e32 v201, v11, v43
	v_fmac_f32_e32 v202, v12, v44
	v_fmac_f32_e32 v203, v13, v45
	v_fmac_f32_e32 v200, v14, v46
	v_fmac_f32_e32 v201, v15, v47
	v_fmac_f32_e32 v202, v16, v48
	v_fmac_f32_e32 v203, v17, v49
	v_fmac_f32_e32 v200, v18, v50
	v_fmac_f32_e32 v201, v19, v51
	v_fmac_f32_e32 v202, v20, v52
	v_fmac_f32_e32 v203, v21, v53
	v_fmac_f32_e32 v200, v22, v54
	v_fmac_f32_e32 v201, v23, v55
	v_fmac_f32_e32 v202, v24, v56
	v_fmac_f32_e32 v203, v25, v57
	v_fmac_f32_e32 v200, v26, v58
	v_fmac_f32_e32 v201, v27, v59
	v_fmac_f32_e32 v202, v28, v60
	v_fmac_f32_e32 v203, v29, v61
	v_fmac_f32_e32 v200, v30, v62
	v_fmac_f32_e32 v201, v31, v63
	v_fmac_f32_e32 v202, v32, v64
	v_fmac_f32_e32 v203, v33, v65
	v_add_f32_e32 v200, v201, v200
	v_add_f32_e32 v202, v203, v202
	v_cvt_scalef32_pk32_f32_fp6 v[2:33], v[140:145], 1.0
	v_add_f32_e32 v200, v202, v200
	s_add_i32 s38, s24, 3
	v_readlane_b32 s26, v199, s38
	s_add_i32 s39, s23, 3
	v_readlane_b32 s25, v198, s39
	v_add_f32_dpp v200, v200, v200 quad_perm:[1,0,3,2] row_mask:0xf bank_mask:0xf bound_ctrl:1
	s_nop 1
	v_add_f32_dpp v200, v200, v200 quad_perm:[2,3,0,1] row_mask:0xf bank_mask:0xf bound_ctrl:1
	s_nop 1
	v_add_f32_dpp v200, v200, v200 row_half_mirror row_mask:0xf bank_mask:0xf bound_ctrl:1
	s_nop 1
	v_add_f32_dpp v200, v200, v200 row_mirror row_mask:0xf bank_mask:0xf bound_ctrl:1
	s_nop 1
	v_add_f32_dpp v200, v200, v200 row_bcast:15 row_mask:0xa bank_mask:0xf
	s_nop 1
	v_add_f32_dpp v200, v200, v200 row_bcast:31 row_mask:0xc bank_mask:0xf
	s_nop 0
	v_readlane_b32 s27, v200, 63
	v_mul_f32_e32 v204, s27, v212
	v_mul_f32_e32 v205, 0x3f3504f3, v204
	v_cmp_lt_f32_e64 s[32:33], |v205|, 1.0
	s_and_b64 vcc, exec, s[32:33]
	s_cbranch_vccnz .Lsm_7
	v_fma_f32 v208, |v205|, s9, v214
	v_fma_f32 v208, |v205|, v208, s10
	v_fma_f32 v208, |v205|, v208, s11
	v_fma_f32 v208, |v205|, v208, s12
	v_fma_f32 v208, |v205|, v208, s13
	v_fma_f32 v208, |v205|, v208, s14
	v_fma_f32 v208, |v205|, v208, |v205|
	v_mul_f32_e32 v209, 0xbfb8aa3b, v208
	v_fma_f32 v210, v208, s15, -v209
	v_rndne_f32_e32 v211, v209
	v_fmac_f32_e32 v210, 0xb2a5705f, v208
	v_sub_f32_e32 v209, v209, v211
	v_add_f32_e32 v209, v209, v210
	v_cvt_i32_f32_e32 v210, v211
	v_exp_f32_e32 v209, v209
	v_cmp_nlt_f32_e32 vcc, s16, v208
	v_ldexp_f32 v209, v209, v210
	s_nop 0
	v_cndmask_b32_e32 v209, 0, v209, vcc
	v_cmp_ngt_f32_e32 vcc, s17, v208
	s_nop 1
	v_cndmask_b32_e32 v208, v215, v209, vcc
	v_sub_f32_e32 v210, 1.0, v208
	s_branch .Ljn_7

; DEV float gelu_exact(float v) { return 0.5f * v * (1.f + erff(v * 0.7071067811865476f)); }
; DEV void peer_gather_token(const Params& p, int tok) {
;     ...
;     for (int s = 0; s < 4; ++s) {
;       const int k = k4 + s;
;       if (k + 3 < 128) issue(k + 3, (s + 3) & 3);
;       const v6u dq = v6u{dn[s][0][0], dn[s][0][1], dn[s][1][0], dn[s][1][1], dn[s][2][0], dn[s][2][1]};
;       const v32f dv = __builtin_amdgcn_cvt_scalef32_pk32_f32_fp6(dq, 1.0f);
;       float d0 = 0.f, d1 = 0.f, d2 = 0.f, d3 = 0.f;
; #pragma unroll
;       for (int i = 0; i < 8; ++i) { d0 += dv[4 * i] * hx[4 * i]; d1 += dv[4 * i + 1] * hx[4 * i + 1]; d2 += dv[4 * i + 2] * hx[4 * i + 2]; d3 += dv[4 * i + 3] * hx[4 * i + 3]; }
;       const float d = wave_sum_fast((d0 + d1) + (d2 + d3)) * (1.f / DOWN_SCALE);
;       const float gk = __builtin_bit_cast(float, (k < 64) ? __builtin_amdgcn_readlane(g0, k) : __builtin_amdgcn_readlane(g1, k - 64));
;       const float act = gelu_exact(d) * gk * (1.f / UP_SCALE);
;       const v6u uq = v6u{up[s][0][0], up[s][0][1], up[s][1][0], up[s][1][1], up[s][2][0], up[s][2][1]};
;       const v32f uv = __builtin_amdgcn_cvt_scalef32_pk32_f32_fp6(uq, 1.0f);
; #pragma unroll
;       for (int i = 0; i < 32; ++i) acc[i] += act * uv[i];
.Ljn_7:
	v_bfi_b32 v209, s18, v210, v205
	v_mul_f32_e32 v208, 0.5, v204
	v_add_f32_e32 v209, 1.0, v209
	v_mul_f32_e32 v208, v208, v209
	v_mul_f32_e32 v208, s26, v208
	v_mul_f32_e32 v206, 0x3e800000, v208
	v_pk_fma_f32 v[66:67], v[2:3], v[206:207], v[66:67] op_sel_hi:[1,0,1]
	v_pk_fma_f32 v[68:69], v[4:5], v[206:207], v[68:69] op_sel_hi:[1,0,1]
	v_pk_fma_f32 v[70:71], v[6:7], v[206:207], v[70:71] op_sel_hi:[1,0,1]
	v_pk_fma_f32 v[72:73], v[8:9], v[206:207], v[72:73] op_sel_hi:[1,0,1]
	v_pk_fma_f32 v[74:75], v[10:11], v[206:207], v[74:75] op_sel_hi:[1,0,1]
	v_pk_fma_f32 v[76:77], v[12:13], v[206:207], v[76:77] op_sel_hi:[1,0,1]
	v_pk_fma_f32 v[78:79], v[14:15], v[206:207], v[78:79] op_sel_hi:[1,0,1]
	v_pk_fma_f32 v[80:81], v[16:17], v[206:207], v[80:81] op_sel_hi:[1,0,1]
	v_pk_fma_f32 v[82:83], v[18:19], v[206:207], v[82:83] op_sel_hi:[1,0,1]
	v_pk_fma_f32 v[84:85], v[20:21], v[206:207], v[84:85] op_sel_hi:[1,0,1]
	v_pk_fma_f32 v[86:87], v[22:23], v[206:207], v[86:87] op_sel_hi:[1,0,1]
	v_pk_fma_f32 v[88:89], v[24:25], v[206:207], v[88:89] op_sel_hi:[1,0,1]
	v_pk_fma_f32 v[90:91], v[26:27], v[206:207], v[90:91] op_sel_hi:[1,0,1]
	v_pk_fma_f32 v[92:93], v[28:29], v[206:207], v[92:93] op_sel_hi:[1,0,1]
	v_pk_fma_f32 v[94:95], v[30:31], v[206:207], v[94:95] op_sel_hi:[1,0,1]
	v_pk_fma_f32 v[96:97], v[32:33], v[206:207], v[96:97] op_sel_hi:[1,0,1]
	s_mul_i32 s40, s25, 0xc00
	s_add_u32 s28, s62, s40
	s_addc_u32 s29, s63, 0
	global_load_dwordx4 v[134:137], v1, s[28:29]
	global_load_dwordx4 v[138:141], v1, s[28:29] offset:2048
	global_load_dwordx4 v[142:145], v1, s[28:29] offset:1024
	s_waitcnt vmcnt(21)
	v_cvt_scalef32_pk32_f32_fp6 v[2:33], v[146:151], 1.0
	v_mul_f32_e32 v200, v2, v34
	v_mul_f32_e32 v201, v3, v35
	v_mul_f32_e32 v202, v4, v36
	v_mul_f32_e32 v203, v5, v37
	v_fmac_f32_e32 v200, v6, v38
	v_fmac_f32_e32 v201, v7, v39
	v_fmac_f32_e32 v202, v8, v40
	v_fmac_f32_e32 v203, v9, v41
	v_fmac_f32_e32 v200, v10, v42
	v_fmac_f32_e32 v201, v11, v43
	v_fmac_f32_e32 v202, v12, v44
	v_fmac_f32_e32 v203, v13, v45
	v_fmac_f32_e32 v200, v14, v46
	v_fmac_f32_e32 v201, v15, v47
	v_fmac_f32_e32 v202, v16, v48
	v_fmac_f32_e32 v203, v17, v49
	v_fmac_f32_e32 v200, v18, v50
	v_fmac_f32_e32 v201, v19, v51
	v_fmac_f32_e32 v202, v20, v52
	v_fmac_f32_e32 v203, v21, v53
	v_fmac_f32_e32 v200, v22, v54
	v_fmac_f32_e32 v201, v23, v55
	v_fmac_f32_e32 v202, v24, v56
	v_fmac_f32_e32 v203, v25, v57
	v_fmac_f32_e32 v200, v26, v58
	v_fmac_f32_e32 v201, v27, v59
	v_fmac_f32_e32 v202, v28, v60
	v_fmac_f32_e32 v203, v29, v61
	v_fmac_f32_e32 v200, v30, v62
	v_fmac_f32_e32 v201, v31, v63
	v_fmac_f32_e32 v202, v32, v64
	v_fmac_f32_e32 v203, v33, v65
	v_add_f32_e32 v200, v201, v200
	v_add_f32_e32 v202, v203, v202
	v_cvt_scalef32_pk32_f32_fp6 v[2:33], v[152:157], 1.0
	v_add_f32_e32 v200, v202, v200
	s_add_i32 s38, s24, 4
	v_readlane_b32 s26, v199, s38
	s_add_i32 s39, s23, 4
	v_readlane_b32 s25, v198, s39
	v_add_f32_dpp v200, v200, v200 quad_perm:[1,0,3,2] row_mask:0xf bank_mask:0xf bound_ctrl:1
	s_nop 1
	v_add_f32_dpp v200, v200, v200 quad_perm:[2,3,0,1] row_mask:0xf bank_mask:0xf bound_ctrl:1
	s_nop 1
	v_add_f32_dpp v200, v200, v200 row_half_mirror row_mask:0xf bank_mask:0xf bound_ctrl:1
	s_nop 1
	v_add_f32_dpp v200, v200, v200 row_mirror row_mask:0xf bank_mask:0xf bound_ctrl:1
	s_nop 1
	v_add_f32_dpp v200, v200, v200 row_bcast:15 row_mask:0xa bank_mask:0xf
	s_nop 1
	v_add_f32_dpp v200, v200, v200 row_bcast:31 row_mask:0xc bank_mask:0xf
	s_nop 0
	v_readlane_b32 s27, v200, 63
	v_mul_f32_e32 v204, s27, v212
	v_mul_f32_e32 v205, 0x3f3504f3, v204
	v_cmp_lt_f32_e64 s[32:33], |v205|, 1.0
	s_and_b64 vcc, exec, s[32:33]
	s_cbranch_vccnz .Lsm_9
	v_fma_f32 v208, |v205|, s9, v214
	v_fma_f32 v208, |v205|, v208, s10
	v_fma_f32 v208, |v205|, v208, s11
	v_fma_f32 v208, |v205|, v208, s12
	v_fma_f32 v208, |v205|, v208, s13
	v_fma_f32 v208, |v205|, v208, s14
	v_fma_f32 v208, |v205|, v208, |v205|
	v_mul_f32_e32 v209, 0xbfb8aa3b, v208
	v_fma_f32 v210, v208, s15, -v209
	v_rndne_f32_e32 v211, v209
	v_fmac_f32_e32 v210, 0xb2a5705f, v208
	v_sub_f32_e32 v209, v209, v211
	v_add_f32_e32 v209, v209, v210
	v_cvt_i32_f32_e32 v210, v211
	v_exp_f32_e32 v209, v209
	v_cmp_nlt_f32_e32 vcc, s16, v208
	v_ldexp_f32 v209, v209, v210
	s_nop 0
	v_cndmask_b32_e32 v209, 0, v209, vcc
	v_cmp_ngt_f32_e32 vcc, s17, v208
	s_nop 1
	v_cndmask_b32_e32 v208, v215, v209, vcc
	v_sub_f32_e32 v210, 1.0, v208
	s_branch .Ljn_9

; DEV float gelu_exact(float v) { return 0.5f * v * (1.f + erff(v * 0.7071067811865476f)); }
; DEV void peer_gather_token(const Params& p, int tok) {
;     ...
;     for (int s = 0; s < 4; ++s) {
;       const int k = k4 + s;
;       if (k + 3 < 128) issue(k + 3, (s + 3) & 3);
;       const v6u dq = v6u{dn[s][0][0], dn[s][0][1], dn[s][1][0], dn[s][1][1], dn[s][2][0], dn[s][2][1]};
;       const v32f dv = __builtin_amdgcn_cvt_scalef32_pk32_f32_fp6(dq, 1.0f);
;       float d0 = 0.f, d1 = 0.f, d2 = 0.f, d3 = 0.f;
; #pragma unroll
;       for (int i = 0; i < 8; ++i) { d0 += dv[4 * i] * hx[4 * i]; d1 += dv[4 * i + 1] * hx[4 * i + 1]; d2 += dv[4 * i + 2] * hx[4 * i + 2]; d3 += dv[4 * i + 3] * hx[4 * i + 3]; }
;       const float d = wave_sum_fast((d0 + d1) + (d2 + d3)) * (1.f / DOWN_SCALE);
;       const float gk = __builtin_bit_cast(float, (k < 64) ? __builtin_amdgcn_readlane(g0, k) : __builtin_amdgcn_readlane(g1, k - 64));
;       const float act = gelu_exact(d) * gk * (1.f / UP_SCALE);
;       const v6u uq = v6u{up[s][0][0], up[s][0][1], up[s][1][0], up[s][1][1], up[s][2][0], up[s][2][1]};
;       const v32f uv = __builtin_amdgcn_cvt_scalef32_pk32_f32_fp6(uq, 1.0f);
; #pragma unroll
;       for (int i = 0; i < 32; ++i) acc[i] += act * uv[i];
.Ljn_9:
	v_bfi_b32 v209, s18, v210, v205
	v_mul_f32_e32 v208, 0.5, v204
	v_add_f32_e32 v209, 1.0, v209
	v_mul_f32_e32 v208, v208, v209
	v_mul_f32_e32 v208, s26, v208
	v_mul_f32_e32 v206, 0x3e800000, v208
	v_pk_fma_f32 v[66:67], v[2:3], v[206:207], v[66:67] op_sel_hi:[1,0,1]
	v_pk_fma_f32 v[68:69], v[4:5], v[206:207], v[68:69] op_sel_hi:[1,0,1]
	v_pk_fma_f32 v[70:71], v[6:7], v[206:207], v[70:71] op_sel_hi:[1,0,1]
	v_pk_fma_f32 v[72:73], v[8:9], v[206:207], v[72:73] op_sel_hi:[1,0,1]
	v_pk_fma_f32 v[74:75], v[10:11], v[206:207], v[74:75] op_sel_hi:[1,0,1]
	v_pk_fma_f32 v[76:77], v[12:13], v[206:207], v[76:77] op_sel_hi:[1,0,1]
	v_pk_fma_f32 v[78:79], v[14:15], v[206:207], v[78:79] op_sel_hi:[1,0,1]
	v_pk_fma_f32 v[80:81], v[16:17], v[206:207], v[80:81] op_sel_hi:[1,0,1]
	v_pk_fma_f32 v[82:83], v[18:19], v[206:207], v[82:83] op_sel_hi:[1,0,1]
	v_pk_fma_f32 v[84:85], v[20:21], v[206:207], v[84:85] op_sel_hi:[1,0,1]
	v_pk_fma_f32 v[86:87], v[22:23], v[206:207], v[86:87] op_sel_hi:[1,0,1]
	v_pk_fma_f32 v[88:89], v[24:25], v[206:207], v[88:89] op_sel_hi:[1,0,1]
	v_pk_fma_f32 v[90:91], v[26:27], v[206:207], v[90:91] op_sel_hi:[1,0,1]
	v_pk_fma_f32 v[92:93], v[28:29], v[206:207], v[92:93] op_sel_hi:[1,0,1]
	v_pk_fma_f32 v[94:95], v[30:31], v[206:207], v[94:95] op_sel_hi:[1,0,1]
	v_pk_fma_f32 v[96:97], v[32:33], v[206:207], v[96:97] op_sel_hi:[1,0,1]
	s_mul_i32 s40, s25, 0xc00
	s_add_u32 s28, s62, s40
	s_addc_u32 s29, s63, 0
	global_load_dwordx4 v[146:149], v1, s[28:29]
	global_load_dwordx4 v[150:153], v1, s[28:29] offset:2048
	global_load_dwordx4 v[154:157], v1, s[28:29] offset:1024
	s_waitcnt vmcnt(21)
	v_cvt_scalef32_pk32_f32_fp6 v[2:33], v[158:163], 1.0
	v_mul_f32_e32 v200, v2, v34
	v_mul_f32_e32 v201, v3, v35
	v_mul_f32_e32 v202, v4, v36
	v_mul_f32_e32 v203, v5, v37
	v_fmac_f32_e32 v200, v6, v38
	v_fmac_f32_e32 v201, v7, v39
	v_fmac_f32_e32 v202, v8, v40
	v_fmac_f32_e32 v203, v9, v41
	v_fmac_f32_e32 v200, v10, v42
	v_fmac_f32_e32 v201, v11, v43
	v_fmac_f32_e32 v202, v12, v44
	v_fmac_f32_e32 v203, v13, v45
	v_fmac_f32_e32 v200, v14, v46
	v_fmac_f32_e32 v201, v15, v47
	v_fmac_f32_e32 v202, v16, v48
	v_fmac_f32_e32 v203, v17, v49
	v_fmac_f32_e32 v200, v18, v50
	v_fmac_f32_e32 v201, v19, v51
	v_fmac_f32_e32 v202, v20, v52
	v_fmac_f32_e32 v203, v21, v53
	v_fmac_f32_e32 v200, v22, v54
	v_fmac_f32_e32 v201, v23, v55
	v_fmac_f32_e32 v202, v24, v56
	v_fmac_f32_e32 v203, v25, v57
	v_fmac_f32_e32 v200, v26, v58
	v_fmac_f32_e32 v201, v27, v59
	v_fmac_f32_e32 v202, v28, v60
	v_fmac_f32_e32 v203, v29, v61
	v_fmac_f32_e32 v200, v30, v62
	v_fmac_f32_e32 v201, v31, v63
	v_fmac_f32_e32 v202, v32, v64
	v_fmac_f32_e32 v203, v33, v65
	v_add_f32_e32 v200, v201, v200
	v_add_f32_e32 v202, v203, v202
	v_cvt_scalef32_pk32_f32_fp6 v[2:33], v[164:169], 1.0
	v_add_f32_e32 v200, v202, v200
	s_add_i32 s38, s24, 5
	v_readlane_b32 s26, v199, s38
	s_add_i32 s39, s23, 5
	v_readlane_b32 s25, v198, s39
	v_add_f32_dpp v200, v200, v200 quad_perm:[1,0,3,2] row_mask:0xf bank_mask:0xf bound_ctrl:1
	s_nop 1
	v_add_f32_dpp v200, v200, v200 quad_perm:[2,3,0,1] row_mask:0xf bank_mask:0xf bound_ctrl:1
	s_nop 1
	v_add_f32_dpp v200, v200, v200 row_half_mirror row_mask:0xf bank_mask:0xf bound_ctrl:1
	s_nop 1
	v_add_f32_dpp v200, v200, v200 row_mirror row_mask:0xf bank_mask:0xf bound_ctrl:1
	s_nop 1
	v_add_f32_dpp v200, v200, v200 row_bcast:15 row_mask:0xa bank_mask:0xf
	s_nop 1
	v_add_f32_dpp v200, v200, v200 row_bcast:31 row_mask:0xc bank_mask:0xf
	s_nop 0
	v_readlane_b32 s27, v200, 63
	v_mul_f32_e32 v204, s27, v212
	v_mul_f32_e32 v205, 0x3f3504f3, v204
	v_cmp_lt_f32_e64 s[32:33], |v205|, 1.0
	s_and_b64 vcc, exec, s[32:33]
	s_cbranch_vccnz .Lsm_11
	v_fma_f32 v208, |v205|, s9, v214
	v_fma_f32 v208, |v205|, v208, s10
	v_fma_f32 v208, |v205|, v208, s11
	v_fma_f32 v208, |v205|, v208, s12
	v_fma_f32 v208, |v205|, v208, s13
	v_fma_f32 v208, |v205|, v208, s14
	v_fma_f32 v208, |v205|, v208, |v205|
	v_mul_f32_e32 v209, 0xbfb8aa3b, v208
	v_fma_f32 v210, v208, s15, -v209
	v_rndne_f32_e32 v211, v209
	v_fmac_f32_e32 v210, 0xb2a5705f, v208
	v_sub_f32_e32 v209, v209, v211
	v_add_f32_e32 v209, v209, v210
	v_cvt_i32_f32_e32 v210, v211
	v_exp_f32_e32 v209, v209
	v_cmp_nlt_f32_e32 vcc, s16, v208
	v_ldexp_f32 v209, v209, v210
	s_nop 0
	v_cndmask_b32_e32 v209, 0, v209, vcc
	v_cmp_ngt_f32_e32 vcc, s17, v208
	s_nop 1
	v_cndmask_b32_e32 v208, v215, v209, vcc
	v_sub_f32_e32 v210, 1.0, v208
	s_branch .Ljn_11

; DEV float gelu_exact(float v) { return 0.5f * v * (1.f + erff(v * 0.7071067811865476f)); }
; DEV void peer_gather_token(const Params& p, int tok) {
;     ...
;     for (int s = 0; s < 4; ++s) {
;       const int k = k4 + s;
;       if (k + 3 < 128) issue(k + 3, (s + 3) & 3);
;       const v6u dq = v6u{dn[s][0][0], dn[s][0][1], dn[s][1][0], dn[s][1][1], dn[s][2][0], dn[s][2][1]};
;       const v32f dv = __builtin_amdgcn_cvt_scalef32_pk32_f32_fp6(dq, 1.0f);
;       float d0 = 0.f, d1 = 0.f, d2 = 0.f, d3 = 0.f;
; #pragma unroll
;       for (int i = 0; i < 8; ++i) { d0 += dv[4 * i] * hx[4 * i]; d1 += dv[4 * i + 1] * hx[4 * i + 1]; d2 += dv[4 * i + 2] * hx[4 * i + 2]; d3 += dv[4 * i + 3] * hx[4 * i + 3]; }
;       const float d = wave_sum_fast((d0 + d1) + (d2 + d3)) * (1.f / DOWN_SCALE);
;       const float gk = __builtin_bit_cast(float, (k < 64) ? __builtin_amdgcn_readlane(g0, k) : __builtin_amdgcn_readlane(g1, k - 64));
;       const float act = gelu_exact(d) * gk * (1.f / UP_SCALE);
;       const v6u uq = v6u{up[s][0][0], up[s][0][1], up[s][1][0], up[s][1][1], up[s][2][0], up[s][2][1]};
;       const v32f uv = __builtin_amdgcn_cvt_scalef32_pk32_f32_fp6(uq, 1.0f);
; #pragma unroll
;       for (int i = 0; i < 32; ++i) acc[i] += act * uv[i];
.Ljn_11:
	v_bfi_b32 v209, s18, v210, v205
	v_mul_f32_e32 v208, 0.5, v204
	v_add_f32_e32 v209, 1.0, v209
	v_mul_f32_e32 v208, v208, v209
	v_mul_f32_e32 v208, s26, v208
	v_mul_f32_e32 v206, 0x3e800000, v208
	v_pk_fma_f32 v[66:67], v[2:3], v[206:207], v[66:67] op_sel_hi:[1,0,1]
	v_pk_fma_f32 v[68:69], v[4:5], v[206:207], v[68:69] op_sel_hi:[1,0,1]
	v_pk_fma_f32 v[70:71], v[6:7], v[206:207], v[70:71] op_sel_hi:[1,0,1]
	v_pk_fma_f32 v[72:73], v[8:9], v[206:207], v[72:73] op_sel_hi:[1,0,1]
	v_pk_fma_f32 v[74:75], v[10:11], v[206:207], v[74:75] op_sel_hi:[1,0,1]
	v_pk_fma_f32 v[76:77], v[12:13], v[206:207], v[76:77] op_sel_hi:[1,0,1]
	v_pk_fma_f32 v[78:79], v[14:15], v[206:207], v[78:79] op_sel_hi:[1,0,1]
	v_pk_fma_f32 v[80:81], v[16:17], v[206:207], v[80:81] op_sel_hi:[1,0,1]
	v_pk_fma_f32 v[82:83], v[18:19], v[206:207], v[82:83] op_sel_hi:[1,0,1]
	v_pk_fma_f32 v[84:85], v[20:21], v[206:207], v[84:85] op_sel_hi:[1,0,1]
	v_pk_fma_f32 v[86:87], v[22:23], v[206:207], v[86:87] op_sel_hi:[1,0,1]
	v_pk_fma_f32 v[88:89], v[24:25], v[206:207], v[88:89] op_sel_hi:[1,0,1]
	v_pk_fma_f32 v[90:91], v[26:27], v[206:207], v[90:91] op_sel_hi:[1,0,1]
	v_pk_fma_f32 v[92:93], v[28:29], v[206:207], v[92:93] op_sel_hi:[1,0,1]
	v_pk_fma_f32 v[94:95], v[30:31], v[206:207], v[94:95] op_sel_hi:[1,0,1]
	v_pk_fma_f32 v[96:97], v[32:33], v[206:207], v[96:97] op_sel_hi:[1,0,1]
	s_mul_i32 s40, s25, 0xc00
	s_add_u32 s28, s62, s40
	s_addc_u32 s29, s63, 0
	global_load_dwordx4 v[158:161], v1, s[28:29]
	global_load_dwordx4 v[162:165], v1, s[28:29] offset:2048
	global_load_dwordx4 v[166:169], v1, s[28:29] offset:1024
	s_waitcnt vmcnt(21)
	v_cvt_scalef32_pk32_f32_fp6 v[2:33], v[170:175], 1.0
	v_mul_f32_e32 v200, v2, v34
	v_mul_f32_e32 v201, v3, v35
	v_mul_f32_e32 v202, v4, v36
	v_mul_f32_e32 v203, v5, v37
	v_fmac_f32_e32 v200, v6, v38
	v_fmac_f32_e32 v201, v7, v39
	v_fmac_f32_e32 v202, v8, v40
	v_fmac_f32_e32 v203, v9, v41
	v_fmac_f32_e32 v200, v10, v42
	v_fmac_f32_e32 v201, v11, v43
	v_fmac_f32_e32 v202, v12, v44
	v_fmac_f32_e32 v203, v13, v45
	v_fmac_f32_e32 v200, v14, v46
	v_fmac_f32_e32 v201, v15, v47
	v_fmac_f32_e32 v202, v16, v48
	v_fmac_f32_e32 v203, v17, v49
	v_fmac_f32_e32 v200, v18, v50
	v_fmac_f32_e32 v201, v19, v51
	v_fmac_f32_e32 v202, v20, v52
	v_fmac_f32_e32 v203, v21, v53
	v_fmac_f32_e32 v200, v22, v54
	v_fmac_f32_e32 v201, v23, v55
	v_fmac_f32_e32 v202, v24, v56
	v_fmac_f32_e32 v203, v25, v57
	v_fmac_f32_e32 v200, v26, v58
	v_fmac_f32_e32 v201, v27, v59
	v_fmac_f32_e32 v202, v28, v60
	v_fmac_f32_e32 v203, v29, v61
	v_fmac_f32_e32 v200, v30, v62
	v_fmac_f32_e32 v201, v31, v63
	v_fmac_f32_e32 v202, v32, v64
	v_fmac_f32_e32 v203, v33, v65
	v_add_f32_e32 v200, v201, v200
	v_add_f32_e32 v202, v203, v202
	v_cvt_scalef32_pk32_f32_fp6 v[2:33], v[176:181], 1.0
	v_add_f32_e32 v200, v202, v200
	s_add_i32 s38, s24, 6
	v_readlane_b32 s26, v199, s38
	s_add_i32 s39, s23, 6
	v_readlane_b32 s25, v198, s39
	v_add_f32_dpp v200, v200, v200 quad_perm:[1,0,3,2] row_mask:0xf bank_mask:0xf bound_ctrl:1
	s_nop 1
	v_add_f32_dpp v200, v200, v200 quad_perm:[2,3,0,1] row_mask:0xf bank_mask:0xf bound_ctrl:1
	s_nop 1
	v_add_f32_dpp v200, v200, v200 row_half_mirror row_mask:0xf bank_mask:0xf bound_ctrl:1
	s_nop 1
	v_add_f32_dpp v200, v200, v200 row_mirror row_mask:0xf bank_mask:0xf bound_ctrl:1
	s_nop 1
	v_add_f32_dpp v200, v200, v200 row_bcast:15 row_mask:0xa bank_mask:0xf
	s_nop 1
	v_add_f32_dpp v200, v200, v200 row_bcast:31 row_mask:0xc bank_mask:0xf
	s_nop 0
	v_readlane_b32 s27, v200, 63
	v_mul_f32_e32 v204, s27, v212
	v_mul_f32_e32 v205, 0x3f3504f3, v204
	v_cmp_lt_f32_e64 s[32:33], |v205|, 1.0
	s_and_b64 vcc, exec, s[32:33]
	s_cbranch_vccnz .Lsm_13
	v_fma_f32 v208, |v205|, s9, v214
	v_fma_f32 v208, |v205|, v208, s10
	v_fma_f32 v208, |v205|, v208, s11
	v_fma_f32 v208, |v205|, v208, s12
	v_fma_f32 v208, |v205|, v208, s13
	v_fma_f32 v208, |v205|, v208, s14
	v_fma_f32 v208, |v205|, v208, |v205|
	v_mul_f32_e32 v209, 0xbfb8aa3b, v208
	v_fma_f32 v210, v208, s15, -v209
	v_rndne_f32_e32 v211, v209
	v_fmac_f32_e32 v210, 0xb2a5705f, v208
	v_sub_f32_e32 v209, v209, v211
	v_add_f32_e32 v209, v209, v210
	v_cvt_i32_f32_e32 v210, v211
	v_exp_f32_e32 v209, v209
	v_cmp_nlt_f32_e32 vcc, s16, v208
	v_ldexp_f32 v209, v209, v210
	s_nop 0
	v_cndmask_b32_e32 v209, 0, v209, vcc
	v_cmp_ngt_f32_e32 vcc, s17, v208
	s_nop 1
	v_cndmask_b32_e32 v208, v215, v209, vcc
	v_sub_f32_e32 v210, 1.0, v208
	s_branch .Ljn_13

; DEV float gelu_exact(float v) { return 0.5f * v * (1.f + erff(v * 0.7071067811865476f)); }
; DEV void peer_gather_token(const Params& p, int tok) {
;     ...
;     for (int s = 0; s < 4; ++s) {
;       const int k = k4 + s;
;       if (k + 3 < 128) issue(k + 3, (s + 3) & 3);
;       const v6u dq = v6u{dn[s][0][0], dn[s][0][1], dn[s][1][0], dn[s][1][1], dn[s][2][0], dn[s][2][1]};
;       const v32f dv = __builtin_amdgcn_cvt_scalef32_pk32_f32_fp6(dq, 1.0f);
;       float d0 = 0.f, d1 = 0.f, d2 = 0.f, d3 = 0.f;
; #pragma unroll
;       for (int i = 0; i < 8; ++i) { d0 += dv[4 * i] * hx[4 * i]; d1 += dv[4 * i + 1] * hx[4 * i + 1]; d2 += dv[4 * i + 2] * hx[4 * i + 2]; d3 += dv[4 * i + 3] * hx[4 * i + 3]; }
;       const float d = wave_sum_fast((d0 + d1) + (d2 + d3)) * (1.f / DOWN_SCALE);
;       const float gk = __builtin_bit_cast(float, (k < 64) ? __builtin_amdgcn_readlane(g0, k) : __builtin_amdgcn_readlane(g1, k - 64));
;       const float act = gelu_exact(d) * gk * (1.f / UP_SCALE);
;       const v6u uq = v6u{up[s][0][0], up[s][0][1], up[s][1][0], up[s][1][1], up[s][2][0], up[s][2][1]};
;       const v32f uv = __builtin_amdgcn_cvt_scalef32_pk32_f32_fp6(uq, 1.0f);
; #pragma unroll
;       for (int i = 0; i < 32; ++i) acc[i] += act * uv[i];
.Ljn_13:
	v_bfi_b32 v209, s18, v210, v205
	v_mul_f32_e32 v208, 0.5, v204
	v_add_f32_e32 v209, 1.0, v209
	v_mul_f32_e32 v208, v208, v209
	v_mul_f32_e32 v208, s26, v208
	v_mul_f32_e32 v206, 0x3e800000, v208
	v_pk_fma_f32 v[66:67], v[2:3], v[206:207], v[66:67] op_sel_hi:[1,0,1]
	v_pk_fma_f32 v[68:69], v[4:5], v[206:207], v[68:69] op_sel_hi:[1,0,1]
	v_pk_fma_f32 v[70:71], v[6:7], v[206:207], v[70:71] op_sel_hi:[1,0,1]
	v_pk_fma_f32 v[72:73], v[8:9], v[206:207], v[72:73] op_sel_hi:[1,0,1]
	v_pk_fma_f32 v[74:75], v[10:11], v[206:207], v[74:75] op_sel_hi:[1,0,1]
	v_pk_fma_f32 v[76:77], v[12:13], v[206:207], v[76:77] op_sel_hi:[1,0,1]
	v_pk_fma_f32 v[78:79], v[14:15], v[206:207], v[78:79] op_sel_hi:[1,0,1]
	v_pk_fma_f32 v[80:81], v[16:17], v[206:207], v[80:81] op_sel_hi:[1,0,1]
	v_pk_fma_f32 v[82:83], v[18:19], v[206:207], v[82:83] op_sel_hi:[1,0,1]
	v_pk_fma_f32 v[84:85], v[20:21], v[206:207], v[84:85] op_sel_hi:[1,0,1]
	v_pk_fma_f32 v[86:87], v[22:23], v[206:207], v[86:87] op_sel_hi:[1,0,1]
	v_pk_fma_f32 v[88:89], v[24:25], v[206:207], v[88:89] op_sel_hi:[1,0,1]
	v_pk_fma_f32 v[90:91], v[26:27], v[206:207], v[90:91] op_sel_hi:[1,0,1]
	v_pk_fma_f32 v[92:93], v[28:29], v[206:207], v[92:93] op_sel_hi:[1,0,1]
	v_pk_fma_f32 v[94:95], v[30:31], v[206:207], v[94:95] op_sel_hi:[1,0,1]
	v_pk_fma_f32 v[96:97], v[32:33], v[206:207], v[96:97] op_sel_hi:[1,0,1]
	s_mul_i32 s40, s25, 0xc00
	s_add_u32 s28, s62, s40
	s_addc_u32 s29, s63, 0
	global_load_dwordx4 v[170:173], v1, s[28:29]
	global_load_dwordx4 v[174:177], v1, s[28:29] offset:2048
	global_load_dwordx4 v[178:181], v1, s[28:29] offset:1024
	s_waitcnt vmcnt(21)
	v_cvt_scalef32_pk32_f32_fp6 v[2:33], v[182:187], 1.0
	v_mul_f32_e32 v200, v2, v34
	v_mul_f32_e32 v201, v3, v35
	v_mul_f32_e32 v202, v4, v36
	v_mul_f32_e32 v203, v5, v37
	v_fmac_f32_e32 v200, v6, v38
	v_fmac_f32_e32 v201, v7, v39
	v_fmac_f32_e32 v202, v8, v40
	v_fmac_f32_e32 v203, v9, v41
	v_fmac_f32_e32 v200, v10, v42
	v_fmac_f32_e32 v201, v11, v43
	v_fmac_f32_e32 v202, v12, v44
	v_fmac_f32_e32 v203, v13, v45
	v_fmac_f32_e32 v200, v14, v46
	v_fmac_f32_e32 v201, v15, v47
	v_fmac_f32_e32 v202, v16, v48
	v_fmac_f32_e32 v203, v17, v49
	v_fmac_f32_e32 v200, v18, v50
	v_fmac_f32_e32 v201, v19, v51
	v_fmac_f32_e32 v202, v20, v52
	v_fmac_f32_e32 v203, v21, v53
	v_fmac_f32_e32 v200, v22, v54
	v_fmac_f32_e32 v201, v23, v55
	v_fmac_f32_e32 v202, v24, v56
	v_fmac_f32_e32 v203, v25, v57
	v_fmac_f32_e32 v200, v26, v58
	v_fmac_f32_e32 v201, v27, v59
	v_fmac_f32_e32 v202, v28, v60
	v_fmac_f32_e32 v203, v29, v61
	v_fmac_f32_e32 v200, v30, v62
	v_fmac_f32_e32 v201, v31, v63
	v_fmac_f32_e32 v202, v32, v64
	v_fmac_f32_e32 v203, v33, v65
	v_add_f32_e32 v200, v201, v200
	v_add_f32_e32 v202, v203, v202
	v_cvt_scalef32_pk32_f32_fp6 v[2:33], v[188:193], 1.0
	v_add_f32_e32 v200, v202, v200
	s_add_i32 s38, s24, 7
	v_readlane_b32 s26, v199, s38
	s_add_i32 s39, s23, 7
	v_readlane_b32 s25, v198, s39
	v_add_f32_dpp v200, v200, v200 quad_perm:[1,0,3,2] row_mask:0xf bank_mask:0xf bound_ctrl:1
	s_nop 1
	v_add_f32_dpp v200, v200, v200 quad_perm:[2,3,0,1] row_mask:0xf bank_mask:0xf bound_ctrl:1
	s_nop 1
	v_add_f32_dpp v200, v200, v200 row_half_mirror row_mask:0xf bank_mask:0xf bound_ctrl:1
	s_nop 1
	v_add_f32_dpp v200, v200, v200 row_mirror row_mask:0xf bank_mask:0xf bound_ctrl:1
	s_nop 1
	v_add_f32_dpp v200, v200, v200 row_bcast:15 row_mask:0xa bank_mask:0xf
	s_nop 1
	v_add_f32_dpp v200, v200, v200 row_bcast:31 row_mask:0xc bank_mask:0xf
	s_nop 0
	v_readlane_b32 s27, v200, 63
	v_mul_f32_e32 v204, s27, v212
	v_mul_f32_e32 v205, 0x3f3504f3, v204
	v_cmp_lt_f32_e64 s[32:33], |v205|, 1.0
	s_and_b64 vcc, exec, s[32:33]
	s_cbranch_vccnz .Lsm_15
	v_fma_f32 v208, |v205|, s9, v214
	v_fma_f32 v208, |v205|, v208, s10
	v_fma_f32 v208, |v205|, v208, s11
	v_fma_f32 v208, |v205|, v208, s12
	v_fma_f32 v208, |v205|, v208, s13
	v_fma_f32 v208, |v205|, v208, s14
	v_fma_f32 v208, |v205|, v208, |v205|
	v_mul_f32_e32 v209, 0xbfb8aa3b, v208
	v_fma_f32 v210, v208, s15, -v209
	v_rndne_f32_e32 v211, v209
	v_fmac_f32_e32 v210, 0xb2a5705f, v208
	v_sub_f32_e32 v209, v209, v211
	v_add_f32_e32 v209, v209, v210
	v_cvt_i32_f32_e32 v210, v211
	v_exp_f32_e32 v209, v209
	v_cmp_nlt_f32_e32 vcc, s16, v208
	v_ldexp_f32 v209, v209, v210
	s_nop 0
	v_cndmask_b32_e32 v209, 0, v209, vcc
	v_cmp_ngt_f32_e32 vcc, s17, v208
	s_nop 1
	v_cndmask_b32_e32 v208, v215, v209, vcc
	v_sub_f32_e32 v210, 1.0, v208
	s_branch .Ljn_15

; DEV float bflo(unsigned u) { return __uint_as_float(u << 16); }
; DEV float bfhi(unsigned u) { return __uint_as_float(u & 0xffff0000u); }
; DEV float gelu_exact(float v) { return 0.5f * v * (1.f + erff(v * 0.7071067811865476f)); }
; DEV void peer_gather_token(const Params& p, int tok) {
;     ...
;     const u16* hr = p.h + (size_t)tok * 2048 + lane * 32;
; #pragma unroll
;     for (int q = 0; q < 4; ++q) {
;       u32x4 v = *(const u32x4*)(hr + q * 8);
; #pragma unroll
;       for (int e = 0; e < 4; ++e) { hx[q * 8 + 2 * e] = bflo(v[e]); hx[q * 8 + 2 * e + 1] = bfhi(v[e]); }
;     }
;   }
; #pragma unroll
;   for (int e = 0; e < 32; ++e) acc[e] = 0.f;
;   const int e0 = p.eidx[(size_t)tok * 128 + lane], e1 = p.eidx[(size_t)tok * 128 + 64 + lane];
;   const int g0 = __builtin_bit_cast(int, p.gw[(size_t)tok * 128 + lane]), g1 = __builtin_bit_cast(int, p.gw[(size_t)tok * 128 + 64 + lane]);
;     ...
;     for (int s = 0; s < 4; ++s) {
;       const int k = k4 + s;
;       if (k + 3 < 128) issue(k + 3, (s + 3) & 3);
;       const v6u dq = v6u{dn[s][0][0], dn[s][0][1], dn[s][1][0], dn[s][1][1], dn[s][2][0], dn[s][2][1]};
;       const v32f dv = __builtin_amdgcn_cvt_scalef32_pk32_f32_fp6(dq, 1.0f);
;       float d0 = 0.f, d1 = 0.f, d2 = 0.f, d3 = 0.f;
; #pragma unroll
;       for (int i = 0; i < 8; ++i) { d0 += dv[4 * i] * hx[4 * i]; d1 += dv[4 * i + 1] * hx[4 * i + 1]; d2 += dv[4 * i + 2] * hx[4 * i + 2]; d3 += dv[4 * i + 3] * hx[4 * i + 3]; }
;       const float d = wave_sum_fast((d0 + d1) + (d2 + d3)) * (1.f / DOWN_SCALE);
;       const float gk = __builtin_bit_cast(float, (k < 64) ? __builtin_amdgcn_readlane(g0, k) : __builtin_amdgcn_readlane(g1, k - 64));
;       const float act = gelu_exact(d) * gk * (1.f / UP_SCALE);
;       const v6u uq = v6u{up[s][0][0], up[s][0][1], up[s][1][0], up[s][1][1], up[s][2][0], up[s][2][1]};
;       const v32f uv = __builtin_amdgcn_cvt_scalef32_pk32_f32_fp6(uq, 1.0f);
; #pragma unroll
;       for (int i = 0; i < 32; ++i) acc[i] += act * uv[i];
.Ljn_15:
	v_bfi_b32 v209, s18, v210, v205
	v_mul_f32_e32 v208, 0.5, v204
	v_add_f32_e32 v209, 1.0, v209
	v_mul_f32_e32 v208, v208, v209
	v_mul_f32_e32 v208, s26, v208
	v_mul_f32_e32 v206, 0x3e800000, v208
	v_pk_fma_f32 v[66:67], v[2:3], v[206:207], v[66:67] op_sel_hi:[1,0,1]
	v_pk_fma_f32 v[68:69], v[4:5], v[206:207], v[68:69] op_sel_hi:[1,0,1]
	v_pk_fma_f32 v[70:71], v[6:7], v[206:207], v[70:71] op_sel_hi:[1,0,1]
	v_pk_fma_f32 v[72:73], v[8:9], v[206:207], v[72:73] op_sel_hi:[1,0,1]
	v_pk_fma_f32 v[74:75], v[10:11], v[206:207], v[74:75] op_sel_hi:[1,0,1]
	v_pk_fma_f32 v[76:77], v[12:13], v[206:207], v[76:77] op_sel_hi:[1,0,1]
	v_pk_fma_f32 v[78:79], v[14:15], v[206:207], v[78:79] op_sel_hi:[1,0,1]
	v_pk_fma_f32 v[80:81], v[16:17], v[206:207], v[80:81] op_sel_hi:[1,0,1]
	v_pk_fma_f32 v[82:83], v[18:19], v[206:207], v[82:83] op_sel_hi:[1,0,1]
	v_pk_fma_f32 v[84:85], v[20:21], v[206:207], v[84:85] op_sel_hi:[1,0,1]
	v_pk_fma_f32 v[86:87], v[22:23], v[206:207], v[86:87] op_sel_hi:[1,0,1]
	v_pk_fma_f32 v[88:89], v[24:25], v[206:207], v[88:89] op_sel_hi:[1,0,1]
	v_pk_fma_f32 v[90:91], v[26:27], v[206:207], v[90:91] op_sel_hi:[1,0,1]
	v_pk_fma_f32 v[92:93], v[28:29], v[206:207], v[92:93] op_sel_hi:[1,0,1]
	v_pk_fma_f32 v[94:95], v[30:31], v[206:207], v[94:95] op_sel_hi:[1,0,1]
	v_pk_fma_f32 v[96:97], v[32:33], v[206:207], v[96:97] op_sel_hi:[1,0,1]
	s_mul_i32 s40, s25, 0xc00
	s_add_u32 s28, s62, s40
	s_addc_u32 s29, s63, 0
	global_load_dwordx4 v[182:185], v1, s[28:29]
	global_load_dwordx4 v[186:189], v1, s[28:29] offset:2048
	global_load_dwordx4 v[190:193], v1, s[28:29] offset:1024
	s_add_i32 s22, s22, 1
	s_add_i32 s23, s23, 8
	s_and_b32 s23, s23, 63
	s_add_i32 s24, s24, 8
	s_and_b32 s24, s24, 63
	s_cmp_lt_u32 s22, 14
	s_cbranch_scc1 .Lp12_main
	s_add_i32 s60, s20, s21
	s_cmpk_lt_u32 s60, 0x4000
	s_cselect_b32 s60, s60, s20
	s_lshl_b32 s38, s60, 9
	s_add_u32 s58, s66, s38
	s_addc_u32 s59, s67, 0
	global_load_dword v216, v242, s[58:59]
	global_load_dword v217, v242, s[58:59] offset:256
	s_add_u32 s58, s68, s38
	s_addc_u32 s59, s69, 0
	global_load_dword v218, v242, s[58:59]
	global_load_dword v219, v242, s[58:59] offset:256
	s_lshl_b32 s38, s60, 6
	s_add_u32 s58, s80, s38
	s_addc_u32 s59, s81, 0
	global_load_dwordx2 v[220:221], v246, s[58:59]
	global_load_dwordx2 v[222:223], v247, s[58:59]
	global_load_dwordx2 v[224:225], v248, s[58:59]
	global_load_dwordx2 v[226:227], v249, s[58:59]
	global_load_dwordx2 v[228:229], v250, s[58:59]
	global_load_dwordx2 v[230:231], v251, s[58:59]
	global_load_dwordx2 v[232:233], v252, s[58:59]
	global_load_dwordx2 v[234:235], v253, s[58:59]
	s_waitcnt vmcnt(33)
	v_cvt_scalef32_pk32_f32_fp6 v[2:33], v[98:103], 1.0
	v_mul_f32_e32 v200, v2, v34
	v_mul_f32_e32 v201, v3, v35
	v_mul_f32_e32 v202, v4, v36
	v_mul_f32_e32 v203, v5, v37
	v_fmac_f32_e32 v200, v6, v38
	v_fmac_f32_e32 v201, v7, v39
	v_fmac_f32_e32 v202, v8, v40
	v_fmac_f32_e32 v203, v9, v41
	v_fmac_f32_e32 v200, v10, v42
	v_fmac_f32_e32 v201, v11, v43
	v_fmac_f32_e32 v202, v12, v44
	v_fmac_f32_e32 v203, v13, v45
	v_fmac_f32_e32 v200, v14, v46
	v_fmac_f32_e32 v201, v15, v47
	v_fmac_f32_e32 v202, v16, v48
	v_fmac_f32_e32 v203, v17, v49
	v_fmac_f32_e32 v200, v18, v50
	v_fmac_f32_e32 v201, v19, v51
	v_fmac_f32_e32 v202, v20, v52
	v_fmac_f32_e32 v203, v21, v53
	v_fmac_f32_e32 v200, v22, v54
	v_fmac_f32_e32 v201, v23, v55
	v_fmac_f32_e32 v202, v24, v56
	v_fmac_f32_e32 v203, v25, v57
	v_fmac_f32_e32 v200, v26, v58
	v_fmac_f32_e32 v201, v27, v59
	v_fmac_f32_e32 v202, v28, v60
	v_fmac_f32_e32 v203, v29, v61
	v_fmac_f32_e32 v200, v30, v62
	v_fmac_f32_e32 v201, v31, v63
	v_fmac_f32_e32 v202, v32, v64
	v_fmac_f32_e32 v203, v33, v65
	v_add_f32_e32 v200, v201, v200
	v_add_f32_e32 v202, v203, v202
	v_cvt_scalef32_pk32_f32_fp6 v[2:33], v[104:109], 1.0
	v_add_f32_e32 v200, v202, v200
	s_add_i32 s38, s24, 0
	v_readlane_b32 s26, v199, s38
	s_add_i32 s39, s23, 0
	v_readlane_b32 s25, v198, s39
	v_add_f32_dpp v200, v200, v200 quad_perm:[1,0,3,2] row_mask:0xf bank_mask:0xf bound_ctrl:1
	s_nop 1
	v_add_f32_dpp v200, v200, v200 quad_perm:[2,3,0,1] row_mask:0xf bank_mask:0xf bound_ctrl:1
	s_nop 1
	v_add_f32_dpp v200, v200, v200 row_half_mirror row_mask:0xf bank_mask:0xf bound_ctrl:1
	s_nop 1
	v_add_f32_dpp v200, v200, v200 row_mirror row_mask:0xf bank_mask:0xf bound_ctrl:1
	s_nop 1
	v_add_f32_dpp v200, v200, v200 row_bcast:15 row_mask:0xa bank_mask:0xf
	s_nop 1
	v_add_f32_dpp v200, v200, v200 row_bcast:31 row_mask:0xc bank_mask:0xf
	s_nop 0
	v_readlane_b32 s27, v200, 63
	v_mul_f32_e32 v204, s27, v212
	v_mul_f32_e32 v205, 0x3f3504f3, v204
	v_cmp_lt_f32_e64 s[32:33], |v205|, 1.0
	s_and_b64 vcc, exec, s[32:33]
	s_cbranch_vccnz .Lsm_17
	v_fma_f32 v208, |v205|, s9, v214
	v_fma_f32 v208, |v205|, v208, s10
	v_fma_f32 v208, |v205|, v208, s11
	v_fma_f32 v208, |v205|, v208, s12
	v_fma_f32 v208, |v205|, v208, s13
	v_fma_f32 v208, |v205|, v208, s14
	v_fma_f32 v208, |v205|, v208, |v205|
	v_mul_f32_e32 v209, 0xbfb8aa3b, v208
	v_fma_f32 v210, v208, s15, -v209
	v_rndne_f32_e32 v211, v209
	v_fmac_f32_e32 v210, 0xb2a5705f, v208
	v_sub_f32_e32 v209, v209, v211
	v_add_f32_e32 v209, v209, v210
	v_cvt_i32_f32_e32 v210, v211
	v_exp_f32_e32 v209, v209
	v_cmp_nlt_f32_e32 vcc, s16, v208
	v_ldexp_f32 v209, v209, v210
	s_nop 0
	v_cndmask_b32_e32 v209, 0, v209, vcc
	v_cmp_ngt_f32_e32 vcc, s17, v208
	s_nop 1
	v_cndmask_b32_e32 v208, v215, v209, vcc
	v_sub_f32_e32 v210, 1.0, v208
	s_branch .Ljn_17

; DEV float gelu_exact(float v) { return 0.5f * v * (1.f + erff(v * 0.7071067811865476f)); }
; DEV void peer_gather_token(const Params& p, int tok) {
;     ...
;     for (int s = 0; s < 4; ++s) {
;       const int k = k4 + s;
;       if (k + 3 < 128) issue(k + 3, (s + 3) & 3);
;       const v6u dq = v6u{dn[s][0][0], dn[s][0][1], dn[s][1][0], dn[s][1][1], dn[s][2][0], dn[s][2][1]};
;       const v32f dv = __builtin_amdgcn_cvt_scalef32_pk32_f32_fp6(dq, 1.0f);
;       float d0 = 0.f, d1 = 0.f, d2 = 0.f, d3 = 0.f;
; #pragma unroll
;       for (int i = 0; i < 8; ++i) { d0 += dv[4 * i] * hx[4 * i]; d1 += dv[4 * i + 1] * hx[4 * i + 1]; d2 += dv[4 * i + 2] * hx[4 * i + 2]; d3 += dv[4 * i + 3] * hx[4 * i + 3]; }
;       const float d = wave_sum_fast((d0 + d1) + (d2 + d3)) * (1.f / DOWN_SCALE);
;       const float gk = __builtin_bit_cast(float, (k < 64) ? __builtin_amdgcn_readlane(g0, k) : __builtin_amdgcn_readlane(g1, k - 64));
;       const float act = gelu_exact(d) * gk * (1.f / UP_SCALE);
;       const v6u uq = v6u{up[s][0][0], up[s][0][1], up[s][1][0], up[s][1][1], up[s][2][0], up[s][2][1]};
;       const v32f uv = __builtin_amdgcn_cvt_scalef32_pk32_f32_fp6(uq, 1.0f);
; #pragma unroll
;       for (int i = 0; i < 32; ++i) acc[i] += act * uv[i];
.Ljn_17:
	v_bfi_b32 v209, s18, v210, v205
	v_mul_f32_e32 v208, 0.5, v204
	v_add_f32_e32 v209, 1.0, v209
	v_mul_f32_e32 v208, v208, v209
	v_mul_f32_e32 v208, s26, v208
	v_mul_f32_e32 v206, 0x3e800000, v208
	v_pk_fma_f32 v[66:67], v[2:3], v[206:207], v[66:67] op_sel_hi:[1,0,1]
	v_pk_fma_f32 v[68:69], v[4:5], v[206:207], v[68:69] op_sel_hi:[1,0,1]
	v_pk_fma_f32 v[70:71], v[6:7], v[206:207], v[70:71] op_sel_hi:[1,0,1]
	v_pk_fma_f32 v[72:73], v[8:9], v[206:207], v[72:73] op_sel_hi:[1,0,1]
	v_pk_fma_f32 v[74:75], v[10:11], v[206:207], v[74:75] op_sel_hi:[1,0,1]
	v_pk_fma_f32 v[76:77], v[12:13], v[206:207], v[76:77] op_sel_hi:[1,0,1]
	v_pk_fma_f32 v[78:79], v[14:15], v[206:207], v[78:79] op_sel_hi:[1,0,1]
	v_pk_fma_f32 v[80:81], v[16:17], v[206:207], v[80:81] op_sel_hi:[1,0,1]
	v_pk_fma_f32 v[82:83], v[18:19], v[206:207], v[82:83] op_sel_hi:[1,0,1]
	v_pk_fma_f32 v[84:85], v[20:21], v[206:207], v[84:85] op_sel_hi:[1,0,1]
	v_pk_fma_f32 v[86:87], v[22:23], v[206:207], v[86:87] op_sel_hi:[1,0,1]
	v_pk_fma_f32 v[88:89], v[24:25], v[206:207], v[88:89] op_sel_hi:[1,0,1]
	v_pk_fma_f32 v[90:91], v[26:27], v[206:207], v[90:91] op_sel_hi:[1,0,1]
	v_pk_fma_f32 v[92:93], v[28:29], v[206:207], v[92:93] op_sel_hi:[1,0,1]
	v_pk_fma_f32 v[94:95], v[30:31], v[206:207], v[94:95] op_sel_hi:[1,0,1]
	v_pk_fma_f32 v[96:97], v[32:33], v[206:207], v[96:97] op_sel_hi:[1,0,1]
	s_mul_i32 s40, s25, 0xc00
	s_add_u32 s28, s62, s40
	s_addc_u32 s29, s63, 0
	global_load_dwordx4 v[98:101], v1, s[28:29]
	global_load_dwordx4 v[102:105], v1, s[28:29] offset:2048
	global_load_dwordx4 v[106:109], v1, s[28:29] offset:1024
	s_waitcnt vmcnt(33)
	v_cvt_scalef32_pk32_f32_fp6 v[2:33], v[110:115], 1.0
	v_mul_f32_e32 v200, v2, v34
	v_mul_f32_e32 v201, v3, v35
	v_mul_f32_e32 v202, v4, v36
	v_mul_f32_e32 v203, v5, v37
	v_fmac_f32_e32 v200, v6, v38
	v_fmac_f32_e32 v201, v7, v39
	v_fmac_f32_e32 v202, v8, v40
	v_fmac_f32_e32 v203, v9, v41
	v_fmac_f32_e32 v200, v10, v42
	v_fmac_f32_e32 v201, v11, v43
	v_fmac_f32_e32 v202, v12, v44
	v_fmac_f32_e32 v203, v13, v45
	v_fmac_f32_e32 v200, v14, v46
	v_fmac_f32_e32 v201, v15, v47
	v_fmac_f32_e32 v202, v16, v48
	v_fmac_f32_e32 v203, v17, v49
	v_fmac_f32_e32 v200, v18, v50
	v_fmac_f32_e32 v201, v19, v51
	v_fmac_f32_e32 v202, v20, v52
	v_fmac_f32_e32 v203, v21, v53
	v_fmac_f32_e32 v200, v22, v54
	v_fmac_f32_e32 v201, v23, v55
	v_fmac_f32_e32 v202, v24, v56
	v_fmac_f32_e32 v203, v25, v57
	v_fmac_f32_e32 v200, v26, v58
	v_fmac_f32_e32 v201, v27, v59
	v_fmac_f32_e32 v202, v28, v60
	v_fmac_f32_e32 v203, v29, v61
	v_fmac_f32_e32 v200, v30, v62
	v_fmac_f32_e32 v201, v31, v63
	v_fmac_f32_e32 v202, v32, v64
	v_fmac_f32_e32 v203, v33, v65
	v_add_f32_e32 v200, v201, v200
	v_add_f32_e32 v202, v203, v202
	v_cvt_scalef32_pk32_f32_fp6 v[2:33], v[116:121], 1.0
	v_add_f32_e32 v200, v202, v200
	s_add_i32 s38, s24, 1
	v_readlane_b32 s26, v199, s38
	s_add_i32 s39, s23, 1
	v_readlane_b32 s25, v198, s39
	v_add_f32_dpp v200, v200, v200 quad_perm:[1,0,3,2] row_mask:0xf bank_mask:0xf bound_ctrl:1
	s_nop 1
	v_add_f32_dpp v200, v200, v200 quad_perm:[2,3,0,1] row_mask:0xf bank_mask:0xf bound_ctrl:1
	s_nop 1
	v_add_f32_dpp v200, v200, v200 row_half_mirror row_mask:0xf bank_mask:0xf bound_ctrl:1
	s_nop 1
	v_add_f32_dpp v200, v200, v200 row_mirror row_mask:0xf bank_mask:0xf bound_ctrl:1
	s_nop 1
	v_add_f32_dpp v200, v200, v200 row_bcast:15 row_mask:0xa bank_mask:0xf
	s_nop 1
	v_add_f32_dpp v200, v200, v200 row_bcast:31 row_mask:0xc bank_mask:0xf
	s_nop 0
	v_readlane_b32 s27, v200, 63
	v_mul_f32_e32 v204, s27, v212
	v_mul_f32_e32 v205, 0x3f3504f3, v204
	v_cmp_lt_f32_e64 s[32:33], |v205|, 1.0
	s_and_b64 vcc, exec, s[32:33]
	s_cbranch_vccnz .Lsm_19
	v_fma_f32 v208, |v205|, s9, v214
	v_fma_f32 v208, |v205|, v208, s10
	v_fma_f32 v208, |v205|, v208, s11
	v_fma_f32 v208, |v205|, v208, s12
	v_fma_f32 v208, |v205|, v208, s13
	v_fma_f32 v208, |v205|, v208, s14
	v_fma_f32 v208, |v205|, v208, |v205|
	v_mul_f32_e32 v209, 0xbfb8aa3b, v208
	v_fma_f32 v210, v208, s15, -v209
	v_rndne_f32_e32 v211, v209
	v_fmac_f32_e32 v210, 0xb2a5705f, v208
	v_sub_f32_e32 v209, v209, v211
	v_add_f32_e32 v209, v209, v210
	v_cvt_i32_f32_e32 v210, v211
	v_exp_f32_e32 v209, v209
	v_cmp_nlt_f32_e32 vcc, s16, v208
	v_ldexp_f32 v209, v209, v210
	s_nop 0
	v_cndmask_b32_e32 v209, 0, v209, vcc
	v_cmp_ngt_f32_e32 vcc, s17, v208
	s_nop 1
	v_cndmask_b32_e32 v208, v215, v209, vcc
	v_sub_f32_e32 v210, 1.0, v208
	s_branch .Ljn_19

; DEV float gelu_exact(float v) { return 0.5f * v * (1.f + erff(v * 0.7071067811865476f)); }
; DEV void peer_gather_token(const Params& p, int tok) {
;     ...
;     for (int s = 0; s < 4; ++s) {
;       const int k = k4 + s;
;       if (k + 3 < 128) issue(k + 3, (s + 3) & 3);
;       const v6u dq = v6u{dn[s][0][0], dn[s][0][1], dn[s][1][0], dn[s][1][1], dn[s][2][0], dn[s][2][1]};
;       const v32f dv = __builtin_amdgcn_cvt_scalef32_pk32_f32_fp6(dq, 1.0f);
;       float d0 = 0.f, d1 = 0.f, d2 = 0.f, d3 = 0.f;
; #pragma unroll
;       for (int i = 0; i < 8; ++i) { d0 += dv[4 * i] * hx[4 * i]; d1 += dv[4 * i + 1] * hx[4 * i + 1]; d2 += dv[4 * i + 2] * hx[4 * i + 2]; d3 += dv[4 * i + 3] * hx[4 * i + 3]; }
;       const float d = wave_sum_fast((d0 + d1) + (d2 + d3)) * (1.f / DOWN_SCALE);
;       const float gk = __builtin_bit_cast(float, (k < 64) ? __builtin_amdgcn_readlane(g0, k) : __builtin_amdgcn_readlane(g1, k - 64));
;       const float act = gelu_exact(d) * gk * (1.f / UP_SCALE);
;       const v6u uq = v6u{up[s][0][0], up[s][0][1], up[s][1][0], up[s][1][1], up[s][2][0], up[s][2][1]};
;       const v32f uv = __builtin_amdgcn_cvt_scalef32_pk32_f32_fp6(uq, 1.0f);
; #pragma unroll
;       for (int i = 0; i < 32; ++i) acc[i] += act * uv[i];
.Ljn_19:
	v_bfi_b32 v209, s18, v210, v205
	v_mul_f32_e32 v208, 0.5, v204
	v_add_f32_e32 v209, 1.0, v209
	v_mul_f32_e32 v208, v208, v209
	v_mul_f32_e32 v208, s26, v208
	v_mul_f32_e32 v206, 0x3e800000, v208
	v_pk_fma_f32 v[66:67], v[2:3], v[206:207], v[66:67] op_sel_hi:[1,0,1]
	v_pk_fma_f32 v[68:69], v[4:5], v[206:207], v[68:69] op_sel_hi:[1,0,1]
	v_pk_fma_f32 v[70:71], v[6:7], v[206:207], v[70:71] op_sel_hi:[1,0,1]
	v_pk_fma_f32 v[72:73], v[8:9], v[206:207], v[72:73] op_sel_hi:[1,0,1]
	v_pk_fma_f32 v[74:75], v[10:11], v[206:207], v[74:75] op_sel_hi:[1,0,1]
	v_pk_fma_f32 v[76:77], v[12:13], v[206:207], v[76:77] op_sel_hi:[1,0,1]
	v_pk_fma_f32 v[78:79], v[14:15], v[206:207], v[78:79] op_sel_hi:[1,0,1]
	v_pk_fma_f32 v[80:81], v[16:17], v[206:207], v[80:81] op_sel_hi:[1,0,1]
	v_pk_fma_f32 v[82:83], v[18:19], v[206:207], v[82:83] op_sel_hi:[1,0,1]
	v_pk_fma_f32 v[84:85], v[20:21], v[206:207], v[84:85] op_sel_hi:[1,0,1]
	v_pk_fma_f32 v[86:87], v[22:23], v[206:207], v[86:87] op_sel_hi:[1,0,1]
	v_pk_fma_f32 v[88:89], v[24:25], v[206:207], v[88:89] op_sel_hi:[1,0,1]
	v_pk_fma_f32 v[90:91], v[26:27], v[206:207], v[90:91] op_sel_hi:[1,0,1]
	v_pk_fma_f32 v[92:93], v[28:29], v[206:207], v[92:93] op_sel_hi:[1,0,1]
	v_pk_fma_f32 v[94:95], v[30:31], v[206:207], v[94:95] op_sel_hi:[1,0,1]
	v_pk_fma_f32 v[96:97], v[32:33], v[206:207], v[96:97] op_sel_hi:[1,0,1]
	s_mul_i32 s40, s25, 0xc00
	s_add_u32 s28, s62, s40
	s_addc_u32 s29, s63, 0
	global_load_dwordx4 v[110:113], v1, s[28:29]
	global_load_dwordx4 v[114:117], v1, s[28:29] offset:2048
	global_load_dwordx4 v[118:121], v1, s[28:29] offset:1024
	s_waitcnt vmcnt(33)
	v_cvt_scalef32_pk32_f32_fp6 v[2:33], v[122:127], 1.0
	v_mul_f32_e32 v200, v2, v34
	v_mul_f32_e32 v201, v3, v35
	v_mul_f32_e32 v202, v4, v36
	v_mul_f32_e32 v203, v5, v37
	v_fmac_f32_e32 v200, v6, v38
	v_fmac_f32_e32 v201, v7, v39
	v_fmac_f32_e32 v202, v8, v40
	v_fmac_f32_e32 v203, v9, v41
	v_fmac_f32_e32 v200, v10, v42
	v_fmac_f32_e32 v201, v11, v43
	v_fmac_f32_e32 v202, v12, v44
	v_fmac_f32_e32 v203, v13, v45
	v_fmac_f32_e32 v200, v14, v46
	v_fmac_f32_e32 v201, v15, v47
	v_fmac_f32_e32 v202, v16, v48
	v_fmac_f32_e32 v203, v17, v49
	v_fmac_f32_e32 v200, v18, v50
	v_fmac_f32_e32 v201, v19, v51
	v_fmac_f32_e32 v202, v20, v52
	v_fmac_f32_e32 v203, v21, v53
	v_fmac_f32_e32 v200, v22, v54
	v_fmac_f32_e32 v201, v23, v55
	v_fmac_f32_e32 v202, v24, v56
	v_fmac_f32_e32 v203, v25, v57
	v_fmac_f32_e32 v200, v26, v58
	v_fmac_f32_e32 v201, v27, v59
	v_fmac_f32_e32 v202, v28, v60
	v_fmac_f32_e32 v203, v29, v61
	v_fmac_f32_e32 v200, v30, v62
	v_fmac_f32_e32 v201, v31, v63
	v_fmac_f32_e32 v202, v32, v64
	v_fmac_f32_e32 v203, v33, v65
	v_add_f32_e32 v200, v201, v200
	v_add_f32_e32 v202, v203, v202
	v_cvt_scalef32_pk32_f32_fp6 v[2:33], v[128:133], 1.0
	v_add_f32_e32 v200, v202, v200
	s_add_i32 s38, s24, 2
	v_readlane_b32 s26, v199, s38
	s_add_i32 s39, s23, 2
	v_readlane_b32 s25, v198, s39
	v_add_f32_dpp v200, v200, v200 quad_perm:[1,0,3,2] row_mask:0xf bank_mask:0xf bound_ctrl:1
	s_nop 1
	v_add_f32_dpp v200, v200, v200 quad_perm:[2,3,0,1] row_mask:0xf bank_mask:0xf bound_ctrl:1
	s_nop 1
	v_add_f32_dpp v200, v200, v200 row_half_mirror row_mask:0xf bank_mask:0xf bound_ctrl:1
	s_nop 1
	v_add_f32_dpp v200, v200, v200 row_mirror row_mask:0xf bank_mask:0xf bound_ctrl:1
	s_nop 1
	v_add_f32_dpp v200, v200, v200 row_bcast:15 row_mask:0xa bank_mask:0xf
	s_nop 1
	v_add_f32_dpp v200, v200, v200 row_bcast:31 row_mask:0xc bank_mask:0xf
	s_nop 0
	v_readlane_b32 s27, v200, 63
	v_mul_f32_e32 v204, s27, v212
	v_mul_f32_e32 v205, 0x3f3504f3, v204
	v_cmp_lt_f32_e64 s[32:33], |v205|, 1.0
	s_and_b64 vcc, exec, s[32:33]
	s_cbranch_vccnz .Lsm_21
	v_fma_f32 v208, |v205|, s9, v214
	v_fma_f32 v208, |v205|, v208, s10
	v_fma_f32 v208, |v205|, v208, s11
	v_fma_f32 v208, |v205|, v208, s12
	v_fma_f32 v208, |v205|, v208, s13
	v_fma_f32 v208, |v205|, v208, s14
	v_fma_f32 v208, |v205|, v208, |v205|
	v_mul_f32_e32 v209, 0xbfb8aa3b, v208
	v_fma_f32 v210, v208, s15, -v209
	v_rndne_f32_e32 v211, v209
	v_fmac_f32_e32 v210, 0xb2a5705f, v208
	v_sub_f32_e32 v209, v209, v211
	v_add_f32_e32 v209, v209, v210
	v_cvt_i32_f32_e32 v210, v211
	v_exp_f32_e32 v209, v209
	v_cmp_nlt_f32_e32 vcc, s16, v208
	v_ldexp_f32 v209, v209, v210
	s_nop 0
	v_cndmask_b32_e32 v209, 0, v209, vcc
	v_cmp_ngt_f32_e32 vcc, s17, v208
	s_nop 1
	v_cndmask_b32_e32 v208, v215, v209, vcc
	v_sub_f32_e32 v210, 1.0, v208
	s_branch .Ljn_21

; DEV float gelu_exact(float v) { return 0.5f * v * (1.f + erff(v * 0.7071067811865476f)); }
; DEV void peer_gather_token(const Params& p, int tok) {
;     ...
;     for (int s = 0; s < 4; ++s) {
;       const int k = k4 + s;
;       if (k + 3 < 128) issue(k + 3, (s + 3) & 3);
;       const v6u dq = v6u{dn[s][0][0], dn[s][0][1], dn[s][1][0], dn[s][1][1], dn[s][2][0], dn[s][2][1]};
;       const v32f dv = __builtin_amdgcn_cvt_scalef32_pk32_f32_fp6(dq, 1.0f);
;       float d0 = 0.f, d1 = 0.f, d2 = 0.f, d3 = 0.f;
; #pragma unroll
;       for (int i = 0; i < 8; ++i) { d0 += dv[4 * i] * hx[4 * i]; d1 += dv[4 * i + 1] * hx[4 * i + 1]; d2 += dv[4 * i + 2] * hx[4 * i + 2]; d3 += dv[4 * i + 3] * hx[4 * i + 3]; }
;       const float d = wave_sum_fast((d0 + d1) + (d2 + d3)) * (1.f / DOWN_SCALE);
;       const float gk = __builtin_bit_cast(float, (k < 64) ? __builtin_amdgcn_readlane(g0, k) : __builtin_amdgcn_readlane(g1, k - 64));
;       const float act = gelu_exact(d) * gk * (1.f / UP_SCALE);
;       const v6u uq = v6u{up[s][0][0], up[s][0][1], up[s][1][0], up[s][1][1], up[s][2][0], up[s][2][1]};
;       const v32f uv = __builtin_amdgcn_cvt_scalef32_pk32_f32_fp6(uq, 1.0f);
; #pragma unroll
;       for (int i = 0; i < 32; ++i) acc[i] += act * uv[i];
.Ljn_21:
	v_bfi_b32 v209, s18, v210, v205
	v_mul_f32_e32 v208, 0.5, v204
	v_add_f32_e32 v209, 1.0, v209
	v_mul_f32_e32 v208, v208, v209
	v_mul_f32_e32 v208, s26, v208
	v_mul_f32_e32 v206, 0x3e800000, v208
	v_pk_fma_f32 v[66:67], v[2:3], v[206:207], v[66:67] op_sel_hi:[1,0,1]
	v_pk_fma_f32 v[68:69], v[4:5], v[206:207], v[68:69] op_sel_hi:[1,0,1]
	v_pk_fma_f32 v[70:71], v[6:7], v[206:207], v[70:71] op_sel_hi:[1,0,1]
	v_pk_fma_f32 v[72:73], v[8:9], v[206:207], v[72:73] op_sel_hi:[1,0,1]
	v_pk_fma_f32 v[74:75], v[10:11], v[206:207], v[74:75] op_sel_hi:[1,0,1]
	v_pk_fma_f32 v[76:77], v[12:13], v[206:207], v[76:77] op_sel_hi:[1,0,1]
	v_pk_fma_f32 v[78:79], v[14:15], v[206:207], v[78:79] op_sel_hi:[1,0,1]
	v_pk_fma_f32 v[80:81], v[16:17], v[206:207], v[80:81] op_sel_hi:[1,0,1]
	v_pk_fma_f32 v[82:83], v[18:19], v[206:207], v[82:83] op_sel_hi:[1,0,1]
	v_pk_fma_f32 v[84:85], v[20:21], v[206:207], v[84:85] op_sel_hi:[1,0,1]
	v_pk_fma_f32 v[86:87], v[22:23], v[206:207], v[86:87] op_sel_hi:[1,0,1]
	v_pk_fma_f32 v[88:89], v[24:25], v[206:207], v[88:89] op_sel_hi:[1,0,1]
	v_pk_fma_f32 v[90:91], v[26:27], v[206:207], v[90:91] op_sel_hi:[1,0,1]
	v_pk_fma_f32 v[92:93], v[28:29], v[206:207], v[92:93] op_sel_hi:[1,0,1]
	v_pk_fma_f32 v[94:95], v[30:31], v[206:207], v[94:95] op_sel_hi:[1,0,1]
	v_pk_fma_f32 v[96:97], v[32:33], v[206:207], v[96:97] op_sel_hi:[1,0,1]
	s_mul_i32 s40, s25, 0xc00
	s_add_u32 s28, s62, s40
	s_addc_u32 s29, s63, 0
	global_load_dwordx4 v[122:125], v1, s[28:29]
	global_load_dwordx4 v[126:129], v1, s[28:29] offset:2048
	global_load_dwordx4 v[130:133], v1, s[28:29] offset:1024
	s_waitcnt vmcnt(33)
	v_cvt_scalef32_pk32_f32_fp6 v[2:33], v[134:139], 1.0
	v_mul_f32_e32 v200, v2, v34
	v_mul_f32_e32 v201, v3, v35
	v_mul_f32_e32 v202, v4, v36
	v_mul_f32_e32 v203, v5, v37
	v_fmac_f32_e32 v200, v6, v38
	v_fmac_f32_e32 v201, v7, v39
	v_fmac_f32_e32 v202, v8, v40
	v_fmac_f32_e32 v203, v9, v41
	v_fmac_f32_e32 v200, v10, v42
	v_fmac_f32_e32 v201, v11, v43
	v_fmac_f32_e32 v202, v12, v44
	v_fmac_f32_e32 v203, v13, v45
	v_fmac_f32_e32 v200, v14, v46
	v_fmac_f32_e32 v201, v15, v47
	v_fmac_f32_e32 v202, v16, v48
	v_fmac_f32_e32 v203, v17, v49
	v_fmac_f32_e32 v200, v18, v50
	v_fmac_f32_e32 v201, v19, v51
	v_fmac_f32_e32 v202, v20, v52
	v_fmac_f32_e32 v203, v21, v53
	v_fmac_f32_e32 v200, v22, v54
	v_fmac_f32_e32 v201, v23, v55
	v_fmac_f32_e32 v202, v24, v56
	v_fmac_f32_e32 v203, v25, v57
	v_fmac_f32_e32 v200, v26, v58
	v_fmac_f32_e32 v201, v27, v59
	v_fmac_f32_e32 v202, v28, v60
	v_fmac_f32_e32 v203, v29, v61
	v_fmac_f32_e32 v200, v30, v62
	v_fmac_f32_e32 v201, v31, v63
	v_fmac_f32_e32 v202, v32, v64
	v_fmac_f32_e32 v203, v33, v65
	v_add_f32_e32 v200, v201, v200
	v_add_f32_e32 v202, v203, v202
	v_cvt_scalef32_pk32_f32_fp6 v[2:33], v[140:145], 1.0
	v_add_f32_e32 v200, v202, v200
	s_add_i32 s38, s24, 3
	v_readlane_b32 s26, v199, s38
	s_add_i32 s39, s23, 3
	v_readlane_b32 s25, v198, s39
	v_add_f32_dpp v200, v200, v200 quad_perm:[1,0,3,2] row_mask:0xf bank_mask:0xf bound_ctrl:1
	s_nop 1
	v_add_f32_dpp v200, v200, v200 quad_perm:[2,3,0,1] row_mask:0xf bank_mask:0xf bound_ctrl:1
	s_nop 1
	v_add_f32_dpp v200, v200, v200 row_half_mirror row_mask:0xf bank_mask:0xf bound_ctrl:1
	s_nop 1
	v_add_f32_dpp v200, v200, v200 row_mirror row_mask:0xf bank_mask:0xf bound_ctrl:1
	s_nop 1
	v_add_f32_dpp v200, v200, v200 row_bcast:15 row_mask:0xa bank_mask:0xf
	s_nop 1
	v_add_f32_dpp v200, v200, v200 row_bcast:31 row_mask:0xc bank_mask:0xf
	s_nop 0
	v_readlane_b32 s27, v200, 63
	v_mul_f32_e32 v204, s27, v212
	v_mul_f32_e32 v205, 0x3f3504f3, v204
	v_cmp_lt_f32_e64 s[32:33], |v205|, 1.0
	s_and_b64 vcc, exec, s[32:33]
	s_cbranch_vccnz .Lsm_23
	v_fma_f32 v208, |v205|, s9, v214
	v_fma_f32 v208, |v205|, v208, s10
	v_fma_f32 v208, |v205|, v208, s11
	v_fma_f32 v208, |v205|, v208, s12
	v_fma_f32 v208, |v205|, v208, s13
	v_fma_f32 v208, |v205|, v208, s14
	v_fma_f32 v208, |v205|, v208, |v205|
	v_mul_f32_e32 v209, 0xbfb8aa3b, v208
	v_fma_f32 v210, v208, s15, -v209
	v_rndne_f32_e32 v211, v209
	v_fmac_f32_e32 v210, 0xb2a5705f, v208
	v_sub_f32_e32 v209, v209, v211
	v_add_f32_e32 v209, v209, v210
	v_cvt_i32_f32_e32 v210, v211
	v_exp_f32_e32 v209, v209
	v_cmp_nlt_f32_e32 vcc, s16, v208
	v_ldexp_f32 v209, v209, v210
	s_nop 0
	v_cndmask_b32_e32 v209, 0, v209, vcc
	v_cmp_ngt_f32_e32 vcc, s17, v208
	s_nop 1
	v_cndmask_b32_e32 v208, v215, v209, vcc
	v_sub_f32_e32 v210, 1.0, v208
	s_branch .Ljn_23

; DEV float gelu_exact(float v) { return 0.5f * v * (1.f + erff(v * 0.7071067811865476f)); }
; DEV void peer_gather_token(const Params& p, int tok) {
;     ...
;     for (int s = 0; s < 4; ++s) {
;       const int k = k4 + s;
;       if (k + 3 < 128) issue(k + 3, (s + 3) & 3);
;       const v6u dq = v6u{dn[s][0][0], dn[s][0][1], dn[s][1][0], dn[s][1][1], dn[s][2][0], dn[s][2][1]};
;       const v32f dv = __builtin_amdgcn_cvt_scalef32_pk32_f32_fp6(dq, 1.0f);
;       float d0 = 0.f, d1 = 0.f, d2 = 0.f, d3 = 0.f;
; #pragma unroll
;       for (int i = 0; i < 8; ++i) { d0 += dv[4 * i] * hx[4 * i]; d1 += dv[4 * i + 1] * hx[4 * i + 1]; d2 += dv[4 * i + 2] * hx[4 * i + 2]; d3 += dv[4 * i + 3] * hx[4 * i + 3]; }
;       const float d = wave_sum_fast((d0 + d1) + (d2 + d3)) * (1.f / DOWN_SCALE);
;       const float gk = __builtin_bit_cast(float, (k < 64) ? __builtin_amdgcn_readlane(g0, k) : __builtin_amdgcn_readlane(g1, k - 64));
;       const float act = gelu_exact(d) * gk * (1.f / UP_SCALE);
;       const v6u uq = v6u{up[s][0][0], up[s][0][1], up[s][1][0], up[s][1][1], up[s][2][0], up[s][2][1]};
;       const v32f uv = __builtin_amdgcn_cvt_scalef32_pk32_f32_fp6(uq, 1.0f);
; #pragma unroll
;       for (int i = 0; i < 32; ++i) acc[i] += act * uv[i];
.Ljn_23:
	v_bfi_b32 v209, s18, v210, v205
	v_mul_f32_e32 v208, 0.5, v204
	v_add_f32_e32 v209, 1.0, v209
	v_mul_f32_e32 v208, v208, v209
	v_mul_f32_e32 v208, s26, v208
	v_mul_f32_e32 v206, 0x3e800000, v208
	v_pk_fma_f32 v[66:67], v[2:3], v[206:207], v[66:67] op_sel_hi:[1,0,1]
	v_pk_fma_f32 v[68:69], v[4:5], v[206:207], v[68:69] op_sel_hi:[1,0,1]
	v_pk_fma_f32 v[70:71], v[6:7], v[206:207], v[70:71] op_sel_hi:[1,0,1]
	v_pk_fma_f32 v[72:73], v[8:9], v[206:207], v[72:73] op_sel_hi:[1,0,1]
	v_pk_fma_f32 v[74:75], v[10:11], v[206:207], v[74:75] op_sel_hi:[1,0,1]
	v_pk_fma_f32 v[76:77], v[12:13], v[206:207], v[76:77] op_sel_hi:[1,0,1]
	v_pk_fma_f32 v[78:79], v[14:15], v[206:207], v[78:79] op_sel_hi:[1,0,1]
	v_pk_fma_f32 v[80:81], v[16:17], v[206:207], v[80:81] op_sel_hi:[1,0,1]
	v_pk_fma_f32 v[82:83], v[18:19], v[206:207], v[82:83] op_sel_hi:[1,0,1]
	v_pk_fma_f32 v[84:85], v[20:21], v[206:207], v[84:85] op_sel_hi:[1,0,1]
	v_pk_fma_f32 v[86:87], v[22:23], v[206:207], v[86:87] op_sel_hi:[1,0,1]
	v_pk_fma_f32 v[88:89], v[24:25], v[206:207], v[88:89] op_sel_hi:[1,0,1]
	v_pk_fma_f32 v[90:91], v[26:27], v[206:207], v[90:91] op_sel_hi:[1,0,1]
	v_pk_fma_f32 v[92:93], v[28:29], v[206:207], v[92:93] op_sel_hi:[1,0,1]
	v_pk_fma_f32 v[94:95], v[30:31], v[206:207], v[94:95] op_sel_hi:[1,0,1]
	v_pk_fma_f32 v[96:97], v[32:33], v[206:207], v[96:97] op_sel_hi:[1,0,1]
	s_mul_i32 s40, s25, 0xc00
	s_add_u32 s28, s62, s40
	s_addc_u32 s29, s63, 0
	global_load_dwordx4 v[134:137], v1, s[28:29]
	global_load_dwordx4 v[138:141], v1, s[28:29] offset:2048
	global_load_dwordx4 v[142:145], v1, s[28:29] offset:1024
	s_waitcnt vmcnt(33)
	v_cvt_scalef32_pk32_f32_fp6 v[2:33], v[146:151], 1.0
	v_mul_f32_e32 v200, v2, v34
	v_mul_f32_e32 v201, v3, v35
	v_mul_f32_e32 v202, v4, v36
	v_mul_f32_e32 v203, v5, v37
	v_fmac_f32_e32 v200, v6, v38
	v_fmac_f32_e32 v201, v7, v39
	v_fmac_f32_e32 v202, v8, v40
	v_fmac_f32_e32 v203, v9, v41
	v_fmac_f32_e32 v200, v10, v42
	v_fmac_f32_e32 v201, v11, v43
	v_fmac_f32_e32 v202, v12, v44
	v_fmac_f32_e32 v203, v13, v45
	v_fmac_f32_e32 v200, v14, v46
	v_fmac_f32_e32 v201, v15, v47
	v_fmac_f32_e32 v202, v16, v48
	v_fmac_f32_e32 v203, v17, v49
	v_fmac_f32_e32 v200, v18, v50
	v_fmac_f32_e32 v201, v19, v51
	v_fmac_f32_e32 v202, v20, v52
	v_fmac_f32_e32 v203, v21, v53
	v_fmac_f32_e32 v200, v22, v54
	v_fmac_f32_e32 v201, v23, v55
	v_fmac_f32_e32 v202, v24, v56
	v_fmac_f32_e32 v203, v25, v57
	v_fmac_f32_e32 v200, v26, v58
	v_fmac_f32_e32 v201, v27, v59
	v_fmac_f32_e32 v202, v28, v60
	v_fmac_f32_e32 v203, v29, v61
	v_fmac_f32_e32 v200, v30, v62
	v_fmac_f32_e32 v201, v31, v63
	v_fmac_f32_e32 v202, v32, v64
	v_fmac_f32_e32 v203, v33, v65
	v_add_f32_e32 v200, v201, v200
	v_add_f32_e32 v202, v203, v202
	v_cvt_scalef32_pk32_f32_fp6 v[2:33], v[152:157], 1.0
	v_add_f32_e32 v200, v202, v200
	s_add_i32 s38, s24, 4
	v_readlane_b32 s26, v199, s38
	s_add_i32 s39, s23, 4
	v_readlane_b32 s25, v198, s39
	v_add_f32_dpp v200, v200, v200 quad_perm:[1,0,3,2] row_mask:0xf bank_mask:0xf bound_ctrl:1
	s_nop 1
	v_add_f32_dpp v200, v200, v200 quad_perm:[2,3,0,1] row_mask:0xf bank_mask:0xf bound_ctrl:1
	s_nop 1
	v_add_f32_dpp v200, v200, v200 row_half_mirror row_mask:0xf bank_mask:0xf bound_ctrl:1
	s_nop 1
	v_add_f32_dpp v200, v200, v200 row_mirror row_mask:0xf bank_mask:0xf bound_ctrl:1
	s_nop 1
	v_add_f32_dpp v200, v200, v200 row_bcast:15 row_mask:0xa bank_mask:0xf
	s_nop 1
	v_add_f32_dpp v200, v200, v200 row_bcast:31 row_mask:0xc bank_mask:0xf
	s_nop 0
	v_readlane_b32 s27, v200, 63
	v_mul_f32_e32 v204, s27, v212
	v_mul_f32_e32 v205, 0x3f3504f3, v204
	v_cmp_lt_f32_e64 s[32:33], |v205|, 1.0
	s_and_b64 vcc, exec, s[32:33]
	s_cbranch_vccnz .Lsm_25
	v_fma_f32 v208, |v205|, s9, v214
	v_fma_f32 v208, |v205|, v208, s10
	v_fma_f32 v208, |v205|, v208, s11
	v_fma_f32 v208, |v205|, v208, s12
	v_fma_f32 v208, |v205|, v208, s13
	v_fma_f32 v208, |v205|, v208, s14
	v_fma_f32 v208, |v205|, v208, |v205|
	v_mul_f32_e32 v209, 0xbfb8aa3b, v208
	v_fma_f32 v210, v208, s15, -v209
	v_rndne_f32_e32 v211, v209
	v_fmac_f32_e32 v210, 0xb2a5705f, v208
	v_sub_f32_e32 v209, v209, v211
	v_add_f32_e32 v209, v209, v210
	v_cvt_i32_f32_e32 v210, v211
	v_exp_f32_e32 v209, v209
	v_cmp_nlt_f32_e32 vcc, s16, v208
	v_ldexp_f32 v209, v209, v210
	s_nop 0
	v_cndmask_b32_e32 v209, 0, v209, vcc
	v_cmp_ngt_f32_e32 vcc, s17, v208
	s_nop 1
	v_cndmask_b32_e32 v208, v215, v209, vcc
	v_sub_f32_e32 v210, 1.0, v208
	s_branch .Ljn_25

; DEV float gelu_exact(float v) { return 0.5f * v * (1.f + erff(v * 0.7071067811865476f)); }
; DEV void peer_gather_token(const Params& p, int tok) {
;     ...
;     for (int s = 0; s < 4; ++s) {
;       const int k = k4 + s;
;       if (k + 3 < 128) issue(k + 3, (s + 3) & 3);
;       const v6u dq = v6u{dn[s][0][0], dn[s][0][1], dn[s][1][0], dn[s][1][1], dn[s][2][0], dn[s][2][1]};
;       const v32f dv = __builtin_amdgcn_cvt_scalef32_pk32_f32_fp6(dq, 1.0f);
;       float d0 = 0.f, d1 = 0.f, d2 = 0.f, d3 = 0.f;
; #pragma unroll
;       for (int i = 0; i < 8; ++i) { d0 += dv[4 * i] * hx[4 * i]; d1 += dv[4 * i + 1] * hx[4 * i + 1]; d2 += dv[4 * i + 2] * hx[4 * i + 2]; d3 += dv[4 * i + 3] * hx[4 * i + 3]; }
;       const float d = wave_sum_fast((d0 + d1) + (d2 + d3)) * (1.f / DOWN_SCALE);
;       const float gk = __builtin_bit_cast(float, (k < 64) ? __builtin_amdgcn_readlane(g0, k) : __builtin_amdgcn_readlane(g1, k - 64));
;       const float act = gelu_exact(d) * gk * (1.f / UP_SCALE);
;       const v6u uq = v6u{up[s][0][0], up[s][0][1], up[s][1][0], up[s][1][1], up[s][2][0], up[s][2][1]};
;       const v32f uv = __builtin_amdgcn_cvt_scalef32_pk32_f32_fp6(uq, 1.0f);
; #pragma unroll
;       for (int i = 0; i < 32; ++i) acc[i] += act * uv[i];
.Ljn_25:
	v_bfi_b32 v209, s18, v210, v205
	v_mul_f32_e32 v208, 0.5, v204
	v_add_f32_e32 v209, 1.0, v209
	v_mul_f32_e32 v208, v208, v209
	v_mul_f32_e32 v208, s26, v208
	v_mul_f32_e32 v206, 0x3e800000, v208
	v_pk_fma_f32 v[66:67], v[2:3], v[206:207], v[66:67] op_sel_hi:[1,0,1]
	v_pk_fma_f32 v[68:69], v[4:5], v[206:207], v[68:69] op_sel_hi:[1,0,1]
	v_pk_fma_f32 v[70:71], v[6:7], v[206:207], v[70:71] op_sel_hi:[1,0,1]
	v_pk_fma_f32 v[72:73], v[8:9], v[206:207], v[72:73] op_sel_hi:[1,0,1]
	v_pk_fma_f32 v[74:75], v[10:11], v[206:207], v[74:75] op_sel_hi:[1,0,1]
	v_pk_fma_f32 v[76:77], v[12:13], v[206:207], v[76:77] op_sel_hi:[1,0,1]
	v_pk_fma_f32 v[78:79], v[14:15], v[206:207], v[78:79] op_sel_hi:[1,0,1]
	v_pk_fma_f32 v[80:81], v[16:17], v[206:207], v[80:81] op_sel_hi:[1,0,1]
	v_pk_fma_f32 v[82:83], v[18:19], v[206:207], v[82:83] op_sel_hi:[1,0,1]
	v_pk_fma_f32 v[84:85], v[20:21], v[206:207], v[84:85] op_sel_hi:[1,0,1]
	v_pk_fma_f32 v[86:87], v[22:23], v[206:207], v[86:87] op_sel_hi:[1,0,1]
	v_pk_fma_f32 v[88:89], v[24:25], v[206:207], v[88:89] op_sel_hi:[1,0,1]
	v_pk_fma_f32 v[90:91], v[26:27], v[206:207], v[90:91] op_sel_hi:[1,0,1]
	v_pk_fma_f32 v[92:93], v[28:29], v[206:207], v[92:93] op_sel_hi:[1,0,1]
	v_pk_fma_f32 v[94:95], v[30:31], v[206:207], v[94:95] op_sel_hi:[1,0,1]
	v_pk_fma_f32 v[96:97], v[32:33], v[206:207], v[96:97] op_sel_hi:[1,0,1]
	s_mul_i32 s40, s25, 0xc00
	s_add_u32 s28, s62, s40
	s_addc_u32 s29, s63, 0
	global_load_dwordx4 v[146:149], v1, s[28:29]
	global_load_dwordx4 v[150:153], v1, s[28:29] offset:2048
	global_load_dwordx4 v[154:157], v1, s[28:29] offset:1024
	s_waitcnt vmcnt(33)
	v_cvt_scalef32_pk32_f32_fp6 v[2:33], v[158:163], 1.0
	v_mul_f32_e32 v200, v2, v34
	v_mul_f32_e32 v201, v3, v35
	v_mul_f32_e32 v202, v4, v36
	v_mul_f32_e32 v203, v5, v37
	v_fmac_f32_e32 v200, v6, v38
	v_fmac_f32_e32 v201, v7, v39
	v_fmac_f32_e32 v202, v8, v40
	v_fmac_f32_e32 v203, v9, v41
	v_fmac_f32_e32 v200, v10, v42
	v_fmac_f32_e32 v201, v11, v43
	v_fmac_f32_e32 v202, v12, v44
	v_fmac_f32_e32 v203, v13, v45
	v_fmac_f32_e32 v200, v14, v46
	v_fmac_f32_e32 v201, v15, v47
	v_fmac_f32_e32 v202, v16, v48
	v_fmac_f32_e32 v203, v17, v49
	v_fmac_f32_e32 v200, v18, v50
	v_fmac_f32_e32 v201, v19, v51
	v_fmac_f32_e32 v202, v20, v52
	v_fmac_f32_e32 v203, v21, v53
	v_fmac_f32_e32 v200, v22, v54
	v_fmac_f32_e32 v201, v23, v55
	v_fmac_f32_e32 v202, v24, v56
	v_fmac_f32_e32 v203, v25, v57
	v_fmac_f32_e32 v200, v26, v58
	v_fmac_f32_e32 v201, v27, v59
	v_fmac_f32_e32 v202, v28, v60
	v_fmac_f32_e32 v203, v29, v61
	v_fmac_f32_e32 v200, v30, v62
	v_fmac_f32_e32 v201, v31, v63
	v_fmac_f32_e32 v202, v32, v64
	v_fmac_f32_e32 v203, v33, v65
	v_add_f32_e32 v200, v201, v200
	v_add_f32_e32 v202, v203, v202
	v_cvt_scalef32_pk32_f32_fp6 v[2:33], v[164:169], 1.0
	v_add_f32_e32 v200, v202, v200
	s_add_i32 s38, s24, 5
	v_readlane_b32 s26, v199, s38
	s_add_i32 s39, s23, 5
	v_readlane_b32 s25, v198, s39
	v_add_f32_dpp v200, v200, v200 quad_perm:[1,0,3,2] row_mask:0xf bank_mask:0xf bound_ctrl:1
	s_nop 1
	v_add_f32_dpp v200, v200, v200 quad_perm:[2,3,0,1] row_mask:0xf bank_mask:0xf bound_ctrl:1
	s_nop 1
	v_add_f32_dpp v200, v200, v200 row_half_mirror row_mask:0xf bank_mask:0xf bound_ctrl:1
	s_nop 1
	v_add_f32_dpp v200, v200, v200 row_mirror row_mask:0xf bank_mask:0xf bound_ctrl:1
	s_nop 1
	v_add_f32_dpp v200, v200, v200 row_bcast:15 row_mask:0xa bank_mask:0xf
	s_nop 1
	v_add_f32_dpp v200, v200, v200 row_bcast:31 row_mask:0xc bank_mask:0xf
	s_nop 0
	v_readlane_b32 s27, v200, 63
	v_mul_f32_e32 v204, s27, v212
	v_mul_f32_e32 v205, 0x3f3504f3, v204
	v_cmp_lt_f32_e64 s[32:33], |v205|, 1.0
	s_and_b64 vcc, exec, s[32:33]
	s_cbranch_vccnz .Lsm_27
	v_fma_f32 v208, |v205|, s9, v214
	v_fma_f32 v208, |v205|, v208, s10
	v_fma_f32 v208, |v205|, v208, s11
	v_fma_f32 v208, |v205|, v208, s12
	v_fma_f32 v208, |v205|, v208, s13
	v_fma_f32 v208, |v205|, v208, s14
	v_fma_f32 v208, |v205|, v208, |v205|
	v_mul_f32_e32 v209, 0xbfb8aa3b, v208
	v_fma_f32 v210, v208, s15, -v209
	v_rndne_f32_e32 v211, v209
	v_fmac_f32_e32 v210, 0xb2a5705f, v208
	v_sub_f32_e32 v209, v209, v211
	v_add_f32_e32 v209, v209, v210
	v_cvt_i32_f32_e32 v210, v211
	v_exp_f32_e32 v209, v209
	v_cmp_nlt_f32_e32 vcc, s16, v208
	v_ldexp_f32 v209, v209, v210
	s_nop 0
	v_cndmask_b32_e32 v209, 0, v209, vcc
	v_cmp_ngt_f32_e32 vcc, s17, v208
	s_nop 1
	v_cndmask_b32_e32 v208, v215, v209, vcc
	v_sub_f32_e32 v210, 1.0, v208
	s_branch .Ljn_27

; DEV float gelu_exact(float v) { return 0.5f * v * (1.f + erff(v * 0.7071067811865476f)); }
; DEV void peer_gather_token(const Params& p, int tok) {
;     ...
;     for (int s = 0; s < 4; ++s) {
;       const int k = k4 + s;
;       if (k + 3 < 128) issue(k + 3, (s + 3) & 3);
;       const v6u dq = v6u{dn[s][0][0], dn[s][0][1], dn[s][1][0], dn[s][1][1], dn[s][2][0], dn[s][2][1]};
;       const v32f dv = __builtin_amdgcn_cvt_scalef32_pk32_f32_fp6(dq, 1.0f);
;       float d0 = 0.f, d1 = 0.f, d2 = 0.f, d3 = 0.f;
; #pragma unroll
;       for (int i = 0; i < 8; ++i) { d0 += dv[4 * i] * hx[4 * i]; d1 += dv[4 * i + 1] * hx[4 * i + 1]; d2 += dv[4 * i + 2] * hx[4 * i + 2]; d3 += dv[4 * i + 3] * hx[4 * i + 3]; }
;       const float d = wave_sum_fast((d0 + d1) + (d2 + d3)) * (1.f / DOWN_SCALE);
;       const float gk = __builtin_bit_cast(float, (k < 64) ? __builtin_amdgcn_readlane(g0, k) : __builtin_amdgcn_readlane(g1, k - 64));
;       const float act = gelu_exact(d) * gk * (1.f / UP_SCALE);
;       const v6u uq = v6u{up[s][0][0], up[s][0][1], up[s][1][0], up[s][1][1], up[s][2][0], up[s][2][1]};
;       const v32f uv = __builtin_amdgcn_cvt_scalef32_pk32_f32_fp6(uq, 1.0f);
; #pragma unroll
;       for (int i = 0; i < 32; ++i) acc[i] += act * uv[i];
.Ljn_27:
	v_bfi_b32 v209, s18, v210, v205
	v_mul_f32_e32 v208, 0.5, v204
	v_add_f32_e32 v209, 1.0, v209
	v_mul_f32_e32 v208, v208, v209
	v_mul_f32_e32 v208, s26, v208
	v_mul_f32_e32 v206, 0x3e800000, v208
	v_pk_fma_f32 v[66:67], v[2:3], v[206:207], v[66:67] op_sel_hi:[1,0,1]
	v_pk_fma_f32 v[68:69], v[4:5], v[206:207], v[68:69] op_sel_hi:[1,0,1]
	v_pk_fma_f32 v[70:71], v[6:7], v[206:207], v[70:71] op_sel_hi:[1,0,1]
	v_pk_fma_f32 v[72:73], v[8:9], v[206:207], v[72:73] op_sel_hi:[1,0,1]
	v_pk_fma_f32 v[74:75], v[10:11], v[206:207], v[74:75] op_sel_hi:[1,0,1]
	v_pk_fma_f32 v[76:77], v[12:13], v[206:207], v[76:77] op_sel_hi:[1,0,1]
	v_pk_fma_f32 v[78:79], v[14:15], v[206:207], v[78:79] op_sel_hi:[1,0,1]
	v_pk_fma_f32 v[80:81], v[16:17], v[206:207], v[80:81] op_sel_hi:[1,0,1]
	v_pk_fma_f32 v[82:83], v[18:19], v[206:207], v[82:83] op_sel_hi:[1,0,1]
	v_pk_fma_f32 v[84:85], v[20:21], v[206:207], v[84:85] op_sel_hi:[1,0,1]
	v_pk_fma_f32 v[86:87], v[22:23], v[206:207], v[86:87] op_sel_hi:[1,0,1]
	v_pk_fma_f32 v[88:89], v[24:25], v[206:207], v[88:89] op_sel_hi:[1,0,1]
	v_pk_fma_f32 v[90:91], v[26:27], v[206:207], v[90:91] op_sel_hi:[1,0,1]
	v_pk_fma_f32 v[92:93], v[28:29], v[206:207], v[92:93] op_sel_hi:[1,0,1]
	v_pk_fma_f32 v[94:95], v[30:31], v[206:207], v[94:95] op_sel_hi:[1,0,1]
	v_pk_fma_f32 v[96:97], v[32:33], v[206:207], v[96:97] op_sel_hi:[1,0,1]
	s_mul_i32 s40, s25, 0xc00
	s_add_u32 s28, s62, s40
	s_addc_u32 s29, s63, 0
	global_load_dwordx4 v[158:161], v1, s[28:29]
	global_load_dwordx4 v[162:165], v1, s[28:29] offset:2048
	global_load_dwordx4 v[166:169], v1, s[28:29] offset:1024
	s_waitcnt vmcnt(33)
	v_cvt_scalef32_pk32_f32_fp6 v[2:33], v[170:175], 1.0
	v_mul_f32_e32 v200, v2, v34
	v_mul_f32_e32 v201, v3, v35
	v_mul_f32_e32 v202, v4, v36
	v_mul_f32_e32 v203, v5, v37
	v_fmac_f32_e32 v200, v6, v38
	v_fmac_f32_e32 v201, v7, v39
	v_fmac_f32_e32 v202, v8, v40
	v_fmac_f32_e32 v203, v9, v41
	v_fmac_f32_e32 v200, v10, v42
	v_fmac_f32_e32 v201, v11, v43
	v_fmac_f32_e32 v202, v12, v44
	v_fmac_f32_e32 v203, v13, v45
	v_fmac_f32_e32 v200, v14, v46
	v_fmac_f32_e32 v201, v15, v47
	v_fmac_f32_e32 v202, v16, v48
	v_fmac_f32_e32 v203, v17, v49
	v_fmac_f32_e32 v200, v18, v50
	v_fmac_f32_e32 v201, v19, v51
	v_fmac_f32_e32 v202, v20, v52
	v_fmac_f32_e32 v203, v21, v53
	v_fmac_f32_e32 v200, v22, v54
	v_fmac_f32_e32 v201, v23, v55
	v_fmac_f32_e32 v202, v24, v56
	v_fmac_f32_e32 v203, v25, v57
	v_fmac_f32_e32 v200, v26, v58
	v_fmac_f32_e32 v201, v27, v59
	v_fmac_f32_e32 v202, v28, v60
	v_fmac_f32_e32 v203, v29, v61
	v_fmac_f32_e32 v200, v30, v62
	v_fmac_f32_e32 v201, v31, v63
	v_fmac_f32_e32 v202, v32, v64
	v_fmac_f32_e32 v203, v33, v65
	v_add_f32_e32 v200, v201, v200
	v_add_f32_e32 v202, v203, v202
	v_cvt_scalef32_pk32_f32_fp6 v[2:33], v[176:181], 1.0
	v_add_f32_e32 v200, v202, v200
	s_add_i32 s38, s24, 6
	v_readlane_b32 s26, v199, s38
	s_add_i32 s39, s23, 6
	v_readlane_b32 s25, v198, s39
	v_add_f32_dpp v200, v200, v200 quad_perm:[1,0,3,2] row_mask:0xf bank_mask:0xf bound_ctrl:1
	s_nop 1
	v_add_f32_dpp v200, v200, v200 quad_perm:[2,3,0,1] row_mask:0xf bank_mask:0xf bound_ctrl:1
	s_nop 1
	v_add_f32_dpp v200, v200, v200 row_half_mirror row_mask:0xf bank_mask:0xf bound_ctrl:1
	s_nop 1
	v_add_f32_dpp v200, v200, v200 row_mirror row_mask:0xf bank_mask:0xf bound_ctrl:1
	s_nop 1
	v_add_f32_dpp v200, v200, v200 row_bcast:15 row_mask:0xa bank_mask:0xf
	s_nop 1
	v_add_f32_dpp v200, v200, v200 row_bcast:31 row_mask:0xc bank_mask:0xf
	s_nop 0
	v_readlane_b32 s27, v200, 63
	v_mul_f32_e32 v204, s27, v212
	v_mul_f32_e32 v205, 0x3f3504f3, v204
	v_cmp_lt_f32_e64 s[32:33], |v205|, 1.0
	s_and_b64 vcc, exec, s[32:33]
	s_cbranch_vccnz .Lsm_29
	v_fma_f32 v208, |v205|, s9, v214
	v_fma_f32 v208, |v205|, v208, s10
	v_fma_f32 v208, |v205|, v208, s11
	v_fma_f32 v208, |v205|, v208, s12
	v_fma_f32 v208, |v205|, v208, s13
	v_fma_f32 v208, |v205|, v208, s14
	v_fma_f32 v208, |v205|, v208, |v205|
	v_mul_f32_e32 v209, 0xbfb8aa3b, v208
	v_fma_f32 v210, v208, s15, -v209
	v_rndne_f32_e32 v211, v209
	v_fmac_f32_e32 v210, 0xb2a5705f, v208
	v_sub_f32_e32 v209, v209, v211
	v_add_f32_e32 v209, v209, v210
	v_cvt_i32_f32_e32 v210, v211
	v_exp_f32_e32 v209, v209
	v_cmp_nlt_f32_e32 vcc, s16, v208
	v_ldexp_f32 v209, v209, v210
	s_nop 0
	v_cndmask_b32_e32 v209, 0, v209, vcc
	v_cmp_ngt_f32_e32 vcc, s17, v208
	s_nop 1
	v_cndmask_b32_e32 v208, v215, v209, vcc
	v_sub_f32_e32 v210, 1.0, v208
	s_branch .Ljn_29

; DEV float gelu_exact(float v) { return 0.5f * v * (1.f + erff(v * 0.7071067811865476f)); }
; DEV void peer_gather_token(const Params& p, int tok) {
;     ...
;     for (int s = 0; s < 4; ++s) {
;       const int k = k4 + s;
;       if (k + 3 < 128) issue(k + 3, (s + 3) & 3);
;       const v6u dq = v6u{dn[s][0][0], dn[s][0][1], dn[s][1][0], dn[s][1][1], dn[s][2][0], dn[s][2][1]};
;       const v32f dv = __builtin_amdgcn_cvt_scalef32_pk32_f32_fp6(dq, 1.0f);
;       float d0 = 0.f, d1 = 0.f, d2 = 0.f, d3 = 0.f;
; #pragma unroll
;       for (int i = 0; i < 8; ++i) { d0 += dv[4 * i] * hx[4 * i]; d1 += dv[4 * i + 1] * hx[4 * i + 1]; d2 += dv[4 * i + 2] * hx[4 * i + 2]; d3 += dv[4 * i + 3] * hx[4 * i + 3]; }
;       const float d = wave_sum_fast((d0 + d1) + (d2 + d3)) * (1.f / DOWN_SCALE);
;       const float gk = __builtin_bit_cast(float, (k < 64) ? __builtin_amdgcn_readlane(g0, k) : __builtin_amdgcn_readlane(g1, k - 64));
;       const float act = gelu_exact(d) * gk * (1.f / UP_SCALE);
;       const v6u uq = v6u{up[s][0][0], up[s][0][1], up[s][1][0], up[s][1][1], up[s][2][0], up[s][2][1]};
;       const v32f uv = __builtin_amdgcn_cvt_scalef32_pk32_f32_fp6(uq, 1.0f);
; #pragma unroll
;       for (int i = 0; i < 32; ++i) acc[i] += act * uv[i];
.Ljn_29:
	v_bfi_b32 v209, s18, v210, v205
	v_mul_f32_e32 v208, 0.5, v204
	v_add_f32_e32 v209, 1.0, v209
	v_mul_f32_e32 v208, v208, v209
	v_mul_f32_e32 v208, s26, v208
	v_mul_f32_e32 v206, 0x3e800000, v208
	v_pk_fma_f32 v[66:67], v[2:3], v[206:207], v[66:67] op_sel_hi:[1,0,1]
	v_pk_fma_f32 v[68:69], v[4:5], v[206:207], v[68:69] op_sel_hi:[1,0,1]
	v_pk_fma_f32 v[70:71], v[6:7], v[206:207], v[70:71] op_sel_hi:[1,0,1]
	v_pk_fma_f32 v[72:73], v[8:9], v[206:207], v[72:73] op_sel_hi:[1,0,1]
	v_pk_fma_f32 v[74:75], v[10:11], v[206:207], v[74:75] op_sel_hi:[1,0,1]
	v_pk_fma_f32 v[76:77], v[12:13], v[206:207], v[76:77] op_sel_hi:[1,0,1]
	v_pk_fma_f32 v[78:79], v[14:15], v[206:207], v[78:79] op_sel_hi:[1,0,1]
	v_pk_fma_f32 v[80:81], v[16:17], v[206:207], v[80:81] op_sel_hi:[1,0,1]
	v_pk_fma_f32 v[82:83], v[18:19], v[206:207], v[82:83] op_sel_hi:[1,0,1]
	v_pk_fma_f32 v[84:85], v[20:21], v[206:207], v[84:85] op_sel_hi:[1,0,1]
	v_pk_fma_f32 v[86:87], v[22:23], v[206:207], v[86:87] op_sel_hi:[1,0,1]
	v_pk_fma_f32 v[88:89], v[24:25], v[206:207], v[88:89] op_sel_hi:[1,0,1]
	v_pk_fma_f32 v[90:91], v[26:27], v[206:207], v[90:91] op_sel_hi:[1,0,1]
	v_pk_fma_f32 v[92:93], v[28:29], v[206:207], v[92:93] op_sel_hi:[1,0,1]
	v_pk_fma_f32 v[94:95], v[30:31], v[206:207], v[94:95] op_sel_hi:[1,0,1]
	v_pk_fma_f32 v[96:97], v[32:33], v[206:207], v[96:97] op_sel_hi:[1,0,1]
	s_mul_i32 s40, s25, 0xc00
	s_add_u32 s28, s62, s40
	s_addc_u32 s29, s63, 0
	global_load_dwordx4 v[170:173], v1, s[28:29]
	global_load_dwordx4 v[174:177], v1, s[28:29] offset:2048
	global_load_dwordx4 v[178:181], v1, s[28:29] offset:1024
	s_waitcnt vmcnt(33)
	v_cvt_scalef32_pk32_f32_fp6 v[2:33], v[182:187], 1.0
	v_mul_f32_e32 v200, v2, v34
	v_mul_f32_e32 v201, v3, v35
	v_mul_f32_e32 v202, v4, v36
	v_mul_f32_e32 v203, v5, v37
	v_fmac_f32_e32 v200, v6, v38
	v_fmac_f32_e32 v201, v7, v39
	v_fmac_f32_e32 v202, v8, v40
	v_fmac_f32_e32 v203, v9, v41
	v_fmac_f32_e32 v200, v10, v42
	v_fmac_f32_e32 v201, v11, v43
	v_fmac_f32_e32 v202, v12, v44
	v_fmac_f32_e32 v203, v13, v45
	v_fmac_f32_e32 v200, v14, v46
	v_fmac_f32_e32 v201, v15, v47
	v_fmac_f32_e32 v202, v16, v48
	v_fmac_f32_e32 v203, v17, v49
	v_fmac_f32_e32 v200, v18, v50
	v_fmac_f32_e32 v201, v19, v51
	v_fmac_f32_e32 v202, v20, v52
	v_fmac_f32_e32 v203, v21, v53
	v_fmac_f32_e32 v200, v22, v54
	v_fmac_f32_e32 v201, v23, v55
	v_fmac_f32_e32 v202, v24, v56
	v_fmac_f32_e32 v203, v25, v57
	v_fmac_f32_e32 v200, v26, v58
	v_fmac_f32_e32 v201, v27, v59
	v_fmac_f32_e32 v202, v28, v60
	v_fmac_f32_e32 v203, v29, v61
	v_fmac_f32_e32 v200, v30, v62
	v_fmac_f32_e32 v201, v31, v63
	v_fmac_f32_e32 v202, v32, v64
	v_fmac_f32_e32 v203, v33, v65
	v_add_f32_e32 v200, v201, v200
	v_add_f32_e32 v202, v203, v202
	v_cvt_scalef32_pk32_f32_fp6 v[2:33], v[188:193], 1.0
	v_add_f32_e32 v200, v202, v200
	s_add_i32 s38, s24, 7
	v_readlane_b32 s26, v199, s38
	s_add_i32 s39, s23, 7
	v_readlane_b32 s25, v198, s39
	v_add_f32_dpp v200, v200, v200 quad_perm:[1,0,3,2] row_mask:0xf bank_mask:0xf bound_ctrl:1
	s_nop 1
	v_add_f32_dpp v200, v200, v200 quad_perm:[2,3,0,1] row_mask:0xf bank_mask:0xf bound_ctrl:1
	s_nop 1
	v_add_f32_dpp v200, v200, v200 row_half_mirror row_mask:0xf bank_mask:0xf bound_ctrl:1
	s_nop 1
	v_add_f32_dpp v200, v200, v200 row_mirror row_mask:0xf bank_mask:0xf bound_ctrl:1
	s_nop 1
	v_add_f32_dpp v200, v200, v200 row_bcast:15 row_mask:0xa bank_mask:0xf
	s_nop 1
	v_add_f32_dpp v200, v200, v200 row_bcast:31 row_mask:0xc bank_mask:0xf
	s_nop 0
	v_readlane_b32 s27, v200, 63
	v_mul_f32_e32 v204, s27, v212
	v_mul_f32_e32 v205, 0x3f3504f3, v204
	v_cmp_lt_f32_e64 s[32:33], |v205|, 1.0
	s_and_b64 vcc, exec, s[32:33]
	s_cbranch_vccnz .Lsm_31
	v_fma_f32 v208, |v205|, s9, v214
	v_fma_f32 v208, |v205|, v208, s10
	v_fma_f32 v208, |v205|, v208, s11
	v_fma_f32 v208, |v205|, v208, s12
	v_fma_f32 v208, |v205|, v208, s13
	v_fma_f32 v208, |v205|, v208, s14
	v_fma_f32 v208, |v205|, v208, |v205|
	v_mul_f32_e32 v209, 0xbfb8aa3b, v208
	v_fma_f32 v210, v208, s15, -v209
	v_rndne_f32_e32 v211, v209
	v_fmac_f32_e32 v210, 0xb2a5705f, v208
	v_sub_f32_e32 v209, v209, v211
	v_add_f32_e32 v209, v209, v210
	v_cvt_i32_f32_e32 v210, v211
	v_exp_f32_e32 v209, v209
	v_cmp_nlt_f32_e32 vcc, s16, v208
	v_ldexp_f32 v209, v209, v210
	s_nop 0
	v_cndmask_b32_e32 v209, 0, v209, vcc
	v_cmp_ngt_f32_e32 vcc, s17, v208
	s_nop 1
	v_cndmask_b32_e32 v208, v215, v209, vcc
	v_sub_f32_e32 v210, 1.0, v208
	s_branch .Ljn_31

; DEV float gelu_exact(float v) { return 0.5f * v * (1.f + erff(v * 0.7071067811865476f)); }
; DEV void peer_gather_token(const Params& p, int tok) {
;     ...
;   const int e0 = p.eidx[(size_t)tok * 128 + lane], e1 = p.eidx[(size_t)tok * 128 + 64 + lane];
;   const int g0 = __builtin_bit_cast(int, p.gw[(size_t)tok * 128 + lane]), g1 = __builtin_bit_cast(int, p.gw[(size_t)tok * 128 + 64 + lane]);
;   u32x2 dn[4][3], up[4][3];
;   auto issue = [&](int k, int slot) {
;     const int e = (k < 64) ? __builtin_amdgcn_readlane(e0, k) : __builtin_amdgcn_readlane(e1, k - 64);
;     const unsigned char* dr = p.down8 + (size_t)e * ROW6 + lane * 24;
;     const unsigned char* ur = p.up8 + (size_t)e * ROW6 + lane * 24;
; #pragma unroll
;     for (int i = 0; i < 3; ++i) { dn[slot][i] = *(const u32x2*)(dr + i * 8); up[slot][i] = *(const u32x2*)(ur + i * 8); }
;   };
;     ...
;       if (k + 3 < 128) issue(k + 3, (s + 3) & 3);
;       const v6u dq = v6u{dn[s][0][0], dn[s][0][1], dn[s][1][0], dn[s][1][1], dn[s][2][0], dn[s][2][1]};
;       const v32f dv = __builtin_amdgcn_cvt_scalef32_pk32_f32_fp6(dq, 1.0f);
;       float d0 = 0.f, d1 = 0.f, d2 = 0.f, d3 = 0.f;
; #pragma unroll
;       for (int i = 0; i < 8; ++i) { d0 += dv[4 * i] * hx[4 * i]; d1 += dv[4 * i + 1] * hx[4 * i + 1]; d2 += dv[4 * i + 2] * hx[4 * i + 2]; d3 += dv[4 * i + 3] * hx[4 * i + 3]; }
;       const float d = wave_sum_fast((d0 + d1) + (d2 + d3)) * (1.f / DOWN_SCALE);
;       const float gk = __builtin_bit_cast(float, (k < 64) ? __builtin_amdgcn_readlane(g0, k) : __builtin_amdgcn_readlane(g1, k - 64));
;       const float act = gelu_exact(d) * gk * (1.f / UP_SCALE);
;       const v6u uq = v6u{up[s][0][0], up[s][0][1], up[s][1][0], up[s][1][1], up[s][2][0], up[s][2][1]};
;       const v32f uv = __builtin_amdgcn_cvt_scalef32_pk32_f32_fp6(uq, 1.0f);
; #pragma unroll
;       for (int i = 0; i < 32; ++i) acc[i] += act * uv[i];
.Ljn_31:
	v_bfi_b32 v209, s18, v210, v205
	v_mul_f32_e32 v208, 0.5, v204
	v_add_f32_e32 v209, 1.0, v209
	v_mul_f32_e32 v208, v208, v209
	v_mul_f32_e32 v208, s26, v208
	v_mul_f32_e32 v206, 0x3e800000, v208
	v_pk_fma_f32 v[66:67], v[2:3], v[206:207], v[66:67] op_sel_hi:[1,0,1]
	v_pk_fma_f32 v[68:69], v[4:5], v[206:207], v[68:69] op_sel_hi:[1,0,1]
	v_pk_fma_f32 v[70:71], v[6:7], v[206:207], v[70:71] op_sel_hi:[1,0,1]
	v_pk_fma_f32 v[72:73], v[8:9], v[206:207], v[72:73] op_sel_hi:[1,0,1]
	v_pk_fma_f32 v[74:75], v[10:11], v[206:207], v[74:75] op_sel_hi:[1,0,1]
	v_pk_fma_f32 v[76:77], v[12:13], v[206:207], v[76:77] op_sel_hi:[1,0,1]
	v_pk_fma_f32 v[78:79], v[14:15], v[206:207], v[78:79] op_sel_hi:[1,0,1]
	v_pk_fma_f32 v[80:81], v[16:17], v[206:207], v[80:81] op_sel_hi:[1,0,1]
	v_pk_fma_f32 v[82:83], v[18:19], v[206:207], v[82:83] op_sel_hi:[1,0,1]
	v_pk_fma_f32 v[84:85], v[20:21], v[206:207], v[84:85] op_sel_hi:[1,0,1]
	v_pk_fma_f32 v[86:87], v[22:23], v[206:207], v[86:87] op_sel_hi:[1,0,1]
	v_pk_fma_f32 v[88:89], v[24:25], v[206:207], v[88:89] op_sel_hi:[1,0,1]
	v_pk_fma_f32 v[90:91], v[26:27], v[206:207], v[90:91] op_sel_hi:[1,0,1]
	v_pk_fma_f32 v[92:93], v[28:29], v[206:207], v[92:93] op_sel_hi:[1,0,1]
	v_pk_fma_f32 v[94:95], v[30:31], v[206:207], v[94:95] op_sel_hi:[1,0,1]
	v_pk_fma_f32 v[96:97], v[32:33], v[206:207], v[96:97] op_sel_hi:[1,0,1]
	s_mul_i32 s40, s25, 0xc00
	s_add_u32 s28, s62, s40
	s_addc_u32 s29, s63, 0
	global_load_dwordx4 v[182:185], v1, s[28:29]
	global_load_dwordx4 v[186:189], v1, s[28:29] offset:2048
	global_load_dwordx4 v[190:193], v1, s[28:29] offset:1024
	s_add_i32 s24, s24, 8
	s_and_b32 s24, s24, 63
	s_waitcnt vmcnt(21)
	v_and_b32_e32 v236, 63, v0
	v_lshrrev_b32_e32 v241, 6, v0
	v_lshl_or_b32 v237, v216, 7, v236
	v_or_b32_e32 v238, 64, v236
	v_lshl_or_b32 v238, v217, 7, v238
	v_mov_b32_e32 v239, 0
	v_mov_b32_e32 v240, 0
	v_lshlrev_b32_e32 v241, 10, v241
	v_lshl_add_u32 v241, v236, 2, v241
	v_readlane_b32 s46, v237, 0
	v_readlane_b32 s47, v238, 0
	s_nop 1
	v_cmp_lt_u32_e64 s[48:49], s46, v237
	v_cmp_lt_u32_e64 s[50:51], s46, v238
	v_cmp_lt_u32_e64 s[52:53], s47, v237
	v_cmp_lt_u32_e64 s[54:55], s47, v238
	v_readlane_b32 s46, v237, 1
	v_readlane_b32 s47, v238, 1
	v_addc_co_u32_e64 v239, s[56:57], 0, v239, s[48:49]
	v_addc_co_u32_e64 v240, s[56:57], 0, v240, s[50:51]
	v_addc_co_u32_e64 v239, s[56:57], 0, v239, s[52:53]
	v_addc_co_u32_e64 v240, s[56:57], 0, v240, s[54:55]
	v_cmp_lt_u32_e64 s[48:49], s46, v237
	v_cmp_lt_u32_e64 s[50:51], s46, v238
	v_cmp_lt_u32_e64 s[52:53], s47, v237
	v_cmp_lt_u32_e64 s[54:55], s47, v238
	v_readlane_b32 s46, v237, 2
	v_readlane_b32 s47, v238, 2
	v_addc_co_u32_e64 v239, s[56:57], 0, v239, s[48:49]
	v_addc_co_u32_e64 v240, s[56:57], 0, v240, s[50:51]
	v_addc_co_u32_e64 v239, s[56:57], 0, v239, s[52:53]
	v_addc_co_u32_e64 v240, s[56:57], 0, v240, s[54:55]
	v_cmp_lt_u32_e64 s[48:49], s46, v237
	v_cmp_lt_u32_e64 s[50:51], s46, v238
	v_cmp_lt_u32_e64 s[52:53], s47, v237
	v_cmp_lt_u32_e64 s[54:55], s47, v238
	v_readlane_b32 s46, v237, 3
	v_readlane_b32 s47, v238, 3
	v_addc_co_u32_e64 v239, s[56:57], 0, v239, s[48:49]
	v_addc_co_u32_e64 v240, s[56:57], 0, v240, s[50:51]
	v_addc_co_u32_e64 v239, s[56:57], 0, v239, s[52:53]
	v_addc_co_u32_e64 v240, s[56:57], 0, v240, s[54:55]
	v_cmp_lt_u32_e64 s[48:49], s46, v237
	v_cmp_lt_u32_e64 s[50:51], s46, v238
	v_cmp_lt_u32_e64 s[52:53], s47, v237
	v_cmp_lt_u32_e64 s[54:55], s47, v238
	v_readlane_b32 s46, v237, 4
	v_readlane_b32 s47, v238, 4
	v_addc_co_u32_e64 v239, s[56:57], 0, v239, s[48:49]
	v_addc_co_u32_e64 v240, s[56:57], 0, v240, s[50:51]
	v_addc_co_u32_e64 v239, s[56:57], 0, v239, s[52:53]
	v_addc_co_u32_e64 v240, s[56:57], 0, v240, s[54:55]
	v_cmp_lt_u32_e64 s[48:49], s46, v237
	v_cmp_lt_u32_e64 s[50:51], s46, v238
	v_cmp_lt_u32_e64 s[52:53], s47, v237
	v_cmp_lt_u32_e64 s[54:55], s47, v238
	v_readlane_b32 s46, v237, 5
	v_readlane_b32 s47, v238, 5
	v_addc_co_u32_e64 v239, s[56:57], 0, v239, s[48:49]
	v_addc_co_u32_e64 v240, s[56:57], 0, v240, s[50:51]
	v_addc_co_u32_e64 v239, s[56:57], 0, v239, s[52:53]
	v_addc_co_u32_e64 v240, s[56:57], 0, v240, s[54:55]
	v_cmp_lt_u32_e64 s[48:49], s46, v237
	v_cmp_lt_u32_e64 s[50:51], s46, v238
	v_cmp_lt_u32_e64 s[52:53], s47, v237
	v_cmp_lt_u32_e64 s[54:55], s47, v238
	v_readlane_b32 s46, v237, 6
	v_readlane_b32 s47, v238, 6
	v_addc_co_u32_e64 v239, s[56:57], 0, v239, s[48:49]
	v_addc_co_u32_e64 v240, s[56:57], 0, v240, s[50:51]
	v_addc_co_u32_e64 v239, s[56:57], 0, v239, s[52:53]
	v_addc_co_u32_e64 v240, s[56:57], 0, v240, s[54:55]
	v_cmp_lt_u32_e64 s[48:49], s46, v237
	v_cmp_lt_u32_e64 s[50:51], s46, v238
	v_cmp_lt_u32_e64 s[52:53], s47, v237
	v_cmp_lt_u32_e64 s[54:55], s47, v238
	v_readlane_b32 s46, v237, 7
	v_readlane_b32 s47, v238, 7
	v_addc_co_u32_e64 v239, s[56:57], 0, v239, s[48:49]
	v_addc_co_u32_e64 v240, s[56:57], 0, v240, s[50:51]
	v_addc_co_u32_e64 v239, s[56:57], 0, v239, s[52:53]
	v_addc_co_u32_e64 v240, s[56:57], 0, v240, s[54:55]
	v_cmp_lt_u32_e64 s[48:49], s46, v237
	v_cmp_lt_u32_e64 s[50:51], s46, v238
	v_cmp_lt_u32_e64 s[52:53], s47, v237
	v_cmp_lt_u32_e64 s[54:55], s47, v238
	v_readlane_b32 s46, v237, 8
	v_readlane_b32 s47, v238, 8
	v_addc_co_u32_e64 v239, s[56:57], 0, v239, s[48:49]
	v_addc_co_u32_e64 v240, s[56:57], 0, v240, s[50:51]
	v_addc_co_u32_e64 v239, s[56:57], 0, v239, s[52:53]
	v_addc_co_u32_e64 v240, s[56:57], 0, v240, s[54:55]
	v_cmp_lt_u32_e64 s[48:49], s46, v237
	v_cmp_lt_u32_e64 s[50:51], s46, v238
	v_cmp_lt_u32_e64 s[52:53], s47, v237
	v_cmp_lt_u32_e64 s[54:55], s47, v238
	v_readlane_b32 s46, v237, 9
	v_readlane_b32 s47, v238, 9
	v_addc_co_u32_e64 v239, s[56:57], 0, v239, s[48:49]
; DEV void peer_gather_token(const Params& p, int tok) {
;     ...
;   const int e0 = p.eidx[(size_t)tok * 128 + lane], e1 = p.eidx[(size_t)tok * 128 + 64 + lane];
;   const int g0 = __builtin_bit_cast(int, p.gw[(size_t)tok * 128 + lane]), g1 = __builtin_bit_cast(int, p.gw[(size_t)tok * 128 + 64 + lane]);
;   u32x2 dn[4][3], up[4][3];
;   auto issue = [&](int k, int slot) {
;     const int e = (k < 64) ? __builtin_amdgcn_readlane(e0, k) : __builtin_amdgcn_readlane(e1, k - 64);
;     const unsigned char* dr = p.down8 + (size_t)e * ROW6 + lane * 24;
;     const unsigned char* ur = p.up8 + (size_t)e * ROW6 + lane * 24;
; #pragma unroll
;     for (int i = 0; i < 3; ++i) { dn[slot][i] = *(const u32x2*)(dr + i * 8); up[slot][i] = *(const u32x2*)(ur + i * 8); }
;   };
	v_addc_co_u32_e64 v240, s[56:57], 0, v240, s[50:51]
	v_addc_co_u32_e64 v239, s[56:57], 0, v239, s[52:53]
	v_addc_co_u32_e64 v240, s[56:57], 0, v240, s[54:55]
	v_cmp_lt_u32_e64 s[48:49], s46, v237
	v_cmp_lt_u32_e64 s[50:51], s46, v238
	v_cmp_lt_u32_e64 s[52:53], s47, v237
	v_cmp_lt_u32_e64 s[54:55], s47, v238
	v_readlane_b32 s46, v237, 10
	v_readlane_b32 s47, v238, 10
	v_addc_co_u32_e64 v239, s[56:57], 0, v239, s[48:49]
	v_addc_co_u32_e64 v240, s[56:57], 0, v240, s[50:51]
	v_addc_co_u32_e64 v239, s[56:57], 0, v239, s[52:53]
	v_addc_co_u32_e64 v240, s[56:57], 0, v240, s[54:55]
	v_cmp_lt_u32_e64 s[48:49], s46, v237
	v_cmp_lt_u32_e64 s[50:51], s46, v238
	v_cmp_lt_u32_e64 s[52:53], s47, v237
	v_cmp_lt_u32_e64 s[54:55], s47, v238
	v_readlane_b32 s46, v237, 11
	v_readlane_b32 s47, v238, 11
	v_addc_co_u32_e64 v239, s[56:57], 0, v239, s[48:49]
	v_addc_co_u32_e64 v240, s[56:57], 0, v240, s[50:51]
	v_addc_co_u32_e64 v239, s[56:57], 0, v239, s[52:53]
	v_addc_co_u32_e64 v240, s[56:57], 0, v240, s[54:55]
	v_cmp_lt_u32_e64 s[48:49], s46, v237
	v_cmp_lt_u32_e64 s[50:51], s46, v238
	v_cmp_lt_u32_e64 s[52:53], s47, v237
	v_cmp_lt_u32_e64 s[54:55], s47, v238
	v_readlane_b32 s46, v237, 12
	v_readlane_b32 s47, v238, 12
	v_addc_co_u32_e64 v239, s[56:57], 0, v239, s[48:49]
	v_addc_co_u32_e64 v240, s[56:57], 0, v240, s[50:51]
	v_addc_co_u32_e64 v239, s[56:57], 0, v239, s[52:53]
	v_addc_co_u32_e64 v240, s[56:57], 0, v240, s[54:55]
	v_cmp_lt_u32_e64 s[48:49], s46, v237
	v_cmp_lt_u32_e64 s[50:51], s46, v238
	v_cmp_lt_u32_e64 s[52:53], s47, v237
	v_cmp_lt_u32_e64 s[54:55], s47, v238
	v_readlane_b32 s46, v237, 13
	v_readlane_b32 s47, v238, 13
	v_addc_co_u32_e64 v239, s[56:57], 0, v239, s[48:49]
	v_addc_co_u32_e64 v240, s[56:57], 0, v240, s[50:51]
	v_addc_co_u32_e64 v239, s[56:57], 0, v239, s[52:53]
	v_addc_co_u32_e64 v240, s[56:57], 0, v240, s[54:55]
	v_cmp_lt_u32_e64 s[48:49], s46, v237
	v_cmp_lt_u32_e64 s[50:51], s46, v238
	v_cmp_lt_u32_e64 s[52:53], s47, v237
	v_cmp_lt_u32_e64 s[54:55], s47, v238
	v_readlane_b32 s46, v237, 14
	v_readlane_b32 s47, v238, 14
	v_addc_co_u32_e64 v239, s[56:57], 0, v239, s[48:49]
	v_addc_co_u32_e64 v240, s[56:57], 0, v240, s[50:51]
	v_addc_co_u32_e64 v239, s[56:57], 0, v239, s[52:53]
	v_addc_co_u32_e64 v240, s[56:57], 0, v240, s[54:55]
	v_cmp_lt_u32_e64 s[48:49], s46, v237
	v_cmp_lt_u32_e64 s[50:51], s46, v238
	v_cmp_lt_u32_e64 s[52:53], s47, v237
	v_cmp_lt_u32_e64 s[54:55], s47, v238
	v_readlane_b32 s46, v237, 15
	v_readlane_b32 s47, v238, 15
	v_addc_co_u32_e64 v239, s[56:57], 0, v239, s[48:49]
	v_addc_co_u32_e64 v240, s[56:57], 0, v240, s[50:51]
	v_addc_co_u32_e64 v239, s[56:57], 0, v239, s[52:53]
	v_addc_co_u32_e64 v240, s[56:57], 0, v240, s[54:55]
	v_cmp_lt_u32_e64 s[48:49], s46, v237
	v_cmp_lt_u32_e64 s[50:51], s46, v238
	v_cmp_lt_u32_e64 s[52:53], s47, v237
	v_cmp_lt_u32_e64 s[54:55], s47, v238
	v_readlane_b32 s46, v237, 16
	v_readlane_b32 s47, v238, 16
	v_addc_co_u32_e64 v239, s[56:57], 0, v239, s[48:49]
	v_addc_co_u32_e64 v240, s[56:57], 0, v240, s[50:51]
	v_addc_co_u32_e64 v239, s[56:57], 0, v239, s[52:53]
	v_addc_co_u32_e64 v240, s[56:57], 0, v240, s[54:55]
	v_cmp_lt_u32_e64 s[48:49], s46, v237
	v_cmp_lt_u32_e64 s[50:51], s46, v238
	v_cmp_lt_u32_e64 s[52:53], s47, v237
	v_cmp_lt_u32_e64 s[54:55], s47, v238
	v_readlane_b32 s46, v237, 17
	v_readlane_b32 s47, v238, 17
	v_addc_co_u32_e64 v239, s[56:57], 0, v239, s[48:49]
	v_addc_co_u32_e64 v240, s[56:57], 0, v240, s[50:51]
	v_addc_co_u32_e64 v239, s[56:57], 0, v239, s[52:53]
	v_addc_co_u32_e64 v240, s[56:57], 0, v240, s[54:55]
	v_cmp_lt_u32_e64 s[48:49], s46, v237
	v_cmp_lt_u32_e64 s[50:51], s46, v238
	v_cmp_lt_u32_e64 s[52:53], s47, v237
	v_cmp_lt_u32_e64 s[54:55], s47, v238
	v_readlane_b32 s46, v237, 18
	v_readlane_b32 s47, v238, 18
	v_addc_co_u32_e64 v239, s[56:57], 0, v239, s[48:49]
	v_addc_co_u32_e64 v240, s[56:57], 0, v240, s[50:51]
	v_addc_co_u32_e64 v239, s[56:57], 0, v239, s[52:53]
	v_addc_co_u32_e64 v240, s[56:57], 0, v240, s[54:55]
	v_cmp_lt_u32_e64 s[48:49], s46, v237
	v_cmp_lt_u32_e64 s[50:51], s46, v238
	v_cmp_lt_u32_e64 s[52:53], s47, v237
	v_cmp_lt_u32_e64 s[54:55], s47, v238
	v_readlane_b32 s46, v237, 19
	v_readlane_b32 s47, v238, 19
	v_addc_co_u32_e64 v239, s[56:57], 0, v239, s[48:49]
	v_addc_co_u32_e64 v240, s[56:57], 0, v240, s[50:51]
	v_addc_co_u32_e64 v239, s[56:57], 0, v239, s[52:53]
	v_addc_co_u32_e64 v240, s[56:57], 0, v240, s[54:55]
	v_cmp_lt_u32_e64 s[48:49], s46, v237
	v_cmp_lt_u32_e64 s[50:51], s46, v238
	v_cmp_lt_u32_e64 s[52:53], s47, v237
	v_cmp_lt_u32_e64 s[54:55], s47, v238
	v_readlane_b32 s46, v237, 20
	v_readlane_b32 s47, v238, 20
	v_addc_co_u32_e64 v239, s[56:57], 0, v239, s[48:49]
	v_addc_co_u32_e64 v240, s[56:57], 0, v240, s[50:51]
	v_addc_co_u32_e64 v239, s[56:57], 0, v239, s[52:53]
	v_addc_co_u32_e64 v240, s[56:57], 0, v240, s[54:55]
	v_cmp_lt_u32_e64 s[48:49], s46, v237
	v_cmp_lt_u32_e64 s[50:51], s46, v238
	v_cmp_lt_u32_e64 s[52:53], s47, v237
	v_cmp_lt_u32_e64 s[54:55], s47, v238
	v_readlane_b32 s46, v237, 21
	v_readlane_b32 s47, v238, 21
	v_addc_co_u32_e64 v239, s[56:57], 0, v239, s[48:49]
	v_addc_co_u32_e64 v240, s[56:57], 0, v240, s[50:51]
	v_addc_co_u32_e64 v239, s[56:57], 0, v239, s[52:53]
	v_addc_co_u32_e64 v240, s[56:57], 0, v240, s[54:55]
	v_cmp_lt_u32_e64 s[48:49], s46, v237
	v_cmp_lt_u32_e64 s[50:51], s46, v238
	v_cmp_lt_u32_e64 s[52:53], s47, v237
	v_cmp_lt_u32_e64 s[54:55], s47, v238
	v_readlane_b32 s46, v237, 22
	v_readlane_b32 s47, v238, 22
	v_addc_co_u32_e64 v239, s[56:57], 0, v239, s[48:49]
	v_addc_co_u32_e64 v240, s[56:57], 0, v240, s[50:51]
	v_addc_co_u32_e64 v239, s[56:57], 0, v239, s[52:53]
; DEV void peer_gather_token(const Params& p, int tok) {
;     ...
;   const int e0 = p.eidx[(size_t)tok * 128 + lane], e1 = p.eidx[(size_t)tok * 128 + 64 + lane];
;   const int g0 = __builtin_bit_cast(int, p.gw[(size_t)tok * 128 + lane]), g1 = __builtin_bit_cast(int, p.gw[(size_t)tok * 128 + 64 + lane]);
;   u32x2 dn[4][3], up[4][3];
;   auto issue = [&](int k, int slot) {
;     const int e = (k < 64) ? __builtin_amdgcn_readlane(e0, k) : __builtin_amdgcn_readlane(e1, k - 64);
;     const unsigned char* dr = p.down8 + (size_t)e * ROW6 + lane * 24;
;     const unsigned char* ur = p.up8 + (size_t)e * ROW6 + lane * 24;
; #pragma unroll
;     for (int i = 0; i < 3; ++i) { dn[slot][i] = *(const u32x2*)(dr + i * 8); up[slot][i] = *(const u32x2*)(ur + i * 8); }
;   };
	v_addc_co_u32_e64 v240, s[56:57], 0, v240, s[54:55]
	v_cmp_lt_u32_e64 s[48:49], s46, v237
	v_cmp_lt_u32_e64 s[50:51], s46, v238
	v_cmp_lt_u32_e64 s[52:53], s47, v237
	v_cmp_lt_u32_e64 s[54:55], s47, v238
	v_readlane_b32 s46, v237, 23
	v_readlane_b32 s47, v238, 23
	v_addc_co_u32_e64 v239, s[56:57], 0, v239, s[48:49]
	v_addc_co_u32_e64 v240, s[56:57], 0, v240, s[50:51]
	v_addc_co_u32_e64 v239, s[56:57], 0, v239, s[52:53]
	v_addc_co_u32_e64 v240, s[56:57], 0, v240, s[54:55]
	v_cmp_lt_u32_e64 s[48:49], s46, v237
	v_cmp_lt_u32_e64 s[50:51], s46, v238
	v_cmp_lt_u32_e64 s[52:53], s47, v237
	v_cmp_lt_u32_e64 s[54:55], s47, v238
	v_readlane_b32 s46, v237, 24
	v_readlane_b32 s47, v238, 24
	v_addc_co_u32_e64 v239, s[56:57], 0, v239, s[48:49]
	v_addc_co_u32_e64 v240, s[56:57], 0, v240, s[50:51]
	v_addc_co_u32_e64 v239, s[56:57], 0, v239, s[52:53]
	v_addc_co_u32_e64 v240, s[56:57], 0, v240, s[54:55]
	v_cmp_lt_u32_e64 s[48:49], s46, v237
	v_cmp_lt_u32_e64 s[50:51], s46, v238
	v_cmp_lt_u32_e64 s[52:53], s47, v237
	v_cmp_lt_u32_e64 s[54:55], s47, v238
	v_readlane_b32 s46, v237, 25
	v_readlane_b32 s47, v238, 25
	v_addc_co_u32_e64 v239, s[56:57], 0, v239, s[48:49]
	v_addc_co_u32_e64 v240, s[56:57], 0, v240, s[50:51]
	v_addc_co_u32_e64 v239, s[56:57], 0, v239, s[52:53]
	v_addc_co_u32_e64 v240, s[56:57], 0, v240, s[54:55]
	v_cmp_lt_u32_e64 s[48:49], s46, v237
	v_cmp_lt_u32_e64 s[50:51], s46, v238
	v_cmp_lt_u32_e64 s[52:53], s47, v237
	v_cmp_lt_u32_e64 s[54:55], s47, v238
	v_readlane_b32 s46, v237, 26
	v_readlane_b32 s47, v238, 26
	v_addc_co_u32_e64 v239, s[56:57], 0, v239, s[48:49]
	v_addc_co_u32_e64 v240, s[56:57], 0, v240, s[50:51]
	v_addc_co_u32_e64 v239, s[56:57], 0, v239, s[52:53]
	v_addc_co_u32_e64 v240, s[56:57], 0, v240, s[54:55]
	v_cmp_lt_u32_e64 s[48:49], s46, v237
	v_cmp_lt_u32_e64 s[50:51], s46, v238
	v_cmp_lt_u32_e64 s[52:53], s47, v237
	v_cmp_lt_u32_e64 s[54:55], s47, v238
	v_readlane_b32 s46, v237, 27
	v_readlane_b32 s47, v238, 27
	v_addc_co_u32_e64 v239, s[56:57], 0, v239, s[48:49]
	v_addc_co_u32_e64 v240, s[56:57], 0, v240, s[50:51]
	v_addc_co_u32_e64 v239, s[56:57], 0, v239, s[52:53]
	v_addc_co_u32_e64 v240, s[56:57], 0, v240, s[54:55]
	v_cmp_lt_u32_e64 s[48:49], s46, v237
	v_cmp_lt_u32_e64 s[50:51], s46, v238
	v_cmp_lt_u32_e64 s[52:53], s47, v237
	v_cmp_lt_u32_e64 s[54:55], s47, v238
	v_readlane_b32 s46, v237, 28
	v_readlane_b32 s47, v238, 28
	v_addc_co_u32_e64 v239, s[56:57], 0, v239, s[48:49]
	v_addc_co_u32_e64 v240, s[56:57], 0, v240, s[50:51]
	v_addc_co_u32_e64 v239, s[56:57], 0, v239, s[52:53]
	v_addc_co_u32_e64 v240, s[56:57], 0, v240, s[54:55]
	v_cmp_lt_u32_e64 s[48:49], s46, v237
	v_cmp_lt_u32_e64 s[50:51], s46, v238
	v_cmp_lt_u32_e64 s[52:53], s47, v237
	v_cmp_lt_u32_e64 s[54:55], s47, v238
	v_readlane_b32 s46, v237, 29
	v_readlane_b32 s47, v238, 29
	v_addc_co_u32_e64 v239, s[56:57], 0, v239, s[48:49]
	v_addc_co_u32_e64 v240, s[56:57], 0, v240, s[50:51]
	v_addc_co_u32_e64 v239, s[56:57], 0, v239, s[52:53]
	v_addc_co_u32_e64 v240, s[56:57], 0, v240, s[54:55]
	v_cmp_lt_u32_e64 s[48:49], s46, v237
	v_cmp_lt_u32_e64 s[50:51], s46, v238
	v_cmp_lt_u32_e64 s[52:53], s47, v237
	v_cmp_lt_u32_e64 s[54:55], s47, v238
	v_readlane_b32 s46, v237, 30
	v_readlane_b32 s47, v238, 30
	v_addc_co_u32_e64 v239, s[56:57], 0, v239, s[48:49]
	v_addc_co_u32_e64 v240, s[56:57], 0, v240, s[50:51]
	v_addc_co_u32_e64 v239, s[56:57], 0, v239, s[52:53]
	v_addc_co_u32_e64 v240, s[56:57], 0, v240, s[54:55]
	v_cmp_lt_u32_e64 s[48:49], s46, v237
	v_cmp_lt_u32_e64 s[50:51], s46, v238
	v_cmp_lt_u32_e64 s[52:53], s47, v237
	v_cmp_lt_u32_e64 s[54:55], s47, v238
	v_readlane_b32 s46, v237, 31
	v_readlane_b32 s47, v238, 31
	v_addc_co_u32_e64 v239, s[56:57], 0, v239, s[48:49]
	v_addc_co_u32_e64 v240, s[56:57], 0, v240, s[50:51]
	v_addc_co_u32_e64 v239, s[56:57], 0, v239, s[52:53]
	v_addc_co_u32_e64 v240, s[56:57], 0, v240, s[54:55]
	v_cmp_lt_u32_e64 s[48:49], s46, v237
	v_cmp_lt_u32_e64 s[50:51], s46, v238
	v_cmp_lt_u32_e64 s[52:53], s47, v237
	v_cmp_lt_u32_e64 s[54:55], s47, v238
	v_readlane_b32 s46, v237, 32
	v_readlane_b32 s47, v238, 32
	v_addc_co_u32_e64 v239, s[56:57], 0, v239, s[48:49]
	v_addc_co_u32_e64 v240, s[56:57], 0, v240, s[50:51]
	v_addc_co_u32_e64 v239, s[56:57], 0, v239, s[52:53]
	v_addc_co_u32_e64 v240, s[56:57], 0, v240, s[54:55]
	v_cmp_lt_u32_e64 s[48:49], s46, v237
	v_cmp_lt_u32_e64 s[50:51], s46, v238
	v_cmp_lt_u32_e64 s[52:53], s47, v237
	v_cmp_lt_u32_e64 s[54:55], s47, v238
	v_readlane_b32 s46, v237, 33
	v_readlane_b32 s47, v238, 33
	v_addc_co_u32_e64 v239, s[56:57], 0, v239, s[48:49]
	v_addc_co_u32_e64 v240, s[56:57], 0, v240, s[50:51]
	v_addc_co_u32_e64 v239, s[56:57], 0, v239, s[52:53]
	v_addc_co_u32_e64 v240, s[56:57], 0, v240, s[54:55]
	v_cmp_lt_u32_e64 s[48:49], s46, v237
	v_cmp_lt_u32_e64 s[50:51], s46, v238
	v_cmp_lt_u32_e64 s[52:53], s47, v237
	v_cmp_lt_u32_e64 s[54:55], s47, v238
	v_readlane_b32 s46, v237, 34
	v_readlane_b32 s47, v238, 34
	v_addc_co_u32_e64 v239, s[56:57], 0, v239, s[48:49]
	v_addc_co_u32_e64 v240, s[56:57], 0, v240, s[50:51]
	v_addc_co_u32_e64 v239, s[56:57], 0, v239, s[52:53]
	v_addc_co_u32_e64 v240, s[56:57], 0, v240, s[54:55]
	v_cmp_lt_u32_e64 s[48:49], s46, v237
	v_cmp_lt_u32_e64 s[50:51], s46, v238
	v_cmp_lt_u32_e64 s[52:53], s47, v237
	v_cmp_lt_u32_e64 s[54:55], s47, v238
	v_readlane_b32 s46, v237, 35
	v_readlane_b32 s47, v238, 35
	v_addc_co_u32_e64 v239, s[56:57], 0, v239, s[48:49]
	v_addc_co_u32_e64 v240, s[56:57], 0, v240, s[50:51]
	v_addc_co_u32_e64 v239, s[56:57], 0, v239, s[52:53]
	v_addc_co_u32_e64 v240, s[56:57], 0, v240, s[54:55]
	v_cmp_lt_u32_e64 s[48:49], s46, v237
	v_cmp_lt_u32_e64 s[50:51], s46, v238
; DEV void peer_gather_token(const Params& p, int tok) {
;     ...
;   const int e0 = p.eidx[(size_t)tok * 128 + lane], e1 = p.eidx[(size_t)tok * 128 + 64 + lane];
;   const int g0 = __builtin_bit_cast(int, p.gw[(size_t)tok * 128 + lane]), g1 = __builtin_bit_cast(int, p.gw[(size_t)tok * 128 + 64 + lane]);
;   u32x2 dn[4][3], up[4][3];
;   auto issue = [&](int k, int slot) {
;     const int e = (k < 64) ? __builtin_amdgcn_readlane(e0, k) : __builtin_amdgcn_readlane(e1, k - 64);
;     const unsigned char* dr = p.down8 + (size_t)e * ROW6 + lane * 24;
;     const unsigned char* ur = p.up8 + (size_t)e * ROW6 + lane * 24;
; #pragma unroll
;     for (int i = 0; i < 3; ++i) { dn[slot][i] = *(const u32x2*)(dr + i * 8); up[slot][i] = *(const u32x2*)(ur + i * 8); }
;   };
	v_cmp_lt_u32_e64 s[52:53], s47, v237
	v_cmp_lt_u32_e64 s[54:55], s47, v238
	v_readlane_b32 s46, v237, 36
	v_readlane_b32 s47, v238, 36
	v_addc_co_u32_e64 v239, s[56:57], 0, v239, s[48:49]
	v_addc_co_u32_e64 v240, s[56:57], 0, v240, s[50:51]
	v_addc_co_u32_e64 v239, s[56:57], 0, v239, s[52:53]
	v_addc_co_u32_e64 v240, s[56:57], 0, v240, s[54:55]
	v_cmp_lt_u32_e64 s[48:49], s46, v237
	v_cmp_lt_u32_e64 s[50:51], s46, v238
	v_cmp_lt_u32_e64 s[52:53], s47, v237
	v_cmp_lt_u32_e64 s[54:55], s47, v238
	v_readlane_b32 s46, v237, 37
	v_readlane_b32 s47, v238, 37
	v_addc_co_u32_e64 v239, s[56:57], 0, v239, s[48:49]
	v_addc_co_u32_e64 v240, s[56:57], 0, v240, s[50:51]
	v_addc_co_u32_e64 v239, s[56:57], 0, v239, s[52:53]
	v_addc_co_u32_e64 v240, s[56:57], 0, v240, s[54:55]
	v_cmp_lt_u32_e64 s[48:49], s46, v237
	v_cmp_lt_u32_e64 s[50:51], s46, v238
	v_cmp_lt_u32_e64 s[52:53], s47, v237
	v_cmp_lt_u32_e64 s[54:55], s47, v238
	v_readlane_b32 s46, v237, 38
	v_readlane_b32 s47, v238, 38
	v_addc_co_u32_e64 v239, s[56:57], 0, v239, s[48:49]
	v_addc_co_u32_e64 v240, s[56:57], 0, v240, s[50:51]
	v_addc_co_u32_e64 v239, s[56:57], 0, v239, s[52:53]
	v_addc_co_u32_e64 v240, s[56:57], 0, v240, s[54:55]
	v_cmp_lt_u32_e64 s[48:49], s46, v237
	v_cmp_lt_u32_e64 s[50:51], s46, v238
	v_cmp_lt_u32_e64 s[52:53], s47, v237
	v_cmp_lt_u32_e64 s[54:55], s47, v238
	v_readlane_b32 s46, v237, 39
	v_readlane_b32 s47, v238, 39
	v_addc_co_u32_e64 v239, s[56:57], 0, v239, s[48:49]
	v_addc_co_u32_e64 v240, s[56:57], 0, v240, s[50:51]
	v_addc_co_u32_e64 v239, s[56:57], 0, v239, s[52:53]
	v_addc_co_u32_e64 v240, s[56:57], 0, v240, s[54:55]
	v_cmp_lt_u32_e64 s[48:49], s46, v237
	v_cmp_lt_u32_e64 s[50:51], s46, v238
	v_cmp_lt_u32_e64 s[52:53], s47, v237
	v_cmp_lt_u32_e64 s[54:55], s47, v238
	v_readlane_b32 s46, v237, 40
	v_readlane_b32 s47, v238, 40
	v_addc_co_u32_e64 v239, s[56:57], 0, v239, s[48:49]
	v_addc_co_u32_e64 v240, s[56:57], 0, v240, s[50:51]
	v_addc_co_u32_e64 v239, s[56:57], 0, v239, s[52:53]
	v_addc_co_u32_e64 v240, s[56:57], 0, v240, s[54:55]
	v_cmp_lt_u32_e64 s[48:49], s46, v237
	v_cmp_lt_u32_e64 s[50:51], s46, v238
	v_cmp_lt_u32_e64 s[52:53], s47, v237
	v_cmp_lt_u32_e64 s[54:55], s47, v238
	v_readlane_b32 s46, v237, 41
	v_readlane_b32 s47, v238, 41
	v_addc_co_u32_e64 v239, s[56:57], 0, v239, s[48:49]
	v_addc_co_u32_e64 v240, s[56:57], 0, v240, s[50:51]
	v_addc_co_u32_e64 v239, s[56:57], 0, v239, s[52:53]
	v_addc_co_u32_e64 v240, s[56:57], 0, v240, s[54:55]
	v_cmp_lt_u32_e64 s[48:49], s46, v237
	v_cmp_lt_u32_e64 s[50:51], s46, v238
	v_cmp_lt_u32_e64 s[52:53], s47, v237
	v_cmp_lt_u32_e64 s[54:55], s47, v238
	v_readlane_b32 s46, v237, 42
	v_readlane_b32 s47, v238, 42
	v_addc_co_u32_e64 v239, s[56:57], 0, v239, s[48:49]
	v_addc_co_u32_e64 v240, s[56:57], 0, v240, s[50:51]
	v_addc_co_u32_e64 v239, s[56:57], 0, v239, s[52:53]
	v_addc_co_u32_e64 v240, s[56:57], 0, v240, s[54:55]
	v_cmp_lt_u32_e64 s[48:49], s46, v237
	v_cmp_lt_u32_e64 s[50:51], s46, v238
	v_cmp_lt_u32_e64 s[52:53], s47, v237
	v_cmp_lt_u32_e64 s[54:55], s47, v238
	v_readlane_b32 s46, v237, 43
	v_readlane_b32 s47, v238, 43
	v_addc_co_u32_e64 v239, s[56:57], 0, v239, s[48:49]
	v_addc_co_u32_e64 v240, s[56:57], 0, v240, s[50:51]
	v_addc_co_u32_e64 v239, s[56:57], 0, v239, s[52:53]
	v_addc_co_u32_e64 v240, s[56:57], 0, v240, s[54:55]
	v_cmp_lt_u32_e64 s[48:49], s46, v237
	v_cmp_lt_u32_e64 s[50:51], s46, v238
	v_cmp_lt_u32_e64 s[52:53], s47, v237
	v_cmp_lt_u32_e64 s[54:55], s47, v238
	v_readlane_b32 s46, v237, 44
	v_readlane_b32 s47, v238, 44
	v_addc_co_u32_e64 v239, s[56:57], 0, v239, s[48:49]
	v_addc_co_u32_e64 v240, s[56:57], 0, v240, s[50:51]
	v_addc_co_u32_e64 v239, s[56:57], 0, v239, s[52:53]
	v_addc_co_u32_e64 v240, s[56:57], 0, v240, s[54:55]
	v_cmp_lt_u32_e64 s[48:49], s46, v237
	v_cmp_lt_u32_e64 s[50:51], s46, v238
	v_cmp_lt_u32_e64 s[52:53], s47, v237
	v_cmp_lt_u32_e64 s[54:55], s47, v238
	v_readlane_b32 s46, v237, 45
	v_readlane_b32 s47, v238, 45
	v_addc_co_u32_e64 v239, s[56:57], 0, v239, s[48:49]
	v_addc_co_u32_e64 v240, s[56:57], 0, v240, s[50:51]
	v_addc_co_u32_e64 v239, s[56:57], 0, v239, s[52:53]
	v_addc_co_u32_e64 v240, s[56:57], 0, v240, s[54:55]
	v_cmp_lt_u32_e64 s[48:49], s46, v237
	v_cmp_lt_u32_e64 s[50:51], s46, v238
	v_cmp_lt_u32_e64 s[52:53], s47, v237
	v_cmp_lt_u32_e64 s[54:55], s47, v238
	v_readlane_b32 s46, v237, 46
	v_readlane_b32 s47, v238, 46
	v_addc_co_u32_e64 v239, s[56:57], 0, v239, s[48:49]
	v_addc_co_u32_e64 v240, s[56:57], 0, v240, s[50:51]
	v_addc_co_u32_e64 v239, s[56:57], 0, v239, s[52:53]
	v_addc_co_u32_e64 v240, s[56:57], 0, v240, s[54:55]
	v_cmp_lt_u32_e64 s[48:49], s46, v237
	v_cmp_lt_u32_e64 s[50:51], s46, v238
	v_cmp_lt_u32_e64 s[52:53], s47, v237
	v_cmp_lt_u32_e64 s[54:55], s47, v238
	v_readlane_b32 s46, v237, 47
	v_readlane_b32 s47, v238, 47
	v_addc_co_u32_e64 v239, s[56:57], 0, v239, s[48:49]
	v_addc_co_u32_e64 v240, s[56:57], 0, v240, s[50:51]
	v_addc_co_u32_e64 v239, s[56:57], 0, v239, s[52:53]
	v_addc_co_u32_e64 v240, s[56:57], 0, v240, s[54:55]
	v_cmp_lt_u32_e64 s[48:49], s46, v237
	v_cmp_lt_u32_e64 s[50:51], s46, v238
	v_cmp_lt_u32_e64 s[52:53], s47, v237
	v_cmp_lt_u32_e64 s[54:55], s47, v238
	v_readlane_b32 s46, v237, 48
	v_readlane_b32 s47, v238, 48
	v_addc_co_u32_e64 v239, s[56:57], 0, v239, s[48:49]
	v_addc_co_u32_e64 v240, s[56:57], 0, v240, s[50:51]
	v_addc_co_u32_e64 v239, s[56:57], 0, v239, s[52:53]
	v_addc_co_u32_e64 v240, s[56:57], 0, v240, s[54:55]
	v_cmp_lt_u32_e64 s[48:49], s46, v237
	v_cmp_lt_u32_e64 s[50:51], s46, v238
	v_cmp_lt_u32_e64 s[52:53], s47, v237
	v_cmp_lt_u32_e64 s[54:55], s47, v238
	v_readlane_b32 s46, v237, 49
	v_readlane_b32 s47, v238, 49
; DEV void peer_gather_token(const Params& p, int tok) {
;     ...
;   const int e0 = p.eidx[(size_t)tok * 128 + lane], e1 = p.eidx[(size_t)tok * 128 + 64 + lane];
;   const int g0 = __builtin_bit_cast(int, p.gw[(size_t)tok * 128 + lane]), g1 = __builtin_bit_cast(int, p.gw[(size_t)tok * 128 + 64 + lane]);
;   u32x2 dn[4][3], up[4][3];
;   auto issue = [&](int k, int slot) {
;     const int e = (k < 64) ? __builtin_amdgcn_readlane(e0, k) : __builtin_amdgcn_readlane(e1, k - 64);
;     const unsigned char* dr = p.down8 + (size_t)e * ROW6 + lane * 24;
;     const unsigned char* ur = p.up8 + (size_t)e * ROW6 + lane * 24;
; #pragma unroll
;     for (int i = 0; i < 3; ++i) { dn[slot][i] = *(const u32x2*)(dr + i * 8); up[slot][i] = *(const u32x2*)(ur + i * 8); }
;   };
	v_addc_co_u32_e64 v239, s[56:57], 0, v239, s[48:49]
	v_addc_co_u32_e64 v240, s[56:57], 0, v240, s[50:51]
	v_addc_co_u32_e64 v239, s[56:57], 0, v239, s[52:53]
	v_addc_co_u32_e64 v240, s[56:57], 0, v240, s[54:55]
	v_cmp_lt_u32_e64 s[48:49], s46, v237
	v_cmp_lt_u32_e64 s[50:51], s46, v238
	v_cmp_lt_u32_e64 s[52:53], s47, v237
	v_cmp_lt_u32_e64 s[54:55], s47, v238
	v_readlane_b32 s46, v237, 50
	v_readlane_b32 s47, v238, 50
	v_addc_co_u32_e64 v239, s[56:57], 0, v239, s[48:49]
	v_addc_co_u32_e64 v240, s[56:57], 0, v240, s[50:51]
	v_addc_co_u32_e64 v239, s[56:57], 0, v239, s[52:53]
	v_addc_co_u32_e64 v240, s[56:57], 0, v240, s[54:55]
	v_cmp_lt_u32_e64 s[48:49], s46, v237
	v_cmp_lt_u32_e64 s[50:51], s46, v238
	v_cmp_lt_u32_e64 s[52:53], s47, v237
	v_cmp_lt_u32_e64 s[54:55], s47, v238
	v_readlane_b32 s46, v237, 51
	v_readlane_b32 s47, v238, 51
	v_addc_co_u32_e64 v239, s[56:57], 0, v239, s[48:49]
	v_addc_co_u32_e64 v240, s[56:57], 0, v240, s[50:51]
	v_addc_co_u32_e64 v239, s[56:57], 0, v239, s[52:53]
	v_addc_co_u32_e64 v240, s[56:57], 0, v240, s[54:55]
	v_cmp_lt_u32_e64 s[48:49], s46, v237
	v_cmp_lt_u32_e64 s[50:51], s46, v238
	v_cmp_lt_u32_e64 s[52:53], s47, v237
	v_cmp_lt_u32_e64 s[54:55], s47, v238
	v_readlane_b32 s46, v237, 52
	v_readlane_b32 s47, v238, 52
	v_addc_co_u32_e64 v239, s[56:57], 0, v239, s[48:49]
	v_addc_co_u32_e64 v240, s[56:57], 0, v240, s[50:51]
	v_addc_co_u32_e64 v239, s[56:57], 0, v239, s[52:53]
	v_addc_co_u32_e64 v240, s[56:57], 0, v240, s[54:55]
	v_cmp_lt_u32_e64 s[48:49], s46, v237
	v_cmp_lt_u32_e64 s[50:51], s46, v238
	v_cmp_lt_u32_e64 s[52:53], s47, v237
	v_cmp_lt_u32_e64 s[54:55], s47, v238
	v_readlane_b32 s46, v237, 53
	v_readlane_b32 s47, v238, 53
	v_addc_co_u32_e64 v239, s[56:57], 0, v239, s[48:49]
	v_addc_co_u32_e64 v240, s[56:57], 0, v240, s[50:51]
	v_addc_co_u32_e64 v239, s[56:57], 0, v239, s[52:53]
	v_addc_co_u32_e64 v240, s[56:57], 0, v240, s[54:55]
	v_cmp_lt_u32_e64 s[48:49], s46, v237
	v_cmp_lt_u32_e64 s[50:51], s46, v238
	v_cmp_lt_u32_e64 s[52:53], s47, v237
	v_cmp_lt_u32_e64 s[54:55], s47, v238
	v_readlane_b32 s46, v237, 54
	v_readlane_b32 s47, v238, 54
	v_addc_co_u32_e64 v239, s[56:57], 0, v239, s[48:49]
	v_addc_co_u32_e64 v240, s[56:57], 0, v240, s[50:51]
	v_addc_co_u32_e64 v239, s[56:57], 0, v239, s[52:53]
	v_addc_co_u32_e64 v240, s[56:57], 0, v240, s[54:55]
	v_cmp_lt_u32_e64 s[48:49], s46, v237
	v_cmp_lt_u32_e64 s[50:51], s46, v238
	v_cmp_lt_u32_e64 s[52:53], s47, v237
	v_cmp_lt_u32_e64 s[54:55], s47, v238
	v_readlane_b32 s46, v237, 55
	v_readlane_b32 s47, v238, 55
	v_addc_co_u32_e64 v239, s[56:57], 0, v239, s[48:49]
	v_addc_co_u32_e64 v240, s[56:57], 0, v240, s[50:51]
	v_addc_co_u32_e64 v239, s[56:57], 0, v239, s[52:53]
	v_addc_co_u32_e64 v240, s[56:57], 0, v240, s[54:55]
	v_cmp_lt_u32_e64 s[48:49], s46, v237
	v_cmp_lt_u32_e64 s[50:51], s46, v238
	v_cmp_lt_u32_e64 s[52:53], s47, v237
	v_cmp_lt_u32_e64 s[54:55], s47, v238
	v_readlane_b32 s46, v237, 56
	v_readlane_b32 s47, v238, 56
	v_addc_co_u32_e64 v239, s[56:57], 0, v239, s[48:49]
	v_addc_co_u32_e64 v240, s[56:57], 0, v240, s[50:51]
	v_addc_co_u32_e64 v239, s[56:57], 0, v239, s[52:53]
	v_addc_co_u32_e64 v240, s[56:57], 0, v240, s[54:55]
	v_cmp_lt_u32_e64 s[48:49], s46, v237
	v_cmp_lt_u32_e64 s[50:51], s46, v238
	v_cmp_lt_u32_e64 s[52:53], s47, v237
	v_cmp_lt_u32_e64 s[54:55], s47, v238
	v_readlane_b32 s46, v237, 57
	v_readlane_b32 s47, v238, 57
	v_addc_co_u32_e64 v239, s[56:57], 0, v239, s[48:49]
	v_addc_co_u32_e64 v240, s[56:57], 0, v240, s[50:51]
	v_addc_co_u32_e64 v239, s[56:57], 0, v239, s[52:53]
	v_addc_co_u32_e64 v240, s[56:57], 0, v240, s[54:55]
	v_cmp_lt_u32_e64 s[48:49], s46, v237
	v_cmp_lt_u32_e64 s[50:51], s46, v238
	v_cmp_lt_u32_e64 s[52:53], s47, v237
	v_cmp_lt_u32_e64 s[54:55], s47, v238
	v_readlane_b32 s46, v237, 58
	v_readlane_b32 s47, v238, 58
	v_addc_co_u32_e64 v239, s[56:57], 0, v239, s[48:49]
	v_addc_co_u32_e64 v240, s[56:57], 0, v240, s[50:51]
	v_addc_co_u32_e64 v239, s[56:57], 0, v239, s[52:53]
	v_addc_co_u32_e64 v240, s[56:57], 0, v240, s[54:55]
	v_cmp_lt_u32_e64 s[48:49], s46, v237
	v_cmp_lt_u32_e64 s[50:51], s46, v238
	v_cmp_lt_u32_e64 s[52:53], s47, v237
	v_cmp_lt_u32_e64 s[54:55], s47, v238
	v_readlane_b32 s46, v237, 59
	v_readlane_b32 s47, v238, 59
	v_addc_co_u32_e64 v239, s[56:57], 0, v239, s[48:49]
	v_addc_co_u32_e64 v240, s[56:57], 0, v240, s[50:51]
	v_addc_co_u32_e64 v239, s[56:57], 0, v239, s[52:53]
	v_addc_co_u32_e64 v240, s[56:57], 0, v240, s[54:55]
	v_cmp_lt_u32_e64 s[48:49], s46, v237
	v_cmp_lt_u32_e64 s[50:51], s46, v238
	v_cmp_lt_u32_e64 s[52:53], s47, v237
	v_cmp_lt_u32_e64 s[54:55], s47, v238
	v_readlane_b32 s46, v237, 60
	v_readlane_b32 s47, v238, 60
	v_addc_co_u32_e64 v239, s[56:57], 0, v239, s[48:49]
	v_addc_co_u32_e64 v240, s[56:57], 0, v240, s[50:51]
	v_addc_co_u32_e64 v239, s[56:57], 0, v239, s[52:53]
	v_addc_co_u32_e64 v240, s[56:57], 0, v240, s[54:55]
	v_cmp_lt_u32_e64 s[48:49], s46, v237
	v_cmp_lt_u32_e64 s[50:51], s46, v238
	v_cmp_lt_u32_e64 s[52:53], s47, v237
	v_cmp_lt_u32_e64 s[54:55], s47, v238
	v_readlane_b32 s46, v237, 61
	v_readlane_b32 s47, v238, 61
	v_addc_co_u32_e64 v239, s[56:57], 0, v239, s[48:49]
	v_addc_co_u32_e64 v240, s[56:57], 0, v240, s[50:51]
	v_addc_co_u32_e64 v239, s[56:57], 0, v239, s[52:53]
	v_addc_co_u32_e64 v240, s[56:57], 0, v240, s[54:55]
	v_cmp_lt_u32_e64 s[48:49], s46, v237
	v_cmp_lt_u32_e64 s[50:51], s46, v238
	v_cmp_lt_u32_e64 s[52:53], s47, v237
	v_cmp_lt_u32_e64 s[54:55], s47, v238
	v_readlane_b32 s46, v237, 62
	v_readlane_b32 s47, v238, 62
	v_addc_co_u32_e64 v239, s[56:57], 0, v239, s[48:49]
	v_addc_co_u32_e64 v240, s[56:57], 0, v240, s[50:51]
	v_addc_co_u32_e64 v239, s[56:57], 0, v239, s[52:53]
	v_addc_co_u32_e64 v240, s[56:57], 0, v240, s[54:55]
	v_cmp_lt_u32_e64 s[48:49], s46, v237
	v_cmp_lt_u32_e64 s[50:51], s46, v238
	v_cmp_lt_u32_e64 s[52:53], s47, v237
	v_cmp_lt_u32_e64 s[54:55], s47, v238
	v_readlane_b32 s46, v237, 63
	v_readlane_b32 s47, v238, 63
	v_addc_co_u32_e64 v239, s[56:57], 0, v239, s[48:49]
	v_addc_co_u32_e64 v240, s[56:57], 0, v240, s[50:51]
	v_addc_co_u32_e64 v239, s[56:57], 0, v239, s[52:53]
	v_addc_co_u32_e64 v240, s[56:57], 0, v240, s[54:55]
	v_cmp_lt_u32_e64 s[48:49], s46, v237
	v_cmp_lt_u32_e64 s[50:51], s46, v238
	v_cmp_lt_u32_e64 s[52:53], s47, v237
	v_cmp_lt_u32_e64 s[54:55], s47, v238
	s_nop 1
	v_addc_co_u32_e64 v239, s[56:57], 0, v239, s[48:49]
	v_addc_co_u32_e64 v240, s[56:57], 0, v240, s[50:51]
	v_addc_co_u32_e64 v239, s[56:57], 0, v239, s[52:53]
	v_addc_co_u32_e64 v240, s[56:57], 0, v240, s[54:55]
	v_xor_b32_e32 v239, s19, v239
	v_xor_b32_e32 v240, s19, v240
	s_xor_b32 s19, s19, 0x7f
	v_and_b32_e32 v237, 0xfffffc00, v241
	v_lshl_add_u32 v239, v239, 2, v237
	v_lshl_add_u32 v240, v240, 2, v237
	ds_write_b32 v239, v216
	ds_write_b32 v240, v217
	ds_write_b32 v239, v218 offset:512
	ds_write_b32 v240, v219 offset:512
	s_waitcnt lgkmcnt(0)
; DEV float gelu_exact(float v) { return 0.5f * v * (1.f + erff(v * 0.7071067811865476f)); }
; DEV void peer_gather_token(const Params& p, int tok) {
;     ...
;       if (k + 3 < 128) issue(k + 3, (s + 3) & 3);
;       const v6u dq = v6u{dn[s][0][0], dn[s][0][1], dn[s][1][0], dn[s][1][1], dn[s][2][0], dn[s][2][1]};
;       const v32f dv = __builtin_amdgcn_cvt_scalef32_pk32_f32_fp6(dq, 1.0f);
;       float d0 = 0.f, d1 = 0.f, d2 = 0.f, d3 = 0.f;
; #pragma unroll
;       for (int i = 0; i < 8; ++i) { d0 += dv[4 * i] * hx[4 * i]; d1 += dv[4 * i + 1] * hx[4 * i + 1]; d2 += dv[4 * i + 2] * hx[4 * i + 2]; d3 += dv[4 * i + 3] * hx[4 * i + 3]; }
;       const float d = wave_sum_fast((d0 + d1) + (d2 + d3)) * (1.f / DOWN_SCALE);
;       const float gk = __builtin_bit_cast(float, (k < 64) ? __builtin_amdgcn_readlane(g0, k) : __builtin_amdgcn_readlane(g1, k - 64));
;       const float act = gelu_exact(d) * gk * (1.f / UP_SCALE);
	ds_read_b32 v216, v241
	ds_read_b32 v217, v241 offset:256
	ds_read_b32 v218, v241 offset:512
	ds_read_b32 v219, v241 offset:768
	s_waitcnt lgkmcnt(0)
	v_cvt_scalef32_pk32_f32_fp6 v[2:33], v[98:103], 1.0
	v_mul_f32_e32 v200, v2, v34
	v_mul_f32_e32 v201, v3, v35
	v_mul_f32_e32 v202, v4, v36
	v_mul_f32_e32 v203, v5, v37
	v_fmac_f32_e32 v200, v6, v38
	v_fmac_f32_e32 v201, v7, v39
	v_fmac_f32_e32 v202, v8, v40
	v_fmac_f32_e32 v203, v9, v41
	v_fmac_f32_e32 v200, v10, v42
	v_fmac_f32_e32 v201, v11, v43
	v_fmac_f32_e32 v202, v12, v44
	v_fmac_f32_e32 v203, v13, v45
	v_fmac_f32_e32 v200, v14, v46
	v_fmac_f32_e32 v201, v15, v47
	v_fmac_f32_e32 v202, v16, v48
	v_fmac_f32_e32 v203, v17, v49
	v_fmac_f32_e32 v200, v18, v50
	v_fmac_f32_e32 v201, v19, v51
	v_fmac_f32_e32 v202, v20, v52
	v_fmac_f32_e32 v203, v21, v53
	v_fmac_f32_e32 v200, v22, v54
	v_fmac_f32_e32 v201, v23, v55
	v_fmac_f32_e32 v202, v24, v56
	v_fmac_f32_e32 v203, v25, v57
	v_fmac_f32_e32 v200, v26, v58
	v_fmac_f32_e32 v201, v27, v59
	v_fmac_f32_e32 v202, v28, v60
	v_fmac_f32_e32 v203, v29, v61
	v_fmac_f32_e32 v200, v30, v62
	v_fmac_f32_e32 v201, v31, v63
	v_fmac_f32_e32 v202, v32, v64
	v_fmac_f32_e32 v203, v33, v65
	v_add_f32_e32 v200, v201, v200
	v_add_f32_e32 v202, v203, v202
	v_cvt_scalef32_pk32_f32_fp6 v[2:33], v[104:109], 1.0
	v_add_f32_e32 v200, v202, v200
	s_add_i32 s38, s24, 0
	v_readlane_b32 s26, v199, s38
	s_mov_b32 s39, 0
	v_readlane_b32 s25, v216, s39
	v_add_f32_dpp v200, v200, v200 quad_perm:[1,0,3,2] row_mask:0xf bank_mask:0xf bound_ctrl:1
	s_nop 1
	v_add_f32_dpp v200, v200, v200 quad_perm:[2,3,0,1] row_mask:0xf bank_mask:0xf bound_ctrl:1
	s_nop 1
	v_add_f32_dpp v200, v200, v200 row_half_mirror row_mask:0xf bank_mask:0xf bound_ctrl:1
	s_nop 1
	v_add_f32_dpp v200, v200, v200 row_mirror row_mask:0xf bank_mask:0xf bound_ctrl:1
	s_nop 1
	v_add_f32_dpp v200, v200, v200 row_bcast:15 row_mask:0xa bank_mask:0xf
	s_nop 1
	v_add_f32_dpp v200, v200, v200 row_bcast:31 row_mask:0xc bank_mask:0xf
	s_nop 0
	v_readlane_b32 s27, v200, 63
	v_mul_f32_e32 v204, s27, v212
	v_mul_f32_e32 v205, 0x3f3504f3, v204
	v_cmp_lt_f32_e64 s[32:33], |v205|, 1.0
	s_and_b64 vcc, exec, s[32:33]
	s_cbranch_vccnz .Lsm_33
	v_fma_f32 v208, |v205|, s9, v214
	v_fma_f32 v208, |v205|, v208, s10
	v_fma_f32 v208, |v205|, v208, s11
	v_fma_f32 v208, |v205|, v208, s12
	v_fma_f32 v208, |v205|, v208, s13
	v_fma_f32 v208, |v205|, v208, s14
	v_fma_f32 v208, |v205|, v208, |v205|
	v_mul_f32_e32 v209, 0xbfb8aa3b, v208
	v_fma_f32 v210, v208, s15, -v209
	v_rndne_f32_e32 v211, v209
	v_fmac_f32_e32 v210, 0xb2a5705f, v208
	v_sub_f32_e32 v209, v209, v211
	v_add_f32_e32 v209, v209, v210
	v_cvt_i32_f32_e32 v210, v211
	v_exp_f32_e32 v209, v209
	v_cmp_nlt_f32_e32 vcc, s16, v208
	v_ldexp_f32 v209, v209, v210
	s_nop 0
	v_cndmask_b32_e32 v209, 0, v209, vcc
	v_cmp_ngt_f32_e32 vcc, s17, v208
	s_nop 1
	v_cndmask_b32_e32 v208, v215, v209, vcc
	v_sub_f32_e32 v210, 1.0, v208
	s_branch .Ljn_33

; DEV float gelu_exact(float v) { return 0.5f * v * (1.f + erff(v * 0.7071067811865476f)); }
; DEV void peer_gather_token(const Params& p, int tok) {
;     ...
;       if (k + 3 < 128) issue(k + 3, (s + 3) & 3);
;       const v6u dq = v6u{dn[s][0][0], dn[s][0][1], dn[s][1][0], dn[s][1][1], dn[s][2][0], dn[s][2][1]};
;       const v32f dv = __builtin_amdgcn_cvt_scalef32_pk32_f32_fp6(dq, 1.0f);
;       float d0 = 0.f, d1 = 0.f, d2 = 0.f, d3 = 0.f;
; #pragma unroll
;       for (int i = 0; i < 8; ++i) { d0 += dv[4 * i] * hx[4 * i]; d1 += dv[4 * i + 1] * hx[4 * i + 1]; d2 += dv[4 * i + 2] * hx[4 * i + 2]; d3 += dv[4 * i + 3] * hx[4 * i + 3]; }
;       const float d = wave_sum_fast((d0 + d1) + (d2 + d3)) * (1.f / DOWN_SCALE);
;       const float gk = __builtin_bit_cast(float, (k < 64) ? __builtin_amdgcn_readlane(g0, k) : __builtin_amdgcn_readlane(g1, k - 64));
;       const float act = gelu_exact(d) * gk * (1.f / UP_SCALE);
;       const v6u uq = v6u{up[s][0][0], up[s][0][1], up[s][1][0], up[s][1][1], up[s][2][0], up[s][2][1]};
;       const v32f uv = __builtin_amdgcn_cvt_scalef32_pk32_f32_fp6(uq, 1.0f);
; #pragma unroll
;       for (int i = 0; i < 32; ++i) acc[i] += act * uv[i];
.Ljn_33:
	v_bfi_b32 v209, s18, v210, v205
	v_mul_f32_e32 v208, 0.5, v204
	v_add_f32_e32 v209, 1.0, v209
	v_mul_f32_e32 v208, v208, v209
	v_mul_f32_e32 v208, s26, v208
	v_mul_f32_e32 v206, 0x3e800000, v208
	v_pk_fma_f32 v[66:67], v[2:3], v[206:207], v[66:67] op_sel_hi:[1,0,1]
	v_pk_fma_f32 v[68:69], v[4:5], v[206:207], v[68:69] op_sel_hi:[1,0,1]
	v_pk_fma_f32 v[70:71], v[6:7], v[206:207], v[70:71] op_sel_hi:[1,0,1]
	v_pk_fma_f32 v[72:73], v[8:9], v[206:207], v[72:73] op_sel_hi:[1,0,1]
	v_pk_fma_f32 v[74:75], v[10:11], v[206:207], v[74:75] op_sel_hi:[1,0,1]
	v_pk_fma_f32 v[76:77], v[12:13], v[206:207], v[76:77] op_sel_hi:[1,0,1]
	v_pk_fma_f32 v[78:79], v[14:15], v[206:207], v[78:79] op_sel_hi:[1,0,1]
	v_pk_fma_f32 v[80:81], v[16:17], v[206:207], v[80:81] op_sel_hi:[1,0,1]
	v_pk_fma_f32 v[82:83], v[18:19], v[206:207], v[82:83] op_sel_hi:[1,0,1]
	v_pk_fma_f32 v[84:85], v[20:21], v[206:207], v[84:85] op_sel_hi:[1,0,1]
	v_pk_fma_f32 v[86:87], v[22:23], v[206:207], v[86:87] op_sel_hi:[1,0,1]
	v_pk_fma_f32 v[88:89], v[24:25], v[206:207], v[88:89] op_sel_hi:[1,0,1]
	v_pk_fma_f32 v[90:91], v[26:27], v[206:207], v[90:91] op_sel_hi:[1,0,1]
	v_pk_fma_f32 v[92:93], v[28:29], v[206:207], v[92:93] op_sel_hi:[1,0,1]
	v_pk_fma_f32 v[94:95], v[30:31], v[206:207], v[94:95] op_sel_hi:[1,0,1]
	v_pk_fma_f32 v[96:97], v[32:33], v[206:207], v[96:97] op_sel_hi:[1,0,1]
	s_mul_i32 s40, s25, 0xc00
	s_add_u32 s28, s62, s40
	s_addc_u32 s29, s63, 0
	global_load_dwordx4 v[98:101], v1, s[28:29]
	global_load_dwordx4 v[102:105], v1, s[28:29] offset:2048
	global_load_dwordx4 v[106:109], v1, s[28:29] offset:1024
	s_waitcnt vmcnt(21)
	v_cvt_scalef32_pk32_f32_fp6 v[2:33], v[110:115], 1.0
	v_mul_f32_e32 v200, v2, v34
	v_mul_f32_e32 v201, v3, v35
	v_mul_f32_e32 v202, v4, v36
	v_mul_f32_e32 v203, v5, v37
	v_fmac_f32_e32 v200, v6, v38
	v_fmac_f32_e32 v201, v7, v39
	v_fmac_f32_e32 v202, v8, v40
	v_fmac_f32_e32 v203, v9, v41
	v_fmac_f32_e32 v200, v10, v42
	v_fmac_f32_e32 v201, v11, v43
	v_fmac_f32_e32 v202, v12, v44
	v_fmac_f32_e32 v203, v13, v45
	v_fmac_f32_e32 v200, v14, v46
	v_fmac_f32_e32 v201, v15, v47
	v_fmac_f32_e32 v202, v16, v48
	v_fmac_f32_e32 v203, v17, v49
	v_fmac_f32_e32 v200, v18, v50
	v_fmac_f32_e32 v201, v19, v51
	v_fmac_f32_e32 v202, v20, v52
	v_fmac_f32_e32 v203, v21, v53
	v_fmac_f32_e32 v200, v22, v54
	v_fmac_f32_e32 v201, v23, v55
	v_fmac_f32_e32 v202, v24, v56
	v_fmac_f32_e32 v203, v25, v57
	v_fmac_f32_e32 v200, v26, v58
	v_fmac_f32_e32 v201, v27, v59
	v_fmac_f32_e32 v202, v28, v60
	v_fmac_f32_e32 v203, v29, v61
	v_fmac_f32_e32 v200, v30, v62
	v_fmac_f32_e32 v201, v31, v63
	v_fmac_f32_e32 v202, v32, v64
	v_fmac_f32_e32 v203, v33, v65
	v_add_f32_e32 v200, v201, v200
	v_add_f32_e32 v202, v203, v202
	v_cvt_scalef32_pk32_f32_fp6 v[2:33], v[116:121], 1.0
	v_add_f32_e32 v200, v202, v200
	s_add_i32 s38, s24, 1
	v_readlane_b32 s26, v199, s38
	s_mov_b32 s39, 1
	v_readlane_b32 s25, v216, s39
	v_add_f32_dpp v200, v200, v200 quad_perm:[1,0,3,2] row_mask:0xf bank_mask:0xf bound_ctrl:1
	s_nop 1
	v_add_f32_dpp v200, v200, v200 quad_perm:[2,3,0,1] row_mask:0xf bank_mask:0xf bound_ctrl:1
	s_nop 1
	v_add_f32_dpp v200, v200, v200 row_half_mirror row_mask:0xf bank_mask:0xf bound_ctrl:1
	s_nop 1
	v_add_f32_dpp v200, v200, v200 row_mirror row_mask:0xf bank_mask:0xf bound_ctrl:1
	s_nop 1
	v_add_f32_dpp v200, v200, v200 row_bcast:15 row_mask:0xa bank_mask:0xf
	s_nop 1
	v_add_f32_dpp v200, v200, v200 row_bcast:31 row_mask:0xc bank_mask:0xf
	s_nop 0
	v_readlane_b32 s27, v200, 63
	v_mul_f32_e32 v204, s27, v212
	v_mul_f32_e32 v205, 0x3f3504f3, v204
	v_cmp_lt_f32_e64 s[32:33], |v205|, 1.0
	s_and_b64 vcc, exec, s[32:33]
	s_cbranch_vccnz .Lsm_35
	v_fma_f32 v208, |v205|, s9, v214
	v_fma_f32 v208, |v205|, v208, s10
	v_fma_f32 v208, |v205|, v208, s11
	v_fma_f32 v208, |v205|, v208, s12
	v_fma_f32 v208, |v205|, v208, s13
	v_fma_f32 v208, |v205|, v208, s14
	v_fma_f32 v208, |v205|, v208, |v205|
	v_mul_f32_e32 v209, 0xbfb8aa3b, v208
	v_fma_f32 v210, v208, s15, -v209
	v_rndne_f32_e32 v211, v209
	v_fmac_f32_e32 v210, 0xb2a5705f, v208
	v_sub_f32_e32 v209, v209, v211
	v_add_f32_e32 v209, v209, v210
	v_cvt_i32_f32_e32 v210, v211
	v_exp_f32_e32 v209, v209
	v_cmp_nlt_f32_e32 vcc, s16, v208
	v_ldexp_f32 v209, v209, v210
	s_nop 0
	v_cndmask_b32_e32 v209, 0, v209, vcc
	v_cmp_ngt_f32_e32 vcc, s17, v208
	s_nop 1
	v_cndmask_b32_e32 v208, v215, v209, vcc
	v_sub_f32_e32 v210, 1.0, v208
	s_branch .Ljn_35

; DEV float gelu_exact(float v) { return 0.5f * v * (1.f + erff(v * 0.7071067811865476f)); }
; DEV void peer_gather_token(const Params& p, int tok) {
;     ...
;       if (k + 3 < 128) issue(k + 3, (s + 3) & 3);
;       const v6u dq = v6u{dn[s][0][0], dn[s][0][1], dn[s][1][0], dn[s][1][1], dn[s][2][0], dn[s][2][1]};
;       const v32f dv = __builtin_amdgcn_cvt_scalef32_pk32_f32_fp6(dq, 1.0f);
;       float d0 = 0.f, d1 = 0.f, d2 = 0.f, d3 = 0.f;
; #pragma unroll
;       for (int i = 0; i < 8; ++i) { d0 += dv[4 * i] * hx[4 * i]; d1 += dv[4 * i + 1] * hx[4 * i + 1]; d2 += dv[4 * i + 2] * hx[4 * i + 2]; d3 += dv[4 * i + 3] * hx[4 * i + 3]; }
;       const float d = wave_sum_fast((d0 + d1) + (d2 + d3)) * (1.f / DOWN_SCALE);
;       const float gk = __builtin_bit_cast(float, (k < 64) ? __builtin_amdgcn_readlane(g0, k) : __builtin_amdgcn_readlane(g1, k - 64));
;       const float act = gelu_exact(d) * gk * (1.f / UP_SCALE);
;       const v6u uq = v6u{up[s][0][0], up[s][0][1], up[s][1][0], up[s][1][1], up[s][2][0], up[s][2][1]};
;       const v32f uv = __builtin_amdgcn_cvt_scalef32_pk32_f32_fp6(uq, 1.0f);
; #pragma unroll
;       for (int i = 0; i < 32; ++i) acc[i] += act * uv[i];
.Ljn_35:
	v_bfi_b32 v209, s18, v210, v205
	v_mul_f32_e32 v208, 0.5, v204
	v_add_f32_e32 v209, 1.0, v209
	v_mul_f32_e32 v208, v208, v209
	v_mul_f32_e32 v208, s26, v208
	v_mul_f32_e32 v206, 0x3e800000, v208
	v_pk_fma_f32 v[66:67], v[2:3], v[206:207], v[66:67] op_sel_hi:[1,0,1]
	v_pk_fma_f32 v[68:69], v[4:5], v[206:207], v[68:69] op_sel_hi:[1,0,1]
	v_pk_fma_f32 v[70:71], v[6:7], v[206:207], v[70:71] op_sel_hi:[1,0,1]
	v_pk_fma_f32 v[72:73], v[8:9], v[206:207], v[72:73] op_sel_hi:[1,0,1]
	v_pk_fma_f32 v[74:75], v[10:11], v[206:207], v[74:75] op_sel_hi:[1,0,1]
	v_pk_fma_f32 v[76:77], v[12:13], v[206:207], v[76:77] op_sel_hi:[1,0,1]
	v_pk_fma_f32 v[78:79], v[14:15], v[206:207], v[78:79] op_sel_hi:[1,0,1]
	v_pk_fma_f32 v[80:81], v[16:17], v[206:207], v[80:81] op_sel_hi:[1,0,1]
	v_pk_fma_f32 v[82:83], v[18:19], v[206:207], v[82:83] op_sel_hi:[1,0,1]
	v_pk_fma_f32 v[84:85], v[20:21], v[206:207], v[84:85] op_sel_hi:[1,0,1]
	v_pk_fma_f32 v[86:87], v[22:23], v[206:207], v[86:87] op_sel_hi:[1,0,1]
	v_pk_fma_f32 v[88:89], v[24:25], v[206:207], v[88:89] op_sel_hi:[1,0,1]
	v_pk_fma_f32 v[90:91], v[26:27], v[206:207], v[90:91] op_sel_hi:[1,0,1]
	v_pk_fma_f32 v[92:93], v[28:29], v[206:207], v[92:93] op_sel_hi:[1,0,1]
	v_pk_fma_f32 v[94:95], v[30:31], v[206:207], v[94:95] op_sel_hi:[1,0,1]
	v_pk_fma_f32 v[96:97], v[32:33], v[206:207], v[96:97] op_sel_hi:[1,0,1]
	s_mul_i32 s40, s25, 0xc00
	s_add_u32 s28, s62, s40
	s_addc_u32 s29, s63, 0
	global_load_dwordx4 v[110:113], v1, s[28:29]
	global_load_dwordx4 v[114:117], v1, s[28:29] offset:2048
	global_load_dwordx4 v[118:121], v1, s[28:29] offset:1024
	s_waitcnt vmcnt(21)
	v_cvt_scalef32_pk32_f32_fp6 v[2:33], v[122:127], 1.0
	v_mul_f32_e32 v200, v2, v34
	v_mul_f32_e32 v201, v3, v35
	v_mul_f32_e32 v202, v4, v36
	v_mul_f32_e32 v203, v5, v37
	v_fmac_f32_e32 v200, v6, v38
	v_fmac_f32_e32 v201, v7, v39
	v_fmac_f32_e32 v202, v8, v40
	v_fmac_f32_e32 v203, v9, v41
	v_fmac_f32_e32 v200, v10, v42
	v_fmac_f32_e32 v201, v11, v43
	v_fmac_f32_e32 v202, v12, v44
	v_fmac_f32_e32 v203, v13, v45
	v_fmac_f32_e32 v200, v14, v46
	v_fmac_f32_e32 v201, v15, v47
	v_fmac_f32_e32 v202, v16, v48
	v_fmac_f32_e32 v203, v17, v49
	v_fmac_f32_e32 v200, v18, v50
	v_fmac_f32_e32 v201, v19, v51
	v_fmac_f32_e32 v202, v20, v52
	v_fmac_f32_e32 v203, v21, v53
	v_fmac_f32_e32 v200, v22, v54
	v_fmac_f32_e32 v201, v23, v55
	v_fmac_f32_e32 v202, v24, v56
	v_fmac_f32_e32 v203, v25, v57
	v_fmac_f32_e32 v200, v26, v58
	v_fmac_f32_e32 v201, v27, v59
	v_fmac_f32_e32 v202, v28, v60
	v_fmac_f32_e32 v203, v29, v61
	v_fmac_f32_e32 v200, v30, v62
	v_fmac_f32_e32 v201, v31, v63
	v_fmac_f32_e32 v202, v32, v64
	v_fmac_f32_e32 v203, v33, v65
	v_add_f32_e32 v200, v201, v200
	v_add_f32_e32 v202, v203, v202
	v_cvt_scalef32_pk32_f32_fp6 v[2:33], v[128:133], 1.0
	v_add_f32_e32 v200, v202, v200
	s_add_i32 s38, s24, 2
	v_readlane_b32 s26, v199, s38
	s_mov_b32 s39, 2
	v_readlane_b32 s25, v216, s39
	v_add_f32_dpp v200, v200, v200 quad_perm:[1,0,3,2] row_mask:0xf bank_mask:0xf bound_ctrl:1
	s_nop 1
	v_add_f32_dpp v200, v200, v200 quad_perm:[2,3,0,1] row_mask:0xf bank_mask:0xf bound_ctrl:1
	s_nop 1
	v_add_f32_dpp v200, v200, v200 row_half_mirror row_mask:0xf bank_mask:0xf bound_ctrl:1
	s_nop 1
	v_add_f32_dpp v200, v200, v200 row_mirror row_mask:0xf bank_mask:0xf bound_ctrl:1
	s_nop 1
	v_add_f32_dpp v200, v200, v200 row_bcast:15 row_mask:0xa bank_mask:0xf
	s_nop 1
	v_add_f32_dpp v200, v200, v200 row_bcast:31 row_mask:0xc bank_mask:0xf
	s_nop 0
	v_readlane_b32 s27, v200, 63
	v_mul_f32_e32 v204, s27, v212
	v_mul_f32_e32 v205, 0x3f3504f3, v204
	v_cmp_lt_f32_e64 s[32:33], |v205|, 1.0
	s_and_b64 vcc, exec, s[32:33]
	s_cbranch_vccnz .Lsm_37
	v_fma_f32 v208, |v205|, s9, v214
	v_fma_f32 v208, |v205|, v208, s10
	v_fma_f32 v208, |v205|, v208, s11
	v_fma_f32 v208, |v205|, v208, s12
	v_fma_f32 v208, |v205|, v208, s13
	v_fma_f32 v208, |v205|, v208, s14
	v_fma_f32 v208, |v205|, v208, |v205|
	v_mul_f32_e32 v209, 0xbfb8aa3b, v208
	v_fma_f32 v210, v208, s15, -v209
	v_rndne_f32_e32 v211, v209
	v_fmac_f32_e32 v210, 0xb2a5705f, v208
	v_sub_f32_e32 v209, v209, v211
	v_add_f32_e32 v209, v209, v210
	v_cvt_i32_f32_e32 v210, v211
	v_exp_f32_e32 v209, v209
	v_cmp_nlt_f32_e32 vcc, s16, v208
	v_ldexp_f32 v209, v209, v210
	s_nop 0
	v_cndmask_b32_e32 v209, 0, v209, vcc
	v_cmp_ngt_f32_e32 vcc, s17, v208
	s_nop 1
	v_cndmask_b32_e32 v208, v215, v209, vcc
	v_sub_f32_e32 v210, 1.0, v208
	s_branch .Ljn_37

; DEV float gelu_exact(float v) { return 0.5f * v * (1.f + erff(v * 0.7071067811865476f)); }
; DEV void peer_gather_token(const Params& p, int tok) {
;     ...
;       if (k + 3 < 128) issue(k + 3, (s + 3) & 3);
;       const v6u dq = v6u{dn[s][0][0], dn[s][0][1], dn[s][1][0], dn[s][1][1], dn[s][2][0], dn[s][2][1]};
;       const v32f dv = __builtin_amdgcn_cvt_scalef32_pk32_f32_fp6(dq, 1.0f);
;       float d0 = 0.f, d1 = 0.f, d2 = 0.f, d3 = 0.f;
; #pragma unroll
;       for (int i = 0; i < 8; ++i) { d0 += dv[4 * i] * hx[4 * i]; d1 += dv[4 * i + 1] * hx[4 * i + 1]; d2 += dv[4 * i + 2] * hx[4 * i + 2]; d3 += dv[4 * i + 3] * hx[4 * i + 3]; }
;       const float d = wave_sum_fast((d0 + d1) + (d2 + d3)) * (1.f / DOWN_SCALE);
;       const float gk = __builtin_bit_cast(float, (k < 64) ? __builtin_amdgcn_readlane(g0, k) : __builtin_amdgcn_readlane(g1, k - 64));
;       const float act = gelu_exact(d) * gk * (1.f / UP_SCALE);
;       const v6u uq = v6u{up[s][0][0], up[s][0][1], up[s][1][0], up[s][1][1], up[s][2][0], up[s][2][1]};
;       const v32f uv = __builtin_amdgcn_cvt_scalef32_pk32_f32_fp6(uq, 1.0f);
; #pragma unroll
;       for (int i = 0; i < 32; ++i) acc[i] += act * uv[i];
.Ljn_37:
	v_bfi_b32 v209, s18, v210, v205
	v_mul_f32_e32 v208, 0.5, v204
	v_add_f32_e32 v209, 1.0, v209
	v_mul_f32_e32 v208, v208, v209
	v_mul_f32_e32 v208, s26, v208
	v_mul_f32_e32 v206, 0x3e800000, v208
	v_pk_fma_f32 v[66:67], v[2:3], v[206:207], v[66:67] op_sel_hi:[1,0,1]
	v_pk_fma_f32 v[68:69], v[4:5], v[206:207], v[68:69] op_sel_hi:[1,0,1]
	v_pk_fma_f32 v[70:71], v[6:7], v[206:207], v[70:71] op_sel_hi:[1,0,1]
	v_pk_fma_f32 v[72:73], v[8:9], v[206:207], v[72:73] op_sel_hi:[1,0,1]
	v_pk_fma_f32 v[74:75], v[10:11], v[206:207], v[74:75] op_sel_hi:[1,0,1]
	v_pk_fma_f32 v[76:77], v[12:13], v[206:207], v[76:77] op_sel_hi:[1,0,1]
	v_pk_fma_f32 v[78:79], v[14:15], v[206:207], v[78:79] op_sel_hi:[1,0,1]
	v_pk_fma_f32 v[80:81], v[16:17], v[206:207], v[80:81] op_sel_hi:[1,0,1]
	v_pk_fma_f32 v[82:83], v[18:19], v[206:207], v[82:83] op_sel_hi:[1,0,1]
	v_pk_fma_f32 v[84:85], v[20:21], v[206:207], v[84:85] op_sel_hi:[1,0,1]
	v_pk_fma_f32 v[86:87], v[22:23], v[206:207], v[86:87] op_sel_hi:[1,0,1]
	v_pk_fma_f32 v[88:89], v[24:25], v[206:207], v[88:89] op_sel_hi:[1,0,1]
	v_pk_fma_f32 v[90:91], v[26:27], v[206:207], v[90:91] op_sel_hi:[1,0,1]
	v_pk_fma_f32 v[92:93], v[28:29], v[206:207], v[92:93] op_sel_hi:[1,0,1]
	v_pk_fma_f32 v[94:95], v[30:31], v[206:207], v[94:95] op_sel_hi:[1,0,1]
	v_pk_fma_f32 v[96:97], v[32:33], v[206:207], v[96:97] op_sel_hi:[1,0,1]
	s_mul_i32 s40, s25, 0xc00
	s_add_u32 s28, s62, s40
	s_addc_u32 s29, s63, 0
	global_load_dwordx4 v[122:125], v1, s[28:29]
	global_load_dwordx4 v[126:129], v1, s[28:29] offset:2048
	global_load_dwordx4 v[130:133], v1, s[28:29] offset:1024
	s_waitcnt vmcnt(21)
	v_cvt_scalef32_pk32_f32_fp6 v[2:33], v[134:139], 1.0
	v_mul_f32_e32 v200, v2, v34
	v_mul_f32_e32 v201, v3, v35
	v_mul_f32_e32 v202, v4, v36
	v_mul_f32_e32 v203, v5, v37
	v_fmac_f32_e32 v200, v6, v38
	v_fmac_f32_e32 v201, v7, v39
	v_fmac_f32_e32 v202, v8, v40
	v_fmac_f32_e32 v203, v9, v41
	v_fmac_f32_e32 v200, v10, v42
	v_fmac_f32_e32 v201, v11, v43
	v_fmac_f32_e32 v202, v12, v44
	v_fmac_f32_e32 v203, v13, v45
	v_fmac_f32_e32 v200, v14, v46
	v_fmac_f32_e32 v201, v15, v47
	v_fmac_f32_e32 v202, v16, v48
	v_fmac_f32_e32 v203, v17, v49
	v_fmac_f32_e32 v200, v18, v50
	v_fmac_f32_e32 v201, v19, v51
	v_fmac_f32_e32 v202, v20, v52
	v_fmac_f32_e32 v203, v21, v53
	v_fmac_f32_e32 v200, v22, v54
	v_fmac_f32_e32 v201, v23, v55
	v_fmac_f32_e32 v202, v24, v56
	v_fmac_f32_e32 v203, v25, v57
	v_fmac_f32_e32 v200, v26, v58
	v_fmac_f32_e32 v201, v27, v59
	v_fmac_f32_e32 v202, v28, v60
	v_fmac_f32_e32 v203, v29, v61
	v_fmac_f32_e32 v200, v30, v62
	v_fmac_f32_e32 v201, v31, v63
	v_fmac_f32_e32 v202, v32, v64
	v_fmac_f32_e32 v203, v33, v65
	v_add_f32_e32 v200, v201, v200
	v_add_f32_e32 v202, v203, v202
	v_cvt_scalef32_pk32_f32_fp6 v[2:33], v[140:145], 1.0
	v_add_f32_e32 v200, v202, v200
	s_add_i32 s38, s24, 3
	v_readlane_b32 s26, v199, s38
	s_mov_b32 s39, 3
	v_readlane_b32 s25, v216, s39
	v_add_f32_dpp v200, v200, v200 quad_perm:[1,0,3,2] row_mask:0xf bank_mask:0xf bound_ctrl:1
	s_nop 1
	v_add_f32_dpp v200, v200, v200 quad_perm:[2,3,0,1] row_mask:0xf bank_mask:0xf bound_ctrl:1
	s_nop 1
	v_add_f32_dpp v200, v200, v200 row_half_mirror row_mask:0xf bank_mask:0xf bound_ctrl:1
	s_nop 1
	v_add_f32_dpp v200, v200, v200 row_mirror row_mask:0xf bank_mask:0xf bound_ctrl:1
	s_nop 1
	v_add_f32_dpp v200, v200, v200 row_bcast:15 row_mask:0xa bank_mask:0xf
	s_nop 1
	v_add_f32_dpp v200, v200, v200 row_bcast:31 row_mask:0xc bank_mask:0xf
	s_nop 0
	v_readlane_b32 s27, v200, 63
	v_mul_f32_e32 v204, s27, v212
	v_mul_f32_e32 v205, 0x3f3504f3, v204
	v_cmp_lt_f32_e64 s[32:33], |v205|, 1.0
	s_and_b64 vcc, exec, s[32:33]
	s_cbranch_vccnz .Lsm_39
	v_fma_f32 v208, |v205|, s9, v214
	v_fma_f32 v208, |v205|, v208, s10
	v_fma_f32 v208, |v205|, v208, s11
	v_fma_f32 v208, |v205|, v208, s12
	v_fma_f32 v208, |v205|, v208, s13
	v_fma_f32 v208, |v205|, v208, s14
	v_fma_f32 v208, |v205|, v208, |v205|
	v_mul_f32_e32 v209, 0xbfb8aa3b, v208
	v_fma_f32 v210, v208, s15, -v209
	v_rndne_f32_e32 v211, v209
	v_fmac_f32_e32 v210, 0xb2a5705f, v208
	v_sub_f32_e32 v209, v209, v211
	v_add_f32_e32 v209, v209, v210
	v_cvt_i32_f32_e32 v210, v211
	v_exp_f32_e32 v209, v209
	v_cmp_nlt_f32_e32 vcc, s16, v208
	v_ldexp_f32 v209, v209, v210
	s_nop 0
	v_cndmask_b32_e32 v209, 0, v209, vcc
	v_cmp_ngt_f32_e32 vcc, s17, v208
	s_nop 1
	v_cndmask_b32_e32 v208, v215, v209, vcc
	v_sub_f32_e32 v210, 1.0, v208
	s_branch .Ljn_39

; DEV float gelu_exact(float v) { return 0.5f * v * (1.f + erff(v * 0.7071067811865476f)); }
; DEV void peer_gather_token(const Params& p, int tok) {
;     ...
;       if (k + 3 < 128) issue(k + 3, (s + 3) & 3);
;       const v6u dq = v6u{dn[s][0][0], dn[s][0][1], dn[s][1][0], dn[s][1][1], dn[s][2][0], dn[s][2][1]};
;       const v32f dv = __builtin_amdgcn_cvt_scalef32_pk32_f32_fp6(dq, 1.0f);
;       float d0 = 0.f, d1 = 0.f, d2 = 0.f, d3 = 0.f;
; #pragma unroll
;       for (int i = 0; i < 8; ++i) { d0 += dv[4 * i] * hx[4 * i]; d1 += dv[4 * i + 1] * hx[4 * i + 1]; d2 += dv[4 * i + 2] * hx[4 * i + 2]; d3 += dv[4 * i + 3] * hx[4 * i + 3]; }
;       const float d = wave_sum_fast((d0 + d1) + (d2 + d3)) * (1.f / DOWN_SCALE);
;       const float gk = __builtin_bit_cast(float, (k < 64) ? __builtin_amdgcn_readlane(g0, k) : __builtin_amdgcn_readlane(g1, k - 64));
;       const float act = gelu_exact(d) * gk * (1.f / UP_SCALE);
;       const v6u uq = v6u{up[s][0][0], up[s][0][1], up[s][1][0], up[s][1][1], up[s][2][0], up[s][2][1]};
;       const v32f uv = __builtin_amdgcn_cvt_scalef32_pk32_f32_fp6(uq, 1.0f);
; #pragma unroll
;       for (int i = 0; i < 32; ++i) acc[i] += act * uv[i];
.Ljn_39:
	v_bfi_b32 v209, s18, v210, v205
	v_mul_f32_e32 v208, 0.5, v204
	v_add_f32_e32 v209, 1.0, v209
	v_mul_f32_e32 v208, v208, v209
	v_mul_f32_e32 v208, s26, v208
	v_mul_f32_e32 v206, 0x3e800000, v208
	v_pk_fma_f32 v[66:67], v[2:3], v[206:207], v[66:67] op_sel_hi:[1,0,1]
	v_pk_fma_f32 v[68:69], v[4:5], v[206:207], v[68:69] op_sel_hi:[1,0,1]
	v_pk_fma_f32 v[70:71], v[6:7], v[206:207], v[70:71] op_sel_hi:[1,0,1]
	v_pk_fma_f32 v[72:73], v[8:9], v[206:207], v[72:73] op_sel_hi:[1,0,1]
	v_pk_fma_f32 v[74:75], v[10:11], v[206:207], v[74:75] op_sel_hi:[1,0,1]
	v_pk_fma_f32 v[76:77], v[12:13], v[206:207], v[76:77] op_sel_hi:[1,0,1]
	v_pk_fma_f32 v[78:79], v[14:15], v[206:207], v[78:79] op_sel_hi:[1,0,1]
	v_pk_fma_f32 v[80:81], v[16:17], v[206:207], v[80:81] op_sel_hi:[1,0,1]
	v_pk_fma_f32 v[82:83], v[18:19], v[206:207], v[82:83] op_sel_hi:[1,0,1]
	v_pk_fma_f32 v[84:85], v[20:21], v[206:207], v[84:85] op_sel_hi:[1,0,1]
	v_pk_fma_f32 v[86:87], v[22:23], v[206:207], v[86:87] op_sel_hi:[1,0,1]
	v_pk_fma_f32 v[88:89], v[24:25], v[206:207], v[88:89] op_sel_hi:[1,0,1]
	v_pk_fma_f32 v[90:91], v[26:27], v[206:207], v[90:91] op_sel_hi:[1,0,1]
	v_pk_fma_f32 v[92:93], v[28:29], v[206:207], v[92:93] op_sel_hi:[1,0,1]
	v_pk_fma_f32 v[94:95], v[30:31], v[206:207], v[94:95] op_sel_hi:[1,0,1]
	v_pk_fma_f32 v[96:97], v[32:33], v[206:207], v[96:97] op_sel_hi:[1,0,1]
	s_mul_i32 s40, s25, 0xc00
	s_add_u32 s28, s62, s40
	s_addc_u32 s29, s63, 0
	global_load_dwordx4 v[134:137], v1, s[28:29]
	global_load_dwordx4 v[138:141], v1, s[28:29] offset:2048
	global_load_dwordx4 v[142:145], v1, s[28:29] offset:1024
	s_waitcnt vmcnt(21)
	v_cvt_scalef32_pk32_f32_fp6 v[2:33], v[146:151], 1.0
	v_mul_f32_e32 v200, v2, v34
	v_mul_f32_e32 v201, v3, v35
	v_mul_f32_e32 v202, v4, v36
	v_mul_f32_e32 v203, v5, v37
	v_fmac_f32_e32 v200, v6, v38
	v_fmac_f32_e32 v201, v7, v39
	v_fmac_f32_e32 v202, v8, v40
	v_fmac_f32_e32 v203, v9, v41
	v_fmac_f32_e32 v200, v10, v42
	v_fmac_f32_e32 v201, v11, v43
	v_fmac_f32_e32 v202, v12, v44
	v_fmac_f32_e32 v203, v13, v45
	v_fmac_f32_e32 v200, v14, v46
	v_fmac_f32_e32 v201, v15, v47
	v_fmac_f32_e32 v202, v16, v48
	v_fmac_f32_e32 v203, v17, v49
	v_fmac_f32_e32 v200, v18, v50
	v_fmac_f32_e32 v201, v19, v51
	v_fmac_f32_e32 v202, v20, v52
	v_fmac_f32_e32 v203, v21, v53
	v_fmac_f32_e32 v200, v22, v54
	v_fmac_f32_e32 v201, v23, v55
	v_fmac_f32_e32 v202, v24, v56
	v_fmac_f32_e32 v203, v25, v57
	v_fmac_f32_e32 v200, v26, v58
	v_fmac_f32_e32 v201, v27, v59
	v_fmac_f32_e32 v202, v28, v60
	v_fmac_f32_e32 v203, v29, v61
	v_fmac_f32_e32 v200, v30, v62
	v_fmac_f32_e32 v201, v31, v63
	v_fmac_f32_e32 v202, v32, v64
	v_fmac_f32_e32 v203, v33, v65
	v_add_f32_e32 v200, v201, v200
	v_add_f32_e32 v202, v203, v202
	v_cvt_scalef32_pk32_f32_fp6 v[2:33], v[152:157], 1.0
	v_add_f32_e32 v200, v202, v200
	s_add_i32 s38, s24, 4
	v_readlane_b32 s26, v199, s38
	s_mov_b32 s39, 4
	v_readlane_b32 s25, v216, s39
	v_add_f32_dpp v200, v200, v200 quad_perm:[1,0,3,2] row_mask:0xf bank_mask:0xf bound_ctrl:1
	s_nop 1
	v_add_f32_dpp v200, v200, v200 quad_perm:[2,3,0,1] row_mask:0xf bank_mask:0xf bound_ctrl:1
	s_nop 1
	v_add_f32_dpp v200, v200, v200 row_half_mirror row_mask:0xf bank_mask:0xf bound_ctrl:1
	s_nop 1
	v_add_f32_dpp v200, v200, v200 row_mirror row_mask:0xf bank_mask:0xf bound_ctrl:1
	s_nop 1
	v_add_f32_dpp v200, v200, v200 row_bcast:15 row_mask:0xa bank_mask:0xf
	s_nop 1
	v_add_f32_dpp v200, v200, v200 row_bcast:31 row_mask:0xc bank_mask:0xf
	s_nop 0
	v_readlane_b32 s27, v200, 63
	v_mul_f32_e32 v204, s27, v212
	v_mul_f32_e32 v205, 0x3f3504f3, v204
	v_cmp_lt_f32_e64 s[32:33], |v205|, 1.0
	s_and_b64 vcc, exec, s[32:33]
	s_cbranch_vccnz .Lsm_41
	v_fma_f32 v208, |v205|, s9, v214
	v_fma_f32 v208, |v205|, v208, s10
	v_fma_f32 v208, |v205|, v208, s11
	v_fma_f32 v208, |v205|, v208, s12
	v_fma_f32 v208, |v205|, v208, s13
	v_fma_f32 v208, |v205|, v208, s14
	v_fma_f32 v208, |v205|, v208, |v205|
	v_mul_f32_e32 v209, 0xbfb8aa3b, v208
	v_fma_f32 v210, v208, s15, -v209
	v_rndne_f32_e32 v211, v209
	v_fmac_f32_e32 v210, 0xb2a5705f, v208
	v_sub_f32_e32 v209, v209, v211
	v_add_f32_e32 v209, v209, v210
	v_cvt_i32_f32_e32 v210, v211
	v_exp_f32_e32 v209, v209
	v_cmp_nlt_f32_e32 vcc, s16, v208
	v_ldexp_f32 v209, v209, v210
	s_nop 0
	v_cndmask_b32_e32 v209, 0, v209, vcc
	v_cmp_ngt_f32_e32 vcc, s17, v208
	s_nop 1
	v_cndmask_b32_e32 v208, v215, v209, vcc
	v_sub_f32_e32 v210, 1.0, v208
	s_branch .Ljn_41

; DEV float gelu_exact(float v) { return 0.5f * v * (1.f + erff(v * 0.7071067811865476f)); }
; DEV void peer_gather_token(const Params& p, int tok) {
;     ...
;       if (k + 3 < 128) issue(k + 3, (s + 3) & 3);
;       const v6u dq = v6u{dn[s][0][0], dn[s][0][1], dn[s][1][0], dn[s][1][1], dn[s][2][0], dn[s][2][1]};
;       const v32f dv = __builtin_amdgcn_cvt_scalef32_pk32_f32_fp6(dq, 1.0f);
;       float d0 = 0.f, d1 = 0.f, d2 = 0.f, d3 = 0.f;
; #pragma unroll
;       for (int i = 0; i < 8; ++i) { d0 += dv[4 * i] * hx[4 * i]; d1 += dv[4 * i + 1] * hx[4 * i + 1]; d2 += dv[4 * i + 2] * hx[4 * i + 2]; d3 += dv[4 * i + 3] * hx[4 * i + 3]; }
;       const float d = wave_sum_fast((d0 + d1) + (d2 + d3)) * (1.f / DOWN_SCALE);
;       const float gk = __builtin_bit_cast(float, (k < 64) ? __builtin_amdgcn_readlane(g0, k) : __builtin_amdgcn_readlane(g1, k - 64));
;       const float act = gelu_exact(d) * gk * (1.f / UP_SCALE);
;       const v6u uq = v6u{up[s][0][0], up[s][0][1], up[s][1][0], up[s][1][1], up[s][2][0], up[s][2][1]};
;       const v32f uv = __builtin_amdgcn_cvt_scalef32_pk32_f32_fp6(uq, 1.0f);
; #pragma unroll
;       for (int i = 0; i < 32; ++i) acc[i] += act * uv[i];
.Ljn_41:
	v_bfi_b32 v209, s18, v210, v205
	v_mul_f32_e32 v208, 0.5, v204
	v_add_f32_e32 v209, 1.0, v209
	v_mul_f32_e32 v208, v208, v209
	v_mul_f32_e32 v208, s26, v208
	v_mul_f32_e32 v206, 0x3e800000, v208
	v_pk_fma_f32 v[66:67], v[2:3], v[206:207], v[66:67] op_sel_hi:[1,0,1]
	v_pk_fma_f32 v[68:69], v[4:5], v[206:207], v[68:69] op_sel_hi:[1,0,1]
	v_pk_fma_f32 v[70:71], v[6:7], v[206:207], v[70:71] op_sel_hi:[1,0,1]
	v_pk_fma_f32 v[72:73], v[8:9], v[206:207], v[72:73] op_sel_hi:[1,0,1]
	v_pk_fma_f32 v[74:75], v[10:11], v[206:207], v[74:75] op_sel_hi:[1,0,1]
	v_pk_fma_f32 v[76:77], v[12:13], v[206:207], v[76:77] op_sel_hi:[1,0,1]
	v_pk_fma_f32 v[78:79], v[14:15], v[206:207], v[78:79] op_sel_hi:[1,0,1]
	v_pk_fma_f32 v[80:81], v[16:17], v[206:207], v[80:81] op_sel_hi:[1,0,1]
	v_pk_fma_f32 v[82:83], v[18:19], v[206:207], v[82:83] op_sel_hi:[1,0,1]
	v_pk_fma_f32 v[84:85], v[20:21], v[206:207], v[84:85] op_sel_hi:[1,0,1]
	v_pk_fma_f32 v[86:87], v[22:23], v[206:207], v[86:87] op_sel_hi:[1,0,1]
	v_pk_fma_f32 v[88:89], v[24:25], v[206:207], v[88:89] op_sel_hi:[1,0,1]
	v_pk_fma_f32 v[90:91], v[26:27], v[206:207], v[90:91] op_sel_hi:[1,0,1]
	v_pk_fma_f32 v[92:93], v[28:29], v[206:207], v[92:93] op_sel_hi:[1,0,1]
	v_pk_fma_f32 v[94:95], v[30:31], v[206:207], v[94:95] op_sel_hi:[1,0,1]
	v_pk_fma_f32 v[96:97], v[32:33], v[206:207], v[96:97] op_sel_hi:[1,0,1]
	s_mul_i32 s40, s25, 0xc00
	s_add_u32 s28, s62, s40
	s_addc_u32 s29, s63, 0
	global_load_dwordx4 v[146:149], v1, s[28:29]
	global_load_dwordx4 v[150:153], v1, s[28:29] offset:2048
	global_load_dwordx4 v[154:157], v1, s[28:29] offset:1024
	s_waitcnt vmcnt(21)
	v_cvt_scalef32_pk32_f32_fp6 v[2:33], v[158:163], 1.0
	v_mul_f32_e32 v200, v2, v34
	v_mul_f32_e32 v201, v3, v35
	v_mul_f32_e32 v202, v4, v36
	v_mul_f32_e32 v203, v5, v37
	v_fmac_f32_e32 v200, v6, v38
	v_fmac_f32_e32 v201, v7, v39
	v_fmac_f32_e32 v202, v8, v40
	v_fmac_f32_e32 v203, v9, v41
	v_fmac_f32_e32 v200, v10, v42
	v_fmac_f32_e32 v201, v11, v43
	v_fmac_f32_e32 v202, v12, v44
	v_fmac_f32_e32 v203, v13, v45
	v_fmac_f32_e32 v200, v14, v46
	v_fmac_f32_e32 v201, v15, v47
	v_fmac_f32_e32 v202, v16, v48
	v_fmac_f32_e32 v203, v17, v49
	v_fmac_f32_e32 v200, v18, v50
	v_fmac_f32_e32 v201, v19, v51
	v_fmac_f32_e32 v202, v20, v52
	v_fmac_f32_e32 v203, v21, v53
	v_fmac_f32_e32 v200, v22, v54
	v_fmac_f32_e32 v201, v23, v55
	v_fmac_f32_e32 v202, v24, v56
	v_fmac_f32_e32 v203, v25, v57
	v_fmac_f32_e32 v200, v26, v58
	v_fmac_f32_e32 v201, v27, v59
	v_fmac_f32_e32 v202, v28, v60
	v_fmac_f32_e32 v203, v29, v61
	v_fmac_f32_e32 v200, v30, v62
	v_fmac_f32_e32 v201, v31, v63
	v_fmac_f32_e32 v202, v32, v64
	v_fmac_f32_e32 v203, v33, v65
	v_add_f32_e32 v200, v201, v200
	v_add_f32_e32 v202, v203, v202
	v_cvt_scalef32_pk32_f32_fp6 v[2:33], v[164:169], 1.0
	v_add_f32_e32 v200, v202, v200
	s_add_i32 s38, s24, 5
	v_readlane_b32 s26, v199, s38
	s_mov_b32 s39, 5
	v_readlane_b32 s25, v216, s39
	v_add_f32_dpp v200, v200, v200 quad_perm:[1,0,3,2] row_mask:0xf bank_mask:0xf bound_ctrl:1
	s_nop 1
	v_add_f32_dpp v200, v200, v200 quad_perm:[2,3,0,1] row_mask:0xf bank_mask:0xf bound_ctrl:1
	s_nop 1
	v_add_f32_dpp v200, v200, v200 row_half_mirror row_mask:0xf bank_mask:0xf bound_ctrl:1
	s_nop 1
	v_add_f32_dpp v200, v200, v200 row_mirror row_mask:0xf bank_mask:0xf bound_ctrl:1
	s_nop 1
	v_add_f32_dpp v200, v200, v200 row_bcast:15 row_mask:0xa bank_mask:0xf
	s_nop 1
	v_add_f32_dpp v200, v200, v200 row_bcast:31 row_mask:0xc bank_mask:0xf
	s_nop 0
	v_readlane_b32 s27, v200, 63
	v_mul_f32_e32 v204, s27, v212
	v_mul_f32_e32 v205, 0x3f3504f3, v204
	v_cmp_lt_f32_e64 s[32:33], |v205|, 1.0
	s_and_b64 vcc, exec, s[32:33]
	s_cbranch_vccnz .Lsm_43
	v_fma_f32 v208, |v205|, s9, v214
	v_fma_f32 v208, |v205|, v208, s10
	v_fma_f32 v208, |v205|, v208, s11
	v_fma_f32 v208, |v205|, v208, s12
	v_fma_f32 v208, |v205|, v208, s13
	v_fma_f32 v208, |v205|, v208, s14
	v_fma_f32 v208, |v205|, v208, |v205|
	v_mul_f32_e32 v209, 0xbfb8aa3b, v208
	v_fma_f32 v210, v208, s15, -v209
	v_rndne_f32_e32 v211, v209
	v_fmac_f32_e32 v210, 0xb2a5705f, v208
	v_sub_f32_e32 v209, v209, v211
	v_add_f32_e32 v209, v209, v210
	v_cvt_i32_f32_e32 v210, v211
	v_exp_f32_e32 v209, v209
	v_cmp_nlt_f32_e32 vcc, s16, v208
	v_ldexp_f32 v209, v209, v210
	s_nop 0
	v_cndmask_b32_e32 v209, 0, v209, vcc
	v_cmp_ngt_f32_e32 vcc, s17, v208
	s_nop 1
	v_cndmask_b32_e32 v208, v215, v209, vcc
	v_sub_f32_e32 v210, 1.0, v208
	s_branch .Ljn_43

; DEV float gelu_exact(float v) { return 0.5f * v * (1.f + erff(v * 0.7071067811865476f)); }
; DEV void peer_gather_token(const Params& p, int tok) {
;     ...
;       if (k + 3 < 128) issue(k + 3, (s + 3) & 3);
;       const v6u dq = v6u{dn[s][0][0], dn[s][0][1], dn[s][1][0], dn[s][1][1], dn[s][2][0], dn[s][2][1]};
;       const v32f dv = __builtin_amdgcn_cvt_scalef32_pk32_f32_fp6(dq, 1.0f);
;       float d0 = 0.f, d1 = 0.f, d2 = 0.f, d3 = 0.f;
; #pragma unroll
;       for (int i = 0; i < 8; ++i) { d0 += dv[4 * i] * hx[4 * i]; d1 += dv[4 * i + 1] * hx[4 * i + 1]; d2 += dv[4 * i + 2] * hx[4 * i + 2]; d3 += dv[4 * i + 3] * hx[4 * i + 3]; }
;       const float d = wave_sum_fast((d0 + d1) + (d2 + d3)) * (1.f / DOWN_SCALE);
;       const float gk = __builtin_bit_cast(float, (k < 64) ? __builtin_amdgcn_readlane(g0, k) : __builtin_amdgcn_readlane(g1, k - 64));
;       const float act = gelu_exact(d) * gk * (1.f / UP_SCALE);
;       const v6u uq = v6u{up[s][0][0], up[s][0][1], up[s][1][0], up[s][1][1], up[s][2][0], up[s][2][1]};
;       const v32f uv = __builtin_amdgcn_cvt_scalef32_pk32_f32_fp6(uq, 1.0f);
; #pragma unroll
;       for (int i = 0; i < 32; ++i) acc[i] += act * uv[i];
.Ljn_43:
	v_bfi_b32 v209, s18, v210, v205
	v_mul_f32_e32 v208, 0.5, v204
	v_add_f32_e32 v209, 1.0, v209
	v_mul_f32_e32 v208, v208, v209
	v_mul_f32_e32 v208, s26, v208
	v_mul_f32_e32 v206, 0x3e800000, v208
	v_pk_fma_f32 v[66:67], v[2:3], v[206:207], v[66:67] op_sel_hi:[1,0,1]
	v_pk_fma_f32 v[68:69], v[4:5], v[206:207], v[68:69] op_sel_hi:[1,0,1]
	v_pk_fma_f32 v[70:71], v[6:7], v[206:207], v[70:71] op_sel_hi:[1,0,1]
	v_pk_fma_f32 v[72:73], v[8:9], v[206:207], v[72:73] op_sel_hi:[1,0,1]
	v_pk_fma_f32 v[74:75], v[10:11], v[206:207], v[74:75] op_sel_hi:[1,0,1]
	v_pk_fma_f32 v[76:77], v[12:13], v[206:207], v[76:77] op_sel_hi:[1,0,1]
	v_pk_fma_f32 v[78:79], v[14:15], v[206:207], v[78:79] op_sel_hi:[1,0,1]
	v_pk_fma_f32 v[80:81], v[16:17], v[206:207], v[80:81] op_sel_hi:[1,0,1]
	v_pk_fma_f32 v[82:83], v[18:19], v[206:207], v[82:83] op_sel_hi:[1,0,1]
	v_pk_fma_f32 v[84:85], v[20:21], v[206:207], v[84:85] op_sel_hi:[1,0,1]
	v_pk_fma_f32 v[86:87], v[22:23], v[206:207], v[86:87] op_sel_hi:[1,0,1]
	v_pk_fma_f32 v[88:89], v[24:25], v[206:207], v[88:89] op_sel_hi:[1,0,1]
	v_pk_fma_f32 v[90:91], v[26:27], v[206:207], v[90:91] op_sel_hi:[1,0,1]
	v_pk_fma_f32 v[92:93], v[28:29], v[206:207], v[92:93] op_sel_hi:[1,0,1]
	v_pk_fma_f32 v[94:95], v[30:31], v[206:207], v[94:95] op_sel_hi:[1,0,1]
	v_pk_fma_f32 v[96:97], v[32:33], v[206:207], v[96:97] op_sel_hi:[1,0,1]
	s_mul_i32 s40, s25, 0xc00
	s_add_u32 s28, s62, s40
	s_addc_u32 s29, s63, 0
	global_load_dwordx4 v[158:161], v1, s[28:29]
	global_load_dwordx4 v[162:165], v1, s[28:29] offset:2048
	global_load_dwordx4 v[166:169], v1, s[28:29] offset:1024
	s_waitcnt vmcnt(21)
	v_cvt_scalef32_pk32_f32_fp6 v[2:33], v[170:175], 1.0
	v_mul_f32_e32 v200, v2, v34
	v_mul_f32_e32 v201, v3, v35
	v_mul_f32_e32 v202, v4, v36
	v_mul_f32_e32 v203, v5, v37
	v_fmac_f32_e32 v200, v6, v38
	v_fmac_f32_e32 v201, v7, v39
	v_fmac_f32_e32 v202, v8, v40
	v_fmac_f32_e32 v203, v9, v41
	v_fmac_f32_e32 v200, v10, v42
	v_fmac_f32_e32 v201, v11, v43
	v_fmac_f32_e32 v202, v12, v44
	v_fmac_f32_e32 v203, v13, v45
	v_fmac_f32_e32 v200, v14, v46
	v_fmac_f32_e32 v201, v15, v47
	v_fmac_f32_e32 v202, v16, v48
	v_fmac_f32_e32 v203, v17, v49
	v_fmac_f32_e32 v200, v18, v50
	v_fmac_f32_e32 v201, v19, v51
	v_fmac_f32_e32 v202, v20, v52
	v_fmac_f32_e32 v203, v21, v53
	v_fmac_f32_e32 v200, v22, v54
	v_fmac_f32_e32 v201, v23, v55
	v_fmac_f32_e32 v202, v24, v56
	v_fmac_f32_e32 v203, v25, v57
	v_fmac_f32_e32 v200, v26, v58
	v_fmac_f32_e32 v201, v27, v59
	v_fmac_f32_e32 v202, v28, v60
	v_fmac_f32_e32 v203, v29, v61
	v_fmac_f32_e32 v200, v30, v62
	v_fmac_f32_e32 v201, v31, v63
	v_fmac_f32_e32 v202, v32, v64
	v_fmac_f32_e32 v203, v33, v65
	v_add_f32_e32 v200, v201, v200
	v_add_f32_e32 v202, v203, v202
	v_cvt_scalef32_pk32_f32_fp6 v[2:33], v[176:181], 1.0
	v_add_f32_e32 v200, v202, v200
	s_add_i32 s38, s24, 6
	v_readlane_b32 s26, v199, s38
	s_mov_b32 s39, 6
	v_readlane_b32 s25, v216, s39
	v_add_f32_dpp v200, v200, v200 quad_perm:[1,0,3,2] row_mask:0xf bank_mask:0xf bound_ctrl:1
	s_nop 1
	v_add_f32_dpp v200, v200, v200 quad_perm:[2,3,0,1] row_mask:0xf bank_mask:0xf bound_ctrl:1
	s_nop 1
	v_add_f32_dpp v200, v200, v200 row_half_mirror row_mask:0xf bank_mask:0xf bound_ctrl:1
	s_nop 1
	v_add_f32_dpp v200, v200, v200 row_mirror row_mask:0xf bank_mask:0xf bound_ctrl:1
	s_nop 1
	v_add_f32_dpp v200, v200, v200 row_bcast:15 row_mask:0xa bank_mask:0xf
	s_nop 1
	v_add_f32_dpp v200, v200, v200 row_bcast:31 row_mask:0xc bank_mask:0xf
	s_nop 0
	v_readlane_b32 s27, v200, 63
	v_mul_f32_e32 v204, s27, v212
	v_mul_f32_e32 v205, 0x3f3504f3, v204
	v_cmp_lt_f32_e64 s[32:33], |v205|, 1.0
	s_and_b64 vcc, exec, s[32:33]
	s_cbranch_vccnz .Lsm_45
	v_fma_f32 v208, |v205|, s9, v214
	v_fma_f32 v208, |v205|, v208, s10
	v_fma_f32 v208, |v205|, v208, s11
	v_fma_f32 v208, |v205|, v208, s12
	v_fma_f32 v208, |v205|, v208, s13
	v_fma_f32 v208, |v205|, v208, s14
	v_fma_f32 v208, |v205|, v208, |v205|
	v_mul_f32_e32 v209, 0xbfb8aa3b, v208
	v_fma_f32 v210, v208, s15, -v209
	v_rndne_f32_e32 v211, v209
	v_fmac_f32_e32 v210, 0xb2a5705f, v208
	v_sub_f32_e32 v209, v209, v211
	v_add_f32_e32 v209, v209, v210
	v_cvt_i32_f32_e32 v210, v211
	v_exp_f32_e32 v209, v209
	v_cmp_nlt_f32_e32 vcc, s16, v208
	v_ldexp_f32 v209, v209, v210
	s_nop 0
	v_cndmask_b32_e32 v209, 0, v209, vcc
	v_cmp_ngt_f32_e32 vcc, s17, v208
	s_nop 1
	v_cndmask_b32_e32 v208, v215, v209, vcc
	v_sub_f32_e32 v210, 1.0, v208
	s_branch .Ljn_45

; DEV float gelu_exact(float v) { return 0.5f * v * (1.f + erff(v * 0.7071067811865476f)); }
; DEV void peer_gather_token(const Params& p, int tok) {
;     ...
;       if (k + 3 < 128) issue(k + 3, (s + 3) & 3);
;       const v6u dq = v6u{dn[s][0][0], dn[s][0][1], dn[s][1][0], dn[s][1][1], dn[s][2][0], dn[s][2][1]};
;       const v32f dv = __builtin_amdgcn_cvt_scalef32_pk32_f32_fp6(dq, 1.0f);
;       float d0 = 0.f, d1 = 0.f, d2 = 0.f, d3 = 0.f;
; #pragma unroll
;       for (int i = 0; i < 8; ++i) { d0 += dv[4 * i] * hx[4 * i]; d1 += dv[4 * i + 1] * hx[4 * i + 1]; d2 += dv[4 * i + 2] * hx[4 * i + 2]; d3 += dv[4 * i + 3] * hx[4 * i + 3]; }
;       const float d = wave_sum_fast((d0 + d1) + (d2 + d3)) * (1.f / DOWN_SCALE);
;       const float gk = __builtin_bit_cast(float, (k < 64) ? __builtin_amdgcn_readlane(g0, k) : __builtin_amdgcn_readlane(g1, k - 64));
;       const float act = gelu_exact(d) * gk * (1.f / UP_SCALE);
;       const v6u uq = v6u{up[s][0][0], up[s][0][1], up[s][1][0], up[s][1][1], up[s][2][0], up[s][2][1]};
;       const v32f uv = __builtin_amdgcn_cvt_scalef32_pk32_f32_fp6(uq, 1.0f);
; #pragma unroll
;       for (int i = 0; i < 32; ++i) acc[i] += act * uv[i];
.Ljn_45:
	v_bfi_b32 v209, s18, v210, v205
	v_mul_f32_e32 v208, 0.5, v204
	v_add_f32_e32 v209, 1.0, v209
	v_mul_f32_e32 v208, v208, v209
	v_mul_f32_e32 v208, s26, v208
	v_mul_f32_e32 v206, 0x3e800000, v208
	v_pk_fma_f32 v[66:67], v[2:3], v[206:207], v[66:67] op_sel_hi:[1,0,1]
	v_pk_fma_f32 v[68:69], v[4:5], v[206:207], v[68:69] op_sel_hi:[1,0,1]
	v_pk_fma_f32 v[70:71], v[6:7], v[206:207], v[70:71] op_sel_hi:[1,0,1]
	v_pk_fma_f32 v[72:73], v[8:9], v[206:207], v[72:73] op_sel_hi:[1,0,1]
	v_pk_fma_f32 v[74:75], v[10:11], v[206:207], v[74:75] op_sel_hi:[1,0,1]
	v_pk_fma_f32 v[76:77], v[12:13], v[206:207], v[76:77] op_sel_hi:[1,0,1]
	v_pk_fma_f32 v[78:79], v[14:15], v[206:207], v[78:79] op_sel_hi:[1,0,1]
	v_pk_fma_f32 v[80:81], v[16:17], v[206:207], v[80:81] op_sel_hi:[1,0,1]
	v_pk_fma_f32 v[82:83], v[18:19], v[206:207], v[82:83] op_sel_hi:[1,0,1]
	v_pk_fma_f32 v[84:85], v[20:21], v[206:207], v[84:85] op_sel_hi:[1,0,1]
	v_pk_fma_f32 v[86:87], v[22:23], v[206:207], v[86:87] op_sel_hi:[1,0,1]
	v_pk_fma_f32 v[88:89], v[24:25], v[206:207], v[88:89] op_sel_hi:[1,0,1]
	v_pk_fma_f32 v[90:91], v[26:27], v[206:207], v[90:91] op_sel_hi:[1,0,1]
	v_pk_fma_f32 v[92:93], v[28:29], v[206:207], v[92:93] op_sel_hi:[1,0,1]
	v_pk_fma_f32 v[94:95], v[30:31], v[206:207], v[94:95] op_sel_hi:[1,0,1]
	v_pk_fma_f32 v[96:97], v[32:33], v[206:207], v[96:97] op_sel_hi:[1,0,1]
	s_mul_i32 s40, s25, 0xc00
	s_add_u32 s28, s62, s40
	s_addc_u32 s29, s63, 0
	global_load_dwordx4 v[170:173], v1, s[28:29]
	global_load_dwordx4 v[174:177], v1, s[28:29] offset:2048
	global_load_dwordx4 v[178:181], v1, s[28:29] offset:1024
	s_waitcnt vmcnt(21)
	v_cvt_scalef32_pk32_f32_fp6 v[2:33], v[182:187], 1.0
	v_mul_f32_e32 v200, v2, v34
	v_mul_f32_e32 v201, v3, v35
	v_mul_f32_e32 v202, v4, v36
	v_mul_f32_e32 v203, v5, v37
	v_fmac_f32_e32 v200, v6, v38
	v_fmac_f32_e32 v201, v7, v39
	v_fmac_f32_e32 v202, v8, v40
	v_fmac_f32_e32 v203, v9, v41
	v_fmac_f32_e32 v200, v10, v42
	v_fmac_f32_e32 v201, v11, v43
	v_fmac_f32_e32 v202, v12, v44
	v_fmac_f32_e32 v203, v13, v45
	v_fmac_f32_e32 v200, v14, v46
	v_fmac_f32_e32 v201, v15, v47
	v_fmac_f32_e32 v202, v16, v48
	v_fmac_f32_e32 v203, v17, v49
	v_fmac_f32_e32 v200, v18, v50
	v_fmac_f32_e32 v201, v19, v51
	v_fmac_f32_e32 v202, v20, v52
	v_fmac_f32_e32 v203, v21, v53
	v_fmac_f32_e32 v200, v22, v54
	v_fmac_f32_e32 v201, v23, v55
	v_fmac_f32_e32 v202, v24, v56
	v_fmac_f32_e32 v203, v25, v57
	v_fmac_f32_e32 v200, v26, v58
	v_fmac_f32_e32 v201, v27, v59
	v_fmac_f32_e32 v202, v28, v60
	v_fmac_f32_e32 v203, v29, v61
	v_fmac_f32_e32 v200, v30, v62
	v_fmac_f32_e32 v201, v31, v63
	v_fmac_f32_e32 v202, v32, v64
	v_fmac_f32_e32 v203, v33, v65
	v_add_f32_e32 v200, v201, v200
	v_add_f32_e32 v202, v203, v202
	v_cvt_scalef32_pk32_f32_fp6 v[2:33], v[188:193], 1.0
	v_add_f32_e32 v200, v202, v200
	s_add_i32 s38, s24, 7
	v_readlane_b32 s26, v199, s38
	s_mov_b32 s39, 7
	v_readlane_b32 s25, v216, s39
	v_add_f32_dpp v200, v200, v200 quad_perm:[1,0,3,2] row_mask:0xf bank_mask:0xf bound_ctrl:1
	s_nop 1
	v_add_f32_dpp v200, v200, v200 quad_perm:[2,3,0,1] row_mask:0xf bank_mask:0xf bound_ctrl:1
	s_nop 1
	v_add_f32_dpp v200, v200, v200 row_half_mirror row_mask:0xf bank_mask:0xf bound_ctrl:1
	s_nop 1
	v_add_f32_dpp v200, v200, v200 row_mirror row_mask:0xf bank_mask:0xf bound_ctrl:1
	s_nop 1
	v_add_f32_dpp v200, v200, v200 row_bcast:15 row_mask:0xa bank_mask:0xf
	s_nop 1
	v_add_f32_dpp v200, v200, v200 row_bcast:31 row_mask:0xc bank_mask:0xf
	s_nop 0
	v_readlane_b32 s27, v200, 63
	v_mul_f32_e32 v204, s27, v212
	v_mul_f32_e32 v205, 0x3f3504f3, v204
	v_cmp_lt_f32_e64 s[32:33], |v205|, 1.0
	s_and_b64 vcc, exec, s[32:33]
	s_cbranch_vccnz .Lsm_47
	v_fma_f32 v208, |v205|, s9, v214
	v_fma_f32 v208, |v205|, v208, s10
	v_fma_f32 v208, |v205|, v208, s11
	v_fma_f32 v208, |v205|, v208, s12
	v_fma_f32 v208, |v205|, v208, s13
	v_fma_f32 v208, |v205|, v208, s14
	v_fma_f32 v208, |v205|, v208, |v205|
	v_mul_f32_e32 v209, 0xbfb8aa3b, v208
	v_fma_f32 v210, v208, s15, -v209
	v_rndne_f32_e32 v211, v209
	v_fmac_f32_e32 v210, 0xb2a5705f, v208
	v_sub_f32_e32 v209, v209, v211
	v_add_f32_e32 v209, v209, v210
	v_cvt_i32_f32_e32 v210, v211
	v_exp_f32_e32 v209, v209
	v_cmp_nlt_f32_e32 vcc, s16, v208
	v_ldexp_f32 v209, v209, v210
	s_nop 0
	v_cndmask_b32_e32 v209, 0, v209, vcc
	v_cmp_ngt_f32_e32 vcc, s17, v208
	s_nop 1
	v_cndmask_b32_e32 v208, v215, v209, vcc
	v_sub_f32_e32 v210, 1.0, v208
	s_branch .Ljn_47

; DEV float gelu_exact(float v) { return 0.5f * v * (1.f + erff(v * 0.7071067811865476f)); }
; DEV void peer_gather_token(const Params& p, int tok) {
;     ...
;       if (k + 3 < 128) issue(k + 3, (s + 3) & 3);
;       const v6u dq = v6u{dn[s][0][0], dn[s][0][1], dn[s][1][0], dn[s][1][1], dn[s][2][0], dn[s][2][1]};
;       const v32f dv = __builtin_amdgcn_cvt_scalef32_pk32_f32_fp6(dq, 1.0f);
;       float d0 = 0.f, d1 = 0.f, d2 = 0.f, d3 = 0.f;
; #pragma unroll
;       for (int i = 0; i < 8; ++i) { d0 += dv[4 * i] * hx[4 * i]; d1 += dv[4 * i + 1] * hx[4 * i + 1]; d2 += dv[4 * i + 2] * hx[4 * i + 2]; d3 += dv[4 * i + 3] * hx[4 * i + 3]; }
;       const float d = wave_sum_fast((d0 + d1) + (d2 + d3)) * (1.f / DOWN_SCALE);
;       const float gk = __builtin_bit_cast(float, (k < 64) ? __builtin_amdgcn_readlane(g0, k) : __builtin_amdgcn_readlane(g1, k - 64));
;       const float act = gelu_exact(d) * gk * (1.f / UP_SCALE);
;       const v6u uq = v6u{up[s][0][0], up[s][0][1], up[s][1][0], up[s][1][1], up[s][2][0], up[s][2][1]};
;       const v32f uv = __builtin_amdgcn_cvt_scalef32_pk32_f32_fp6(uq, 1.0f);
; #pragma unroll
;       for (int i = 0; i < 32; ++i) acc[i] += act * uv[i];
;     }
;   }
;   const float* gt2 = p.mod + (size_t)b * 12288 + 10240;
;   float* orow = p.out + (size_t)tok * 2048;
; #pragma unroll
;   for (int q = 0; q < 8; ++q) {
;     const int col = lane * 32 + q * 4;
;     float4 x0 = *(const float4*)(orow + col);
;     float4 ga = *(const float4*)(gt2 + col);
;     x0.x += ga.x * acc[q * 4 + 0]; x0.y += ga.y * acc[q * 4 + 1]; x0.z += ga.z * acc[q * 4 + 2]; x0.w += ga.w * acc[q * 4 + 3];
;     *(float4*)(orow + col) = x0;
;   }
.Ljn_47:
	v_bfi_b32 v209, s18, v210, v205
	v_mul_f32_e32 v208, 0.5, v204
	v_add_f32_e32 v209, 1.0, v209
	v_mul_f32_e32 v208, v208, v209
	v_mul_f32_e32 v208, s26, v208
	v_mul_f32_e32 v206, 0x3e800000, v208
	v_pk_fma_f32 v[66:67], v[2:3], v[206:207], v[66:67] op_sel_hi:[1,0,1]
	v_pk_fma_f32 v[68:69], v[4:5], v[206:207], v[68:69] op_sel_hi:[1,0,1]
	v_pk_fma_f32 v[70:71], v[6:7], v[206:207], v[70:71] op_sel_hi:[1,0,1]
	v_pk_fma_f32 v[72:73], v[8:9], v[206:207], v[72:73] op_sel_hi:[1,0,1]
	v_pk_fma_f32 v[74:75], v[10:11], v[206:207], v[74:75] op_sel_hi:[1,0,1]
	v_pk_fma_f32 v[76:77], v[12:13], v[206:207], v[76:77] op_sel_hi:[1,0,1]
	v_pk_fma_f32 v[78:79], v[14:15], v[206:207], v[78:79] op_sel_hi:[1,0,1]
	v_pk_fma_f32 v[80:81], v[16:17], v[206:207], v[80:81] op_sel_hi:[1,0,1]
	v_pk_fma_f32 v[82:83], v[18:19], v[206:207], v[82:83] op_sel_hi:[1,0,1]
	v_pk_fma_f32 v[84:85], v[20:21], v[206:207], v[84:85] op_sel_hi:[1,0,1]
	v_pk_fma_f32 v[86:87], v[22:23], v[206:207], v[86:87] op_sel_hi:[1,0,1]
	v_pk_fma_f32 v[88:89], v[24:25], v[206:207], v[88:89] op_sel_hi:[1,0,1]
	v_pk_fma_f32 v[90:91], v[26:27], v[206:207], v[90:91] op_sel_hi:[1,0,1]
	v_pk_fma_f32 v[92:93], v[28:29], v[206:207], v[92:93] op_sel_hi:[1,0,1]
	v_pk_fma_f32 v[94:95], v[30:31], v[206:207], v[94:95] op_sel_hi:[1,0,1]
	v_pk_fma_f32 v[96:97], v[32:33], v[206:207], v[96:97] op_sel_hi:[1,0,1]
	s_mul_i32 s40, s25, 0xc00
	s_add_u32 s28, s62, s40
	s_addc_u32 s29, s63, 0
	global_load_dwordx4 v[182:185], v1, s[28:29]
	global_load_dwordx4 v[186:189], v1, s[28:29] offset:2048
	global_load_dwordx4 v[190:193], v1, s[28:29] offset:1024
	s_lshr_b32 s38, s20, 11
	s_mul_i32 s38, s38, 0xc000
	s_add_u32 s38, s38, 0xa000
	s_add_u32 s58, s78, s38
	s_addc_u32 s59, s79, 0
	global_load_dwordx4 v[34:37], v244, s[58:59]
	global_load_dwordx4 v[38:41], v244, s[58:59] offset:1024
	global_load_dwordx4 v[42:45], v244, s[58:59] offset:2048
	global_load_dwordx4 v[46:49], v244, s[58:59] offset:3072
	global_load_dwordx4 v[50:53], v245, s[58:59]
	global_load_dwordx4 v[54:57], v245, s[58:59] offset:1024
	global_load_dwordx4 v[58:61], v245, s[58:59] offset:2048
	global_load_dwordx4 v[62:65], v245, s[58:59] offset:3072
	s_lshl_b32 s38, s20, 13
	s_add_u32 s58, s44, s38
	s_addc_u32 s59, s45, 0
	global_load_dwordx4 v[2:5], v244, s[58:59]
	global_load_dwordx4 v[6:9], v244, s[58:59] offset:1024
	global_load_dwordx4 v[10:13], v244, s[58:59] offset:2048
	global_load_dwordx4 v[14:17], v244, s[58:59] offset:3072
	global_load_dwordx4 v[18:21], v245, s[58:59]
	global_load_dwordx4 v[22:25], v245, s[58:59] offset:1024
	global_load_dwordx4 v[26:29], v245, s[58:59] offset:2048
	global_load_dwordx4 v[30:33], v245, s[58:59] offset:3072
	s_waitcnt vmcnt(0)
	v_fmac_f32_e32 v2, v34, v66
	v_fmac_f32_e32 v3, v35, v67
	v_fmac_f32_e32 v4, v36, v68
	v_fmac_f32_e32 v5, v37, v69
	v_fmac_f32_e32 v6, v38, v70
	v_fmac_f32_e32 v7, v39, v71
	v_fmac_f32_e32 v8, v40, v72
	v_fmac_f32_e32 v9, v41, v73
	v_fmac_f32_e32 v10, v42, v74
	v_fmac_f32_e32 v11, v43, v75
	v_fmac_f32_e32 v12, v44, v76
	v_fmac_f32_e32 v13, v45, v77
	v_fmac_f32_e32 v14, v46, v78
	v_fmac_f32_e32 v15, v47, v79
	v_fmac_f32_e32 v16, v48, v80
	v_fmac_f32_e32 v17, v49, v81
	v_fmac_f32_e32 v18, v50, v82
	v_fmac_f32_e32 v19, v51, v83
	v_fmac_f32_e32 v20, v52, v84
	v_fmac_f32_e32 v21, v53, v85
	v_fmac_f32_e32 v22, v54, v86
	v_fmac_f32_e32 v23, v55, v87
	v_fmac_f32_e32 v24, v56, v88
	v_fmac_f32_e32 v25, v57, v89
	v_fmac_f32_e32 v26, v58, v90
	v_fmac_f32_e32 v27, v59, v91
	v_fmac_f32_e32 v28, v60, v92
	v_fmac_f32_e32 v29, v61, v93
	v_fmac_f32_e32 v30, v62, v94
	v_fmac_f32_e32 v31, v63, v95
	v_fmac_f32_e32 v32, v64, v96
	v_fmac_f32_e32 v33, v65, v97
	global_store_dwordx4 v244, v[2:5], s[58:59]
	global_store_dwordx4 v244, v[6:9], s[58:59] offset:1024
	global_store_dwordx4 v244, v[10:13], s[58:59] offset:2048
	global_store_dwordx4 v244, v[14:17], s[58:59] offset:3072
	global_store_dwordx4 v245, v[18:21], s[58:59]
	global_store_dwordx4 v245, v[22:25], s[58:59] offset:1024
	global_store_dwordx4 v245, v[26:29], s[58:59] offset:2048
	global_store_dwordx4 v245, v[30:33], s[58:59] offset:3072
	s_add_i32 s20, s20, s21
	s_cmpk_lt_u32 s20, 0x4000
	s_cbranch_scc0 .Lp12_end
